# n-first chain walk on the toggle-free peeled kernel
# baseline (speedup 1.0000x reference)
; #define PG8_LAS __attribute__((address_space(3)))
; #define PG8_STAGE(bufoff, gbase, voff) do { _Pragma("unroll") for (int _i = 0; _i < 2; ++_i) \
;         __builtin_amdgcn_global_load_lds((const unsigned*)((const char*)(gbase) + (voff)[_i]), (PG8_LAS unsigned*)(lds + (bufoff) + ldsw + _i * 8192), 16, 0, 0); } while (0)
; #define PG8_LDA(dst, b, h) do { _Pragma("unroll") for (int m = 0; m < 4; ++m) _Pragma("unroll") for (int k = 0; k < 2; ++k) dst[m][k] = *(const PG8_LAS bf16x8*)(lds + PG8_SA(b, h) + aoff + m * 2048 + k * 1024); } while (0)
; #define PG8_LDB(dst, b, h) do { _Pragma("unroll") for (int n = 0; n < 2; ++n) _Pragma("unroll") for (int k = 0; k < 2; ++k) dst[n][k] = *(const PG8_LAS bf16x8*)(lds + PG8_SB(b, h) + boff + n * 2048 + k * 1024); } while (0)
; #define PG8_WAIT_V(n) asm volatile("s_waitcnt vmcnt(" #n ")" ::: "memory")
; template <class Epi, class Sched, bool ALIGN_EPI = false, bool SP2 = false, bool ABLK = false, bool BBLK = false>
; __device__ __forceinline__ void gemm_phase(PG8_LAS unsigned char* lds, const Gemm g, const Sched& S, const Epi& E) {
;     ...
;         const bool has_next = S.next(ui + 1, nxt);
;         PG8_LAS unsigned char* const rs_area = lds + STAGE_BYTES + wid * 512;
;         E.stage(cur, rs_area, wr, lane);
;         const char* nA = has_next ? (const char*)g.A + (size_t)nxt.pm * tstep : cA; const char* nB = has_next ? (const char*)g.Bt + (size_t)nxt.pn * tstep : cB;
;         for (int t = 0; t < nt; t += 2) {
;             const bool last = (t == nt - 2);
;             const char* a1 = cA + (size_t)(t + 1) * kstepA;
;             const char* a2 = last ? nA : cA + (size_t)(t + 2) * kstepA; const char* b2 = last ? nB : cB + (size_t)(t + 2) * kstepB;
;             const char* a3 = a2 + kstepA; const char* b3 = b2 + kstepB;
;             if (last && has_next) S.a_ready(nxt);
;             if constexpr (SP2) {
;             PG8_LDB(B0, 0, 0); PG8_LDB(B1, 0, 1); PG8_SCHED; PG8_LDA(At, 0, 0); PG8_STAGE(PG8_SA(1, 1), a1 + hstepA, voffA);
;             PG8_WAIT_V(8); PG8_WAIT_L(0); PG8_BAR; PG8_MMA(0, 0, At, B0); PG8_MMA(0, 1, At, B1); PG8_BAR; PG8_SCHED;
;             PG8_LDA(At, 0, 1); PG8_STAGE(PG8_SB(0, 0), b2, voffB); PG8_STAGE(PG8_SB(0, 1), b2 + hstepB, voffB); PG8_STAGE(PG8_SA(0, 0), a2, voffA);
;             PG8_WAIT_V(8); PG8_WAIT_L(0); PG8_BAR; PG8_MMA(1, 0, At, B0); PG8_MMA(1, 1, At, B1); PG8_BAR; PG8_SCHED;
.LBB0_184:
	s_lshl_b32 s10, s18, 8
	s_ashr_i32 s11, s10, 31
	s_mov_b32 m0, s64
	v_lshl_add_u64 v[4:5], s[10:11], 2, v[144:145]
	global_load_lds_dword v[4:5], off
	v_lshl_add_u64 v[4:5], v[4:5], 0, s[90:91]
	s_add_i32 m0, s64, 0x100
	s_ashr_i32 s9, s8, 31
	global_load_lds_dword v[4:5], off
	s_lshl_b64 s[10:11], s[8:9], 20
	v_readlane_b32 s16, v252, 27
	v_readlane_b32 s17, v252, 28
	s_add_u32 s10, s16, s10
	s_addc_u32 s11, s17, s11
	s_and_b64 s[16:17], s[2:3], exec
	s_cselect_b32 s9, s11, s21
	s_cselect_b32 s70, s10, s20
	s_ashr_i32 s7, s6, 31
	s_lshl_b64 s[16:17], s[6:7], 20
	s_add_u32 s16, s29, s16
	s_addc_u32 s17, s30, s17
	s_and_b64 s[24:25], s[2:3], exec
	s_cselect_b32 s7, s17, s23
	s_cselect_b32 s71, s16, s22
	s_add_u32 s20, s20, 0xc000
	s_addc_u32 s21, s21, 0
	s_add_u32 s77, s22, 0x10000
	s_addc_u32 vcc_lo, s23, 0
	s_mov_b32 vcc_hi, -2
	s_add_u32 s13, s20, 0x4000
	s_addc_u32 s22, s21, 0
	s_cmp_eq_u32 vcc_hi, 28
	s_cselect_b32 s26, s70, s13
	s_cselect_b32 s27, s9, s22
	s_cselect_b32 s24, s71, s77
	s_cselect_b32 s25, s7, vcc_lo
	s_add_u32 s22, s26, 0x8000
	s_addc_u32 s23, s27, 0
	s_add_i32 s13, 0, 0x10000
	v_add_u32_e32 v36, s13, v160
	s_add_i32 s88, 0, 0x14000
	ds_read_b128 v[152:155], v36
	ds_read_b128 v[156:159], v36 offset:1024
	ds_read_b128 v[162:165], v36 offset:2048
	ds_read_b128 v[166:169], v36 offset:3072
	v_add_u32_e32 v36, s88, v160
	ds_read_b128 v[170:173], v36
	ds_read_b128 v[174:177], v36 offset:1024
	ds_read_b128 v[178:181], v36 offset:2048
	ds_read_b128 v[182:185], v36 offset:3072
	s_add_i32 m0, s19, 0xc000
	ds_read_b128 v[186:189], v161
	ds_read_b128 v[190:193], v161 offset:1024
	ds_read_b128 v[194:197], v161 offset:2048
	ds_read_b128 v[198:201], v161 offset:3072
	ds_read_b128 v[202:205], v161 offset:4096
	ds_read_b128 v[206:209], v161 offset:5120
	ds_read_b128 v[210:213], v161 offset:6144
	ds_read_b128 v[214:217], v161 offset:7168
	global_load_lds_dwordx4 v148, s[20:21]
	s_add_i32 m0, s19, 0xe000
	s_nop 0
	global_load_lds_dwordx4 v150, s[20:21]
	s_waitcnt vmcnt(8)
	s_waitcnt lgkmcnt(0)
	v_mfma_f32_16x16x32_bf16 v[132:135], v[152:155], v[186:189], 0
	v_mfma_f32_16x16x32_bf16 v[132:135], v[156:159], v[190:193], v[132:135]
	v_mfma_f32_16x16x32_bf16 v[128:131], v[166:169], v[190:193], 0
	v_mfma_f32_16x16x32_bf16 v[128:131], v[162:165], v[186:189], v[128:131]
	s_barrier
	s_setprio 1
	v_mfma_f32_16x16x32_bf16 v[124:127], v[170:173], v[186:189], 0
	v_mfma_f32_16x16x32_bf16 v[124:127], v[174:177], v[190:193], v[124:127]
	v_mfma_f32_16x16x32_bf16 v[120:123], v[182:185], v[190:193], 0
	v_mfma_f32_16x16x32_bf16 v[120:123], v[178:181], v[186:189], v[120:123]
	v_mfma_f32_16x16x32_bf16 v[104:107], v[178:181], v[194:197], 0
	v_mfma_f32_16x16x32_bf16 v[104:107], v[182:185], v[198:201], v[104:107]
	v_mfma_f32_16x16x32_bf16 v[116:119], v[156:159], v[198:201], 0
	v_mfma_f32_16x16x32_bf16 v[116:119], v[152:155], v[194:197], v[116:119]
	v_mfma_f32_16x16x32_bf16 v[112:115], v[162:165], v[194:197], 0
	v_mfma_f32_16x16x32_bf16 v[112:115], v[166:169], v[198:201], v[112:115]
	v_mfma_f32_16x16x32_bf16 v[108:111], v[174:177], v[198:201], 0
	v_mfma_f32_16x16x32_bf16 v[108:111], v[170:173], v[194:197], v[108:111]
	v_mfma_f32_16x16x32_bf16 v[92:95], v[170:173], v[202:205], 0
	v_mfma_f32_16x16x32_bf16 v[92:95], v[174:177], v[206:209], v[92:95]
	v_mfma_f32_16x16x32_bf16 v[100:103], v[156:159], v[206:209], 0
	v_mfma_f32_16x16x32_bf16 v[100:103], v[152:155], v[202:205], v[100:103]
	v_mfma_f32_16x16x32_bf16 v[96:99], v[162:165], v[202:205], 0
	v_mfma_f32_16x16x32_bf16 v[96:99], v[166:169], v[206:209], v[96:99]
	v_mfma_f32_16x16x32_bf16 v[88:91], v[182:185], v[206:209], 0
	v_mfma_f32_16x16x32_bf16 v[88:91], v[178:181], v[202:205], v[88:91]
	v_mfma_f32_16x16x32_bf16 v[72:75], v[178:181], v[210:213], 0
	v_mfma_f32_16x16x32_bf16 v[72:75], v[182:185], v[214:217], v[72:75]
	v_mfma_f32_16x16x32_bf16 v[84:87], v[156:159], v[214:217], 0
	v_mfma_f32_16x16x32_bf16 v[84:87], v[152:155], v[210:213], v[84:87]
	v_mfma_f32_16x16x32_bf16 v[80:83], v[162:165], v[210:213], 0
	v_mfma_f32_16x16x32_bf16 v[80:83], v[166:169], v[214:217], v[80:83]
	v_mfma_f32_16x16x32_bf16 v[76:79], v[174:177], v[214:217], 0
	v_mfma_f32_16x16x32_bf16 v[76:79], v[170:173], v[210:213], v[76:79]
	s_setprio 0
	s_barrier
	s_add_i32 s13, s13, s31
	s_mov_b32 m0, s13
	ds_read_b128 v[186:189], v161 offset:16384
	ds_read_b128 v[190:193], v161 offset:17408
	ds_read_b128 v[194:197], v161 offset:18432
	ds_read_b128 v[198:201], v161 offset:19456
	ds_read_b128 v[202:205], v161 offset:20480
	ds_read_b128 v[206:209], v161 offset:21504
	ds_read_b128 v[210:213], v161 offset:22528
	ds_read_b128 v[214:217], v161 offset:23552
	global_load_lds_dwordx4 v140, s[24:25]
	s_add_i32 m0, s13, 0x2000
	s_add_u32 s68, s24, 0x4000
	s_addc_u32 s69, s25, 0
	s_add_i32 s13, s88, s31
	global_load_lds_dwordx4 v136, s[24:25]
	s_mov_b32 m0, s13
	s_nop 0
	global_load_lds_dwordx4 v140, s[68:69]
	s_add_i32 m0, s13, 0x2000
	s_nop 0
	global_load_lds_dwordx4 v136, s[68:69]
	s_mov_b32 m0, s19
	s_nop 0
	global_load_lds_dwordx4 v142, s[26:27]
	s_mov_b32 m0, s35
	s_nop 0
	global_load_lds_dwordx4 v138, s[26:27]
	s_waitcnt vmcnt(8)
	s_waitcnt lgkmcnt(0)
	v_mfma_f32_16x16x32_bf16 v[68:71], v[152:155], v[186:189], 0
	v_mfma_f32_16x16x32_bf16 v[68:71], v[156:159], v[190:193], v[68:71]
	v_mfma_f32_16x16x32_bf16 v[64:67], v[166:169], v[190:193], 0
	v_mfma_f32_16x16x32_bf16 v[64:67], v[162:165], v[186:189], v[64:67]
	s_barrier
; #define PG8_STAGE(bufoff, gbase, voff) do { _Pragma("unroll") for (int _i = 0; _i < 2; ++_i) \
;         __builtin_amdgcn_global_load_lds((const unsigned*)((const char*)(gbase) + (voff)[_i]), (PG8_LAS unsigned*)(lds + (bufoff) + ldsw + _i * 8192), 16, 0, 0); } while (0)
; #define PG8_LDA(dst, b, h) do { _Pragma("unroll") for (int m = 0; m < 4; ++m) _Pragma("unroll") for (int k = 0; k < 2; ++k) dst[m][k] = *(const PG8_LAS bf16x8*)(lds + PG8_SA(b, h) + aoff + m * 2048 + k * 1024); } while (0)
; #define PG8_LDB(dst, b, h) do { _Pragma("unroll") for (int n = 0; n < 2; ++n) _Pragma("unroll") for (int k = 0; k < 2; ++k) dst[n][k] = *(const PG8_LAS bf16x8*)(lds + PG8_SB(b, h) + boff + n * 2048 + k * 1024); } while (0)
; #define PG8_MMA(ai, bj, At, Bt) do { __builtin_amdgcn_s_setprio(1); _Pragma("unroll") for (int m = 0; m < 4; ++m) _Pragma("unroll") for (int n = 0; n < 2; ++n) _Pragma("unroll") for (int k = 0; k < 2; ++k) \
;         acc[ai][bj][m][n] = __builtin_amdgcn_mfma_f32_16x16x32_bf16(Bt[n][k], At[m][k], acc[ai][bj][m][n], 0, 0, 0); __builtin_amdgcn_s_setprio(0); } while (0)
; #define PG8_WAIT_V(n) asm volatile("s_waitcnt vmcnt(" #n ")" ::: "memory")
; #define PG8_WAIT_L(n) asm volatile("s_waitcnt lgkmcnt(" #n ")" ::: "memory")
; #define PG8_BAR __builtin_amdgcn_s_barrier()
; #define PG8_SCHED __builtin_amdgcn_sched_barrier(0)
; template <class Epi, class Sched, bool ALIGN_EPI = false, bool SP2 = false, bool ABLK = false, bool BBLK = false>
; __device__ __forceinline__ void gemm_phase(PG8_LAS unsigned char* lds, const Gemm g, const Sched& S, const Epi& E) {
;     ...
;             PG8_WAIT_V(8); PG8_WAIT_L(0); PG8_BAR; PG8_MMA(1, 0, At, B0); PG8_MMA(1, 1, At, B1); PG8_BAR; PG8_SCHED;
;             PG8_LDB(B0, 1, 0); PG8_LDB(B1, 1, 1); PG8_SCHED; PG8_LDA(At, 1, 0); PG8_STAGE(PG8_SA(0, 1), a2 + hstepA, voffA);
;             PG8_WAIT_V(8); PG8_WAIT_L(0); PG8_BAR; PG8_MMA(0, 0, At, B0); PG8_MMA(0, 1, At, B1); PG8_BAR; PG8_SCHED;
	s_setprio 1
	v_mfma_f32_16x16x32_bf16 v[60:63], v[170:173], v[186:189], 0
	v_mfma_f32_16x16x32_bf16 v[60:63], v[174:177], v[190:193], v[60:63]
	v_mfma_f32_16x16x32_bf16 v[56:59], v[182:185], v[190:193], 0
	v_mfma_f32_16x16x32_bf16 v[56:59], v[178:181], v[186:189], v[56:59]
	v_mfma_f32_16x16x32_bf16 v[40:43], v[178:181], v[194:197], 0
	v_mfma_f32_16x16x32_bf16 v[40:43], v[182:185], v[198:201], v[40:43]
	v_mfma_f32_16x16x32_bf16 v[52:55], v[156:159], v[198:201], 0
	v_mfma_f32_16x16x32_bf16 v[52:55], v[152:155], v[194:197], v[52:55]
	v_mfma_f32_16x16x32_bf16 v[48:51], v[162:165], v[194:197], 0
	v_mfma_f32_16x16x32_bf16 v[48:51], v[166:169], v[198:201], v[48:51]
	v_mfma_f32_16x16x32_bf16 v[44:47], v[174:177], v[198:201], 0
	v_mfma_f32_16x16x32_bf16 v[44:47], v[170:173], v[194:197], v[44:47]
	v_mfma_f32_16x16x32_bf16 v[24:27], v[170:173], v[202:205], 0
	v_mfma_f32_16x16x32_bf16 v[24:27], v[174:177], v[206:209], v[24:27]
	v_mfma_f32_16x16x32_bf16 v[32:35], v[156:159], v[206:209], 0
	v_mfma_f32_16x16x32_bf16 v[32:35], v[152:155], v[202:205], v[32:35]
	v_mfma_f32_16x16x32_bf16 v[28:31], v[162:165], v[202:205], 0
	v_mfma_f32_16x16x32_bf16 v[28:31], v[166:169], v[206:209], v[28:31]
	v_mfma_f32_16x16x32_bf16 v[20:23], v[182:185], v[206:209], 0
	v_mfma_f32_16x16x32_bf16 v[20:23], v[178:181], v[202:205], v[20:23]
	v_mfma_f32_16x16x32_bf16 v[4:7], v[178:181], v[210:213], 0
	v_mfma_f32_16x16x32_bf16 v[4:7], v[182:185], v[214:217], v[4:7]
	v_mfma_f32_16x16x32_bf16 v[16:19], v[156:159], v[214:217], 0
	v_mfma_f32_16x16x32_bf16 v[16:19], v[152:155], v[210:213], v[16:19]
	v_mfma_f32_16x16x32_bf16 v[12:15], v[162:165], v[210:213], 0
	v_mfma_f32_16x16x32_bf16 v[12:15], v[166:169], v[214:217], v[12:15]
	v_mfma_f32_16x16x32_bf16 v[8:11], v[174:177], v[214:217], 0
	v_mfma_f32_16x16x32_bf16 v[8:11], v[170:173], v[210:213], v[8:11]
	s_setprio 0
	s_barrier
	s_add_i32 s13, 0, 0x18000
	v_add_u32_e32 v36, s13, v160
	s_add_i32 s68, 0, 0x1c000
	ds_read_b128 v[152:155], v36
	ds_read_b128 v[156:159], v36 offset:1024
	ds_read_b128 v[162:165], v36 offset:2048
	ds_read_b128 v[166:169], v36 offset:3072
	v_add_u32_e32 v36, s68, v160
	ds_read_b128 v[170:173], v36
	ds_read_b128 v[174:177], v36 offset:1024
	ds_read_b128 v[178:181], v36 offset:2048
	ds_read_b128 v[182:185], v36 offset:3072
	s_add_u32 s26, s26, 0x4000
	s_addc_u32 s27, s27, 0
	s_mov_b32 m0, s36
	ds_read_b128 v[186:189], v161 offset:32768
	ds_read_b128 v[190:193], v161 offset:33792
	ds_read_b128 v[194:197], v161 offset:34816
	ds_read_b128 v[198:201], v161 offset:35840
	ds_read_b128 v[202:205], v161 offset:36864
	ds_read_b128 v[206:209], v161 offset:37888
	ds_read_b128 v[210:213], v161 offset:38912
	ds_read_b128 v[214:217], v161 offset:39936
	global_load_lds_dwordx4 v142, s[26:27]
	s_mov_b32 m0, s37
	s_nop 0
	global_load_lds_dwordx4 v138, s[26:27]
	s_waitcnt vmcnt(8)
	s_waitcnt lgkmcnt(0)
	v_mfma_f32_16x16x32_bf16 v[132:135], v[152:155], v[186:189], v[132:135]
	v_mfma_f32_16x16x32_bf16 v[132:135], v[156:159], v[190:193], v[132:135]
	v_mfma_f32_16x16x32_bf16 v[128:131], v[166:169], v[190:193], v[128:131]
	v_mfma_f32_16x16x32_bf16 v[128:131], v[162:165], v[186:189], v[128:131]
	s_barrier
	s_setprio 1
	v_mfma_f32_16x16x32_bf16 v[124:127], v[170:173], v[186:189], v[124:127]
	v_mfma_f32_16x16x32_bf16 v[124:127], v[174:177], v[190:193], v[124:127]
	v_mfma_f32_16x16x32_bf16 v[120:123], v[182:185], v[190:193], v[120:123]
	v_mfma_f32_16x16x32_bf16 v[120:123], v[178:181], v[186:189], v[120:123]
	v_mfma_f32_16x16x32_bf16 v[104:107], v[178:181], v[194:197], v[104:107]
	v_mfma_f32_16x16x32_bf16 v[104:107], v[182:185], v[198:201], v[104:107]
	v_mfma_f32_16x16x32_bf16 v[116:119], v[156:159], v[198:201], v[116:119]
	v_mfma_f32_16x16x32_bf16 v[116:119], v[152:155], v[194:197], v[116:119]
	v_mfma_f32_16x16x32_bf16 v[112:115], v[162:165], v[194:197], v[112:115]
	v_mfma_f32_16x16x32_bf16 v[112:115], v[166:169], v[198:201], v[112:115]
	v_mfma_f32_16x16x32_bf16 v[108:111], v[174:177], v[198:201], v[108:111]
	v_mfma_f32_16x16x32_bf16 v[108:111], v[170:173], v[194:197], v[108:111]
	v_mfma_f32_16x16x32_bf16 v[92:95], v[170:173], v[202:205], v[92:95]
	v_mfma_f32_16x16x32_bf16 v[92:95], v[174:177], v[206:209], v[92:95]
	v_mfma_f32_16x16x32_bf16 v[100:103], v[156:159], v[206:209], v[100:103]
	v_mfma_f32_16x16x32_bf16 v[100:103], v[152:155], v[202:205], v[100:103]
	v_mfma_f32_16x16x32_bf16 v[96:99], v[162:165], v[202:205], v[96:99]
	v_mfma_f32_16x16x32_bf16 v[96:99], v[166:169], v[206:209], v[96:99]
	v_mfma_f32_16x16x32_bf16 v[88:91], v[182:185], v[206:209], v[88:91]
	v_mfma_f32_16x16x32_bf16 v[88:91], v[178:181], v[202:205], v[88:91]
	v_mfma_f32_16x16x32_bf16 v[72:75], v[178:181], v[210:213], v[72:75]
	v_mfma_f32_16x16x32_bf16 v[72:75], v[182:185], v[214:217], v[72:75]
	v_mfma_f32_16x16x32_bf16 v[84:87], v[156:159], v[214:217], v[84:87]
	v_mfma_f32_16x16x32_bf16 v[84:87], v[152:155], v[210:213], v[84:87]
	v_mfma_f32_16x16x32_bf16 v[80:83], v[162:165], v[210:213], v[80:83]
	v_mfma_f32_16x16x32_bf16 v[80:83], v[166:169], v[214:217], v[80:83]
	v_mfma_f32_16x16x32_bf16 v[76:79], v[174:177], v[214:217], v[76:79]
	v_mfma_f32_16x16x32_bf16 v[76:79], v[170:173], v[210:213], v[76:79]
	s_setprio 0
	s_barrier
; #define PG8_STAGE(bufoff, gbase, voff) do { _Pragma("unroll") for (int _i = 0; _i < 2; ++_i) \
;         __builtin_amdgcn_global_load_lds((const unsigned*)((const char*)(gbase) + (voff)[_i]), (PG8_LAS unsigned*)(lds + (bufoff) + ldsw + _i * 8192), 16, 0, 0); } while (0)
; #define PG8_LDA(dst, b, h) do { _Pragma("unroll") for (int m = 0; m < 4; ++m) _Pragma("unroll") for (int k = 0; k < 2; ++k) dst[m][k] = *(const PG8_LAS bf16x8*)(lds + PG8_SA(b, h) + aoff + m * 2048 + k * 1024); } while (0)
; #define PG8_WAIT_V(n) asm volatile("s_waitcnt vmcnt(" #n ")" ::: "memory")
; #define PG8_WAIT_L(n) asm volatile("s_waitcnt lgkmcnt(" #n ")" ::: "memory")
; template <class Epi, class Sched, bool ALIGN_EPI = false, bool SP2 = false, bool ABLK = false, bool BBLK = false>
; __device__ __forceinline__ void gemm_phase(PG8_LAS unsigned char* lds, const Gemm g, const Sched& S, const Epi& E) {
;     ...
;         for (int t = 0; t < nt; t += 2) {
;             const bool last = (t == nt - 2);
;             const char* a1 = cA + (size_t)(t + 1) * kstepA;
;             const char* a2 = last ? nA : cA + (size_t)(t + 2) * kstepA; const char* b2 = last ? nB : cB + (size_t)(t + 2) * kstepB;
;             const char* a3 = a2 + kstepA; const char* b3 = b2 + kstepB;
;             if (last && has_next) S.a_ready(nxt);
;             if constexpr (SP2) {
;             PG8_LDB(B0, 0, 0); PG8_LDB(B1, 0, 1); PG8_SCHED; PG8_LDA(At, 0, 0); PG8_STAGE(PG8_SA(1, 1), a1 + hstepA, voffA);
;             PG8_WAIT_V(8); PG8_WAIT_L(0); PG8_BAR; PG8_MMA(0, 0, At, B0); PG8_MMA(0, 1, At, B1); PG8_BAR; PG8_SCHED;
;             PG8_LDA(At, 0, 1); PG8_STAGE(PG8_SB(0, 0), b2, voffB); PG8_STAGE(PG8_SB(0, 1), b2 + hstepB, voffB); PG8_STAGE(PG8_SA(0, 0), a2, voffA);
;             PG8_WAIT_V(8); PG8_WAIT_L(0); PG8_BAR; PG8_MMA(1, 0, At, B0); PG8_MMA(1, 1, At, B1); PG8_BAR; PG8_SCHED;
;             PG8_LDB(B0, 1, 0); PG8_LDB(B1, 1, 1); PG8_SCHED; PG8_LDA(At, 1, 0); PG8_STAGE(PG8_SA(0, 1), a2 + hstepA, voffA);
;             PG8_WAIT_V(8); PG8_WAIT_L(0); PG8_BAR; PG8_MMA(0, 0, At, B0); PG8_MMA(0, 1, At, B1); PG8_BAR; PG8_SCHED;
;             PG8_LDA(At, 1, 1); PG8_STAGE(PG8_SB(1, 0), b3, voffB); PG8_STAGE(PG8_SB(1, 1), b3 + hstepB, voffB); PG8_STAGE(PG8_SA(1, 0), a3, voffA);
;             PG8_WAIT_V(8); PG8_WAIT_L(0); PG8_BAR; PG8_MMA(1, 0, At, B0); PG8_MMA(1, 1, At, B1); PG8_BAR; PG8_SCHED;
	s_add_u32 s26, s24, 0x8000
	s_addc_u32 s27, s25, 0
	s_add_i32 s13, s13, s31
	s_mov_b32 m0, s13
	ds_read_b128 v[186:189], v161 offset:49152
	ds_read_b128 v[190:193], v161 offset:50176
	ds_read_b128 v[194:197], v161 offset:51200
	ds_read_b128 v[198:201], v161 offset:52224
	ds_read_b128 v[202:205], v161 offset:53248
	ds_read_b128 v[206:209], v161 offset:54272
	ds_read_b128 v[210:213], v161 offset:55296
	ds_read_b128 v[214:217], v161 offset:56320
	global_load_lds_dwordx4 v140, s[26:27]
	s_add_i32 m0, s13, 0x2000
	s_add_u32 s24, s24, 0xc000
	s_addc_u32 s25, s25, 0
	s_add_i32 s13, s68, s31
	global_load_lds_dwordx4 v136, s[26:27]
	s_mov_b32 m0, s13
	s_nop 0
	global_load_lds_dwordx4 v140, s[24:25]
	s_add_i32 m0, s13, 0x2000
	s_nop 0
	global_load_lds_dwordx4 v136, s[24:25]
	s_mov_b32 m0, s62
	s_nop 0
	global_load_lds_dwordx4 v142, s[22:23]
	s_mov_b32 m0, s63
	s_nop 0
	global_load_lds_dwordx4 v138, s[22:23]
	s_waitcnt vmcnt(8)
	s_waitcnt lgkmcnt(0)
	v_mfma_f32_16x16x32_bf16 v[68:71], v[152:155], v[186:189], v[68:71]
	v_mfma_f32_16x16x32_bf16 v[68:71], v[156:159], v[190:193], v[68:71]
	v_mfma_f32_16x16x32_bf16 v[64:67], v[166:169], v[190:193], v[64:67]
	v_mfma_f32_16x16x32_bf16 v[64:67], v[162:165], v[186:189], v[64:67]
	s_barrier
	s_setprio 1
	v_mfma_f32_16x16x32_bf16 v[60:63], v[170:173], v[186:189], v[60:63]
	v_mfma_f32_16x16x32_bf16 v[60:63], v[174:177], v[190:193], v[60:63]
	v_mfma_f32_16x16x32_bf16 v[56:59], v[182:185], v[190:193], v[56:59]
	v_mfma_f32_16x16x32_bf16 v[56:59], v[178:181], v[186:189], v[56:59]
	v_mfma_f32_16x16x32_bf16 v[40:43], v[178:181], v[194:197], v[40:43]
	v_mfma_f32_16x16x32_bf16 v[40:43], v[182:185], v[198:201], v[40:43]
	v_mfma_f32_16x16x32_bf16 v[52:55], v[156:159], v[198:201], v[52:55]
	v_mfma_f32_16x16x32_bf16 v[52:55], v[152:155], v[194:197], v[52:55]
	v_mfma_f32_16x16x32_bf16 v[48:51], v[162:165], v[194:197], v[48:51]
	v_mfma_f32_16x16x32_bf16 v[48:51], v[166:169], v[198:201], v[48:51]
	v_mfma_f32_16x16x32_bf16 v[44:47], v[174:177], v[198:201], v[44:47]
	v_mfma_f32_16x16x32_bf16 v[44:47], v[170:173], v[194:197], v[44:47]
	v_mfma_f32_16x16x32_bf16 v[24:27], v[170:173], v[202:205], v[24:27]
	v_mfma_f32_16x16x32_bf16 v[24:27], v[174:177], v[206:209], v[24:27]
	v_mfma_f32_16x16x32_bf16 v[32:35], v[156:159], v[206:209], v[32:35]
	v_mfma_f32_16x16x32_bf16 v[32:35], v[152:155], v[202:205], v[32:35]
	v_mfma_f32_16x16x32_bf16 v[28:31], v[162:165], v[202:205], v[28:31]
	v_mfma_f32_16x16x32_bf16 v[28:31], v[166:169], v[206:209], v[28:31]
	v_mfma_f32_16x16x32_bf16 v[20:23], v[182:185], v[206:209], v[20:23]
	v_mfma_f32_16x16x32_bf16 v[20:23], v[178:181], v[202:205], v[20:23]
	v_mfma_f32_16x16x32_bf16 v[4:7], v[178:181], v[210:213], v[4:7]
	v_mfma_f32_16x16x32_bf16 v[4:7], v[182:185], v[214:217], v[4:7]
	v_mfma_f32_16x16x32_bf16 v[16:19], v[156:159], v[214:217], v[16:19]
	v_mfma_f32_16x16x32_bf16 v[16:19], v[152:155], v[210:213], v[16:19]
	v_mfma_f32_16x16x32_bf16 v[12:15], v[162:165], v[210:213], v[12:15]
	v_mfma_f32_16x16x32_bf16 v[12:15], v[166:169], v[214:217], v[12:15]
	v_mfma_f32_16x16x32_bf16 v[8:11], v[174:177], v[214:217], v[8:11]
	v_mfma_f32_16x16x32_bf16 v[8:11], v[170:173], v[210:213], v[8:11]
	s_setprio 0
	s_barrier
	s_add_i32 vcc_hi, vcc_hi, 2
	s_add_u32 s20, s20, 0x10000
	s_addc_u32 s21, s21, 0
	s_add_u32 s77, s77, 0x10000
	s_addc_u32 vcc_lo, vcc_lo, 0
	s_cmp_gt_u32 vcc_hi, 29
.LBB0_185:
	s_add_u32 s13, s20, 0x4000
	s_addc_u32 s22, s21, 0
	s_cmp_eq_u32 vcc_hi, 28
	s_cselect_b32 s26, s70, s13
	s_cselect_b32 s27, s9, s22
	s_cselect_b32 s24, s71, s77
	s_cselect_b32 s25, s7, vcc_lo
	s_add_u32 s22, s26, 0x8000
	s_addc_u32 s23, s27, 0
	s_add_i32 s13, 0, 0x10000
	v_add_u32_e32 v36, s13, v160
	s_add_i32 s88, 0, 0x14000
	ds_read_b128 v[152:155], v36
	ds_read_b128 v[156:159], v36 offset:1024
	ds_read_b128 v[162:165], v36 offset:2048
	ds_read_b128 v[166:169], v36 offset:3072
	v_add_u32_e32 v36, s88, v160
	ds_read_b128 v[170:173], v36
	ds_read_b128 v[174:177], v36 offset:1024
	ds_read_b128 v[178:181], v36 offset:2048
	ds_read_b128 v[182:185], v36 offset:3072
	s_add_i32 m0, s19, 0xc000
	ds_read_b128 v[186:189], v161
	ds_read_b128 v[190:193], v161 offset:1024
	ds_read_b128 v[194:197], v161 offset:2048
	ds_read_b128 v[198:201], v161 offset:3072
	ds_read_b128 v[202:205], v161 offset:4096
	ds_read_b128 v[206:209], v161 offset:5120
	ds_read_b128 v[210:213], v161 offset:6144
	ds_read_b128 v[214:217], v161 offset:7168
	global_load_lds_dwordx4 v148, s[20:21]
	s_add_i32 m0, s19, 0xe000
	s_nop 0
	global_load_lds_dwordx4 v150, s[20:21]
	s_waitcnt vmcnt(8)
	s_waitcnt lgkmcnt(0)
	v_mfma_f32_16x16x32_bf16 v[132:135], v[152:155], v[186:189], v[132:135]
	v_mfma_f32_16x16x32_bf16 v[132:135], v[156:159], v[190:193], v[132:135]
	v_mfma_f32_16x16x32_bf16 v[128:131], v[166:169], v[190:193], v[128:131]
	v_mfma_f32_16x16x32_bf16 v[128:131], v[162:165], v[186:189], v[128:131]
	s_barrier
; #define PG8_STAGE(bufoff, gbase, voff) do { _Pragma("unroll") for (int _i = 0; _i < 2; ++_i) \
;         __builtin_amdgcn_global_load_lds((const unsigned*)((const char*)(gbase) + (voff)[_i]), (PG8_LAS unsigned*)(lds + (bufoff) + ldsw + _i * 8192), 16, 0, 0); } while (0)
; #define PG8_LDA(dst, b, h) do { _Pragma("unroll") for (int m = 0; m < 4; ++m) _Pragma("unroll") for (int k = 0; k < 2; ++k) dst[m][k] = *(const PG8_LAS bf16x8*)(lds + PG8_SA(b, h) + aoff + m * 2048 + k * 1024); } while (0)
; #define PG8_LDB(dst, b, h) do { _Pragma("unroll") for (int n = 0; n < 2; ++n) _Pragma("unroll") for (int k = 0; k < 2; ++k) dst[n][k] = *(const PG8_LAS bf16x8*)(lds + PG8_SB(b, h) + boff + n * 2048 + k * 1024); } while (0)
; #define PG8_MMA(ai, bj, At, Bt) do { __builtin_amdgcn_s_setprio(1); _Pragma("unroll") for (int m = 0; m < 4; ++m) _Pragma("unroll") for (int n = 0; n < 2; ++n) _Pragma("unroll") for (int k = 0; k < 2; ++k) \
;         acc[ai][bj][m][n] = __builtin_amdgcn_mfma_f32_16x16x32_bf16(Bt[n][k], At[m][k], acc[ai][bj][m][n], 0, 0, 0); __builtin_amdgcn_s_setprio(0); } while (0)
; #define PG8_WAIT_V(n) asm volatile("s_waitcnt vmcnt(" #n ")" ::: "memory")
; #define PG8_WAIT_L(n) asm volatile("s_waitcnt lgkmcnt(" #n ")" ::: "memory")
; #define PG8_BAR __builtin_amdgcn_s_barrier()
; #define PG8_SCHED __builtin_amdgcn_sched_barrier(0)
; template <class Epi, class Sched, bool ALIGN_EPI = false, bool SP2 = false, bool ABLK = false, bool BBLK = false>
; __device__ __forceinline__ void gemm_phase(PG8_LAS unsigned char* lds, const Gemm g, const Sched& S, const Epi& E) {
;     ...
;             PG8_LDB(B0, 0, 0); PG8_LDB(B1, 0, 1); PG8_SCHED; PG8_LDA(At, 0, 0); PG8_STAGE(PG8_SA(1, 1), a1 + hstepA, voffA);
;             PG8_WAIT_V(8); PG8_WAIT_L(0); PG8_BAR; PG8_MMA(0, 0, At, B0); PG8_MMA(0, 1, At, B1); PG8_BAR; PG8_SCHED;
;             PG8_LDA(At, 0, 1); PG8_STAGE(PG8_SB(0, 0), b2, voffB); PG8_STAGE(PG8_SB(0, 1), b2 + hstepB, voffB); PG8_STAGE(PG8_SA(0, 0), a2, voffA);
;             PG8_WAIT_V(8); PG8_WAIT_L(0); PG8_BAR; PG8_MMA(1, 0, At, B0); PG8_MMA(1, 1, At, B1); PG8_BAR; PG8_SCHED;
	s_setprio 1
	v_mfma_f32_16x16x32_bf16 v[124:127], v[170:173], v[186:189], v[124:127]
	v_mfma_f32_16x16x32_bf16 v[124:127], v[174:177], v[190:193], v[124:127]
	v_mfma_f32_16x16x32_bf16 v[120:123], v[182:185], v[190:193], v[120:123]
	v_mfma_f32_16x16x32_bf16 v[120:123], v[178:181], v[186:189], v[120:123]
	v_mfma_f32_16x16x32_bf16 v[104:107], v[178:181], v[194:197], v[104:107]
	v_mfma_f32_16x16x32_bf16 v[104:107], v[182:185], v[198:201], v[104:107]
	v_mfma_f32_16x16x32_bf16 v[116:119], v[156:159], v[198:201], v[116:119]
	v_mfma_f32_16x16x32_bf16 v[116:119], v[152:155], v[194:197], v[116:119]
	v_mfma_f32_16x16x32_bf16 v[112:115], v[162:165], v[194:197], v[112:115]
	v_mfma_f32_16x16x32_bf16 v[112:115], v[166:169], v[198:201], v[112:115]
	v_mfma_f32_16x16x32_bf16 v[108:111], v[174:177], v[198:201], v[108:111]
	v_mfma_f32_16x16x32_bf16 v[108:111], v[170:173], v[194:197], v[108:111]
	v_mfma_f32_16x16x32_bf16 v[92:95], v[170:173], v[202:205], v[92:95]
	v_mfma_f32_16x16x32_bf16 v[92:95], v[174:177], v[206:209], v[92:95]
	v_mfma_f32_16x16x32_bf16 v[100:103], v[156:159], v[206:209], v[100:103]
	v_mfma_f32_16x16x32_bf16 v[100:103], v[152:155], v[202:205], v[100:103]
	v_mfma_f32_16x16x32_bf16 v[96:99], v[162:165], v[202:205], v[96:99]
	v_mfma_f32_16x16x32_bf16 v[96:99], v[166:169], v[206:209], v[96:99]
	v_mfma_f32_16x16x32_bf16 v[88:91], v[182:185], v[206:209], v[88:91]
	v_mfma_f32_16x16x32_bf16 v[88:91], v[178:181], v[202:205], v[88:91]
	v_mfma_f32_16x16x32_bf16 v[72:75], v[178:181], v[210:213], v[72:75]
	v_mfma_f32_16x16x32_bf16 v[72:75], v[182:185], v[214:217], v[72:75]
	v_mfma_f32_16x16x32_bf16 v[84:87], v[156:159], v[214:217], v[84:87]
	v_mfma_f32_16x16x32_bf16 v[84:87], v[152:155], v[210:213], v[84:87]
	v_mfma_f32_16x16x32_bf16 v[80:83], v[162:165], v[210:213], v[80:83]
	v_mfma_f32_16x16x32_bf16 v[80:83], v[166:169], v[214:217], v[80:83]
	v_mfma_f32_16x16x32_bf16 v[76:79], v[174:177], v[214:217], v[76:79]
	v_mfma_f32_16x16x32_bf16 v[76:79], v[170:173], v[210:213], v[76:79]
	s_setprio 0
	s_barrier
	s_add_i32 s13, s13, s31
	s_mov_b32 m0, s13
	ds_read_b128 v[186:189], v161 offset:16384
	ds_read_b128 v[190:193], v161 offset:17408
	ds_read_b128 v[194:197], v161 offset:18432
	ds_read_b128 v[198:201], v161 offset:19456
	ds_read_b128 v[202:205], v161 offset:20480
	ds_read_b128 v[206:209], v161 offset:21504
	ds_read_b128 v[210:213], v161 offset:22528
	ds_read_b128 v[214:217], v161 offset:23552
	global_load_lds_dwordx4 v140, s[24:25]
	s_add_i32 m0, s13, 0x2000
	s_add_u32 s68, s24, 0x4000
	s_addc_u32 s69, s25, 0
	s_add_i32 s13, s88, s31
	global_load_lds_dwordx4 v136, s[24:25]
	s_mov_b32 m0, s13
	s_nop 0
	global_load_lds_dwordx4 v140, s[68:69]
	s_add_i32 m0, s13, 0x2000
	s_nop 0
	global_load_lds_dwordx4 v136, s[68:69]
	s_mov_b32 m0, s19
	s_nop 0
	global_load_lds_dwordx4 v142, s[26:27]
	s_mov_b32 m0, s35
	s_nop 0
	global_load_lds_dwordx4 v138, s[26:27]
	s_waitcnt vmcnt(8)
	s_waitcnt lgkmcnt(0)
	v_mfma_f32_16x16x32_bf16 v[68:71], v[152:155], v[186:189], v[68:71]
	v_mfma_f32_16x16x32_bf16 v[68:71], v[156:159], v[190:193], v[68:71]
	v_mfma_f32_16x16x32_bf16 v[64:67], v[166:169], v[190:193], v[64:67]
	v_mfma_f32_16x16x32_bf16 v[64:67], v[162:165], v[186:189], v[64:67]
	s_barrier
	s_setprio 1
	v_mfma_f32_16x16x32_bf16 v[60:63], v[170:173], v[186:189], v[60:63]
	v_mfma_f32_16x16x32_bf16 v[60:63], v[174:177], v[190:193], v[60:63]
	v_mfma_f32_16x16x32_bf16 v[56:59], v[182:185], v[190:193], v[56:59]
	v_mfma_f32_16x16x32_bf16 v[56:59], v[178:181], v[186:189], v[56:59]
	v_mfma_f32_16x16x32_bf16 v[40:43], v[178:181], v[194:197], v[40:43]
	v_mfma_f32_16x16x32_bf16 v[40:43], v[182:185], v[198:201], v[40:43]
	v_mfma_f32_16x16x32_bf16 v[52:55], v[156:159], v[198:201], v[52:55]
	v_mfma_f32_16x16x32_bf16 v[52:55], v[152:155], v[194:197], v[52:55]
	v_mfma_f32_16x16x32_bf16 v[48:51], v[162:165], v[194:197], v[48:51]
	v_mfma_f32_16x16x32_bf16 v[48:51], v[166:169], v[198:201], v[48:51]
	v_mfma_f32_16x16x32_bf16 v[44:47], v[174:177], v[198:201], v[44:47]
	v_mfma_f32_16x16x32_bf16 v[44:47], v[170:173], v[194:197], v[44:47]
	v_mfma_f32_16x16x32_bf16 v[24:27], v[170:173], v[202:205], v[24:27]
	v_mfma_f32_16x16x32_bf16 v[24:27], v[174:177], v[206:209], v[24:27]
	v_mfma_f32_16x16x32_bf16 v[32:35], v[156:159], v[206:209], v[32:35]
	v_mfma_f32_16x16x32_bf16 v[32:35], v[152:155], v[202:205], v[32:35]
	v_mfma_f32_16x16x32_bf16 v[28:31], v[162:165], v[202:205], v[28:31]
	v_mfma_f32_16x16x32_bf16 v[28:31], v[166:169], v[206:209], v[28:31]
	v_mfma_f32_16x16x32_bf16 v[20:23], v[182:185], v[206:209], v[20:23]
	v_mfma_f32_16x16x32_bf16 v[20:23], v[178:181], v[202:205], v[20:23]
	v_mfma_f32_16x16x32_bf16 v[4:7], v[178:181], v[210:213], v[4:7]
	v_mfma_f32_16x16x32_bf16 v[4:7], v[182:185], v[214:217], v[4:7]
	v_mfma_f32_16x16x32_bf16 v[16:19], v[156:159], v[214:217], v[16:19]
	v_mfma_f32_16x16x32_bf16 v[16:19], v[152:155], v[210:213], v[16:19]
	v_mfma_f32_16x16x32_bf16 v[12:15], v[162:165], v[210:213], v[12:15]
	v_mfma_f32_16x16x32_bf16 v[12:15], v[166:169], v[214:217], v[12:15]
	v_mfma_f32_16x16x32_bf16 v[8:11], v[174:177], v[214:217], v[8:11]
	v_mfma_f32_16x16x32_bf16 v[8:11], v[170:173], v[210:213], v[8:11]
	s_setprio 0
	s_barrier
; #define PG8_STAGE(bufoff, gbase, voff) do { _Pragma("unroll") for (int _i = 0; _i < 2; ++_i) \
;         __builtin_amdgcn_global_load_lds((const unsigned*)((const char*)(gbase) + (voff)[_i]), (PG8_LAS unsigned*)(lds + (bufoff) + ldsw + _i * 8192), 16, 0, 0); } while (0)
; #define PG8_LDA(dst, b, h) do { _Pragma("unroll") for (int m = 0; m < 4; ++m) _Pragma("unroll") for (int k = 0; k < 2; ++k) dst[m][k] = *(const PG8_LAS bf16x8*)(lds + PG8_SA(b, h) + aoff + m * 2048 + k * 1024); } while (0)
; #define PG8_LDB(dst, b, h) do { _Pragma("unroll") for (int n = 0; n < 2; ++n) _Pragma("unroll") for (int k = 0; k < 2; ++k) dst[n][k] = *(const PG8_LAS bf16x8*)(lds + PG8_SB(b, h) + boff + n * 2048 + k * 1024); } while (0)
; #define PG8_MMA(ai, bj, At, Bt) do { __builtin_amdgcn_s_setprio(1); _Pragma("unroll") for (int m = 0; m < 4; ++m) _Pragma("unroll") for (int n = 0; n < 2; ++n) _Pragma("unroll") for (int k = 0; k < 2; ++k) \
;         acc[ai][bj][m][n] = __builtin_amdgcn_mfma_f32_16x16x32_bf16(Bt[n][k], At[m][k], acc[ai][bj][m][n], 0, 0, 0); __builtin_amdgcn_s_setprio(0); } while (0)
; #define PG8_WAIT_V(n) asm volatile("s_waitcnt vmcnt(" #n ")" ::: "memory")
; #define PG8_WAIT_L(n) asm volatile("s_waitcnt lgkmcnt(" #n ")" ::: "memory")
; #define PG8_BAR __builtin_amdgcn_s_barrier()
; #define PG8_SCHED __builtin_amdgcn_sched_barrier(0)
; template <class Epi, class Sched, bool ALIGN_EPI = false, bool SP2 = false, bool ABLK = false, bool BBLK = false>
; __device__ __forceinline__ void gemm_phase(PG8_LAS unsigned char* lds, const Gemm g, const Sched& S, const Epi& E) {
;     ...
;             PG8_LDB(B0, 1, 0); PG8_LDB(B1, 1, 1); PG8_SCHED; PG8_LDA(At, 1, 0); PG8_STAGE(PG8_SA(0, 1), a2 + hstepA, voffA);
;             PG8_WAIT_V(8); PG8_WAIT_L(0); PG8_BAR; PG8_MMA(0, 0, At, B0); PG8_MMA(0, 1, At, B1); PG8_BAR; PG8_SCHED;
;             PG8_LDA(At, 1, 1); PG8_STAGE(PG8_SB(1, 0), b3, voffB); PG8_STAGE(PG8_SB(1, 1), b3 + hstepB, voffB); PG8_STAGE(PG8_SA(1, 0), a3, voffA);
;             PG8_WAIT_V(8); PG8_WAIT_L(0); PG8_BAR; PG8_MMA(1, 0, At, B0); PG8_MMA(1, 1, At, B1); PG8_BAR; PG8_SCHED;
;     ...
;         if constexpr (ALIGN_EPI) { if (wr == 0) PG8_BAR; }
	s_add_i32 s13, 0, 0x18000
	v_add_u32_e32 v36, s13, v160
	s_add_i32 s68, 0, 0x1c000
	ds_read_b128 v[152:155], v36
	ds_read_b128 v[156:159], v36 offset:1024
	ds_read_b128 v[162:165], v36 offset:2048
	ds_read_b128 v[166:169], v36 offset:3072
	v_add_u32_e32 v36, s68, v160
	ds_read_b128 v[170:173], v36
	ds_read_b128 v[174:177], v36 offset:1024
	ds_read_b128 v[178:181], v36 offset:2048
	ds_read_b128 v[182:185], v36 offset:3072
	s_add_u32 s26, s26, 0x4000
	s_addc_u32 s27, s27, 0
	s_mov_b32 m0, s36
	ds_read_b128 v[186:189], v161 offset:32768
	ds_read_b128 v[190:193], v161 offset:33792
	ds_read_b128 v[194:197], v161 offset:34816
	ds_read_b128 v[198:201], v161 offset:35840
	ds_read_b128 v[202:205], v161 offset:36864
	ds_read_b128 v[206:209], v161 offset:37888
	ds_read_b128 v[210:213], v161 offset:38912
	ds_read_b128 v[214:217], v161 offset:39936
	global_load_lds_dwordx4 v142, s[26:27]
	s_mov_b32 m0, s37
	s_nop 0
	global_load_lds_dwordx4 v138, s[26:27]
	s_waitcnt vmcnt(8)
	s_waitcnt lgkmcnt(0)
	v_mfma_f32_16x16x32_bf16 v[132:135], v[152:155], v[186:189], v[132:135]
	v_mfma_f32_16x16x32_bf16 v[132:135], v[156:159], v[190:193], v[132:135]
	v_mfma_f32_16x16x32_bf16 v[128:131], v[166:169], v[190:193], v[128:131]
	v_mfma_f32_16x16x32_bf16 v[128:131], v[162:165], v[186:189], v[128:131]
	s_barrier
	s_setprio 1
	v_mfma_f32_16x16x32_bf16 v[124:127], v[170:173], v[186:189], v[124:127]
	v_mfma_f32_16x16x32_bf16 v[124:127], v[174:177], v[190:193], v[124:127]
	v_mfma_f32_16x16x32_bf16 v[120:123], v[182:185], v[190:193], v[120:123]
	v_mfma_f32_16x16x32_bf16 v[120:123], v[178:181], v[186:189], v[120:123]
	v_mfma_f32_16x16x32_bf16 v[104:107], v[178:181], v[194:197], v[104:107]
	v_mfma_f32_16x16x32_bf16 v[104:107], v[182:185], v[198:201], v[104:107]
	v_mfma_f32_16x16x32_bf16 v[116:119], v[156:159], v[198:201], v[116:119]
	v_mfma_f32_16x16x32_bf16 v[116:119], v[152:155], v[194:197], v[116:119]
	v_mfma_f32_16x16x32_bf16 v[112:115], v[162:165], v[194:197], v[112:115]
	v_mfma_f32_16x16x32_bf16 v[112:115], v[166:169], v[198:201], v[112:115]
	v_mfma_f32_16x16x32_bf16 v[108:111], v[174:177], v[198:201], v[108:111]
	v_mfma_f32_16x16x32_bf16 v[108:111], v[170:173], v[194:197], v[108:111]
	v_mfma_f32_16x16x32_bf16 v[92:95], v[170:173], v[202:205], v[92:95]
	v_mfma_f32_16x16x32_bf16 v[92:95], v[174:177], v[206:209], v[92:95]
	v_mfma_f32_16x16x32_bf16 v[100:103], v[156:159], v[206:209], v[100:103]
	v_mfma_f32_16x16x32_bf16 v[100:103], v[152:155], v[202:205], v[100:103]
	v_mfma_f32_16x16x32_bf16 v[96:99], v[162:165], v[202:205], v[96:99]
	v_mfma_f32_16x16x32_bf16 v[96:99], v[166:169], v[206:209], v[96:99]
	v_mfma_f32_16x16x32_bf16 v[88:91], v[182:185], v[206:209], v[88:91]
	v_mfma_f32_16x16x32_bf16 v[88:91], v[178:181], v[202:205], v[88:91]
	v_mfma_f32_16x16x32_bf16 v[72:75], v[178:181], v[210:213], v[72:75]
	v_mfma_f32_16x16x32_bf16 v[72:75], v[182:185], v[214:217], v[72:75]
	v_mfma_f32_16x16x32_bf16 v[84:87], v[156:159], v[214:217], v[84:87]
	v_mfma_f32_16x16x32_bf16 v[84:87], v[152:155], v[210:213], v[84:87]
	v_mfma_f32_16x16x32_bf16 v[80:83], v[162:165], v[210:213], v[80:83]
	v_mfma_f32_16x16x32_bf16 v[80:83], v[166:169], v[214:217], v[80:83]
	v_mfma_f32_16x16x32_bf16 v[76:79], v[174:177], v[214:217], v[76:79]
	v_mfma_f32_16x16x32_bf16 v[76:79], v[170:173], v[210:213], v[76:79]
	s_setprio 0
	s_barrier
	s_add_u32 s26, s24, 0x8000
	s_addc_u32 s27, s25, 0
	s_add_i32 s13, s13, s31
	s_mov_b32 m0, s13
	ds_read_b128 v[186:189], v161 offset:49152
	ds_read_b128 v[190:193], v161 offset:50176
	ds_read_b128 v[194:197], v161 offset:51200
	ds_read_b128 v[198:201], v161 offset:52224
	ds_read_b128 v[202:205], v161 offset:53248
	ds_read_b128 v[206:209], v161 offset:54272
	ds_read_b128 v[210:213], v161 offset:55296
	ds_read_b128 v[214:217], v161 offset:56320
	global_load_lds_dwordx4 v140, s[26:27]
	s_add_i32 m0, s13, 0x2000
	s_add_u32 s24, s24, 0xc000
	s_addc_u32 s25, s25, 0
	s_add_i32 s13, s68, s31
	global_load_lds_dwordx4 v136, s[26:27]
	s_mov_b32 m0, s13
	s_nop 0
	global_load_lds_dwordx4 v140, s[24:25]
	s_add_i32 m0, s13, 0x2000
	s_nop 0
	global_load_lds_dwordx4 v136, s[24:25]
	s_mov_b32 m0, s62
	s_nop 0
	global_load_lds_dwordx4 v142, s[22:23]
	s_mov_b32 m0, s63
	s_nop 0
	global_load_lds_dwordx4 v138, s[22:23]
	s_waitcnt vmcnt(8)
	s_waitcnt lgkmcnt(0)
	v_mfma_f32_16x16x32_bf16 v[68:71], v[152:155], v[186:189], v[68:71]
	v_mfma_f32_16x16x32_bf16 v[68:71], v[156:159], v[190:193], v[68:71]
	v_mfma_f32_16x16x32_bf16 v[64:67], v[166:169], v[190:193], v[64:67]
	v_mfma_f32_16x16x32_bf16 v[64:67], v[162:165], v[186:189], v[64:67]
	s_barrier
	s_setprio 1
	v_mfma_f32_16x16x32_bf16 v[60:63], v[170:173], v[186:189], v[60:63]
	v_mfma_f32_16x16x32_bf16 v[60:63], v[174:177], v[190:193], v[60:63]
	v_mfma_f32_16x16x32_bf16 v[56:59], v[182:185], v[190:193], v[56:59]
	v_mfma_f32_16x16x32_bf16 v[56:59], v[178:181], v[186:189], v[56:59]
	v_mfma_f32_16x16x32_bf16 v[40:43], v[178:181], v[194:197], v[40:43]
	v_mfma_f32_16x16x32_bf16 v[40:43], v[182:185], v[198:201], v[40:43]
	v_mfma_f32_16x16x32_bf16 v[52:55], v[156:159], v[198:201], v[52:55]
	v_mfma_f32_16x16x32_bf16 v[52:55], v[152:155], v[194:197], v[52:55]
	v_mfma_f32_16x16x32_bf16 v[48:51], v[162:165], v[194:197], v[48:51]
	v_mfma_f32_16x16x32_bf16 v[48:51], v[166:169], v[198:201], v[48:51]
	v_mfma_f32_16x16x32_bf16 v[44:47], v[174:177], v[198:201], v[44:47]
	v_mfma_f32_16x16x32_bf16 v[44:47], v[170:173], v[194:197], v[44:47]
	v_mfma_f32_16x16x32_bf16 v[24:27], v[170:173], v[202:205], v[24:27]
	v_mfma_f32_16x16x32_bf16 v[24:27], v[174:177], v[206:209], v[24:27]
	v_mfma_f32_16x16x32_bf16 v[32:35], v[156:159], v[206:209], v[32:35]
	v_mfma_f32_16x16x32_bf16 v[32:35], v[152:155], v[202:205], v[32:35]
	v_mfma_f32_16x16x32_bf16 v[28:31], v[162:165], v[202:205], v[28:31]
	v_mfma_f32_16x16x32_bf16 v[28:31], v[166:169], v[206:209], v[28:31]
	v_mfma_f32_16x16x32_bf16 v[20:23], v[182:185], v[206:209], v[20:23]
	v_mfma_f32_16x16x32_bf16 v[20:23], v[178:181], v[202:205], v[20:23]
	v_mfma_f32_16x16x32_bf16 v[4:7], v[178:181], v[210:213], v[4:7]
	v_mfma_f32_16x16x32_bf16 v[4:7], v[182:185], v[214:217], v[4:7]
	v_mfma_f32_16x16x32_bf16 v[16:19], v[156:159], v[214:217], v[16:19]
	v_mfma_f32_16x16x32_bf16 v[16:19], v[152:155], v[210:213], v[16:19]
	v_mfma_f32_16x16x32_bf16 v[12:15], v[162:165], v[210:213], v[12:15]
	v_mfma_f32_16x16x32_bf16 v[12:15], v[166:169], v[214:217], v[12:15]
	v_mfma_f32_16x16x32_bf16 v[8:11], v[174:177], v[214:217], v[8:11]
	v_mfma_f32_16x16x32_bf16 v[8:11], v[170:173], v[210:213], v[8:11]
	s_setprio 0
	s_barrier
	s_add_i32 vcc_hi, vcc_hi, 2
	s_add_u32 s20, s20, 0x10000
	s_addc_u32 s21, s21, 0
	s_add_u32 s77, s77, 0x10000
	s_addc_u32 vcc_lo, vcc_lo, 0
	s_cmp_gt_u32 vcc_hi, 29
	s_cbranch_scc0 .LBB0_185
	s_and_b64 vcc, exec, s[4:5]
	s_cbranch_vccz .LBB0_188
	s_barrier

; #define PG8_STAGE(bufoff, gbase, voff) do { _Pragma("unroll") for (int _i = 0; _i < 2; ++_i) \
;         __builtin_amdgcn_global_load_lds((const unsigned*)((const char*)(gbase) + (voff)[_i]), (PG8_LAS unsigned*)(lds + (bufoff) + ldsw + _i * 8192), 16, 0, 0); } while (0)
; #define PG8_LDA(dst, b, h) do { _Pragma("unroll") for (int m = 0; m < 4; ++m) _Pragma("unroll") for (int k = 0; k < 2; ++k) dst[m][k] = *(const PG8_LAS bf16x8*)(lds + PG8_SA(b, h) + aoff + m * 2048 + k * 1024); } while (0)
; #define PG8_LDB(dst, b, h) do { _Pragma("unroll") for (int n = 0; n < 2; ++n) _Pragma("unroll") for (int k = 0; k < 2; ++k) dst[n][k] = *(const PG8_LAS bf16x8*)(lds + PG8_SB(b, h) + boff + n * 2048 + k * 1024); } while (0)
; #define PG8_MMA(ai, bj, At, Bt) do { __builtin_amdgcn_s_setprio(1); _Pragma("unroll") for (int m = 0; m < 4; ++m) _Pragma("unroll") for (int n = 0; n < 2; ++n) _Pragma("unroll") for (int k = 0; k < 2; ++k) \
;         acc[ai][bj][m][n] = __builtin_amdgcn_mfma_f32_16x16x32_bf16(Bt[n][k], At[m][k], acc[ai][bj][m][n], 0, 0, 0); __builtin_amdgcn_s_setprio(0); } while (0)
; #define PG8_WAIT_V(n) asm volatile("s_waitcnt vmcnt(" #n ")" ::: "memory")
; template <class Epi, class Sched, bool ALIGN_EPI = false, bool SP2 = false, bool ABLK = false, bool BBLK = false>
; __device__ __forceinline__ void gemm_phase(PG8_LAS unsigned char* lds, const Gemm g, const Sched& S, const Epi& E) {
;     ...
;         for (int t = 0; t < nt; t += 2) {
;             const bool last = (t == nt - 2);
;             const char* a1 = cA + (size_t)(t + 1) * kstepA;
;             const char* a2 = last ? nA : cA + (size_t)(t + 2) * kstepA; const char* b2 = last ? nB : cB + (size_t)(t + 2) * kstepB;
;             const char* a3 = a2 + kstepA; const char* b3 = b2 + kstepB;
;             if (last && has_next) S.a_ready(nxt);
;             if constexpr (SP2) {
;             PG8_LDB(B0, 0, 0); PG8_LDB(B1, 0, 1); PG8_SCHED; PG8_LDA(At, 0, 0); PG8_STAGE(PG8_SA(1, 1), a1 + hstepA, voffA);
;             PG8_WAIT_V(8); PG8_WAIT_L(0); PG8_BAR; PG8_MMA(0, 0, At, B0); PG8_MMA(0, 1, At, B1); PG8_BAR; PG8_SCHED;
;             PG8_LDA(At, 0, 1); PG8_STAGE(PG8_SB(0, 0), b2, voffB); PG8_STAGE(PG8_SB(0, 1), b2 + hstepB, voffB); PG8_STAGE(PG8_SA(0, 0), a2, voffA);
;             PG8_WAIT_V(8); PG8_WAIT_L(0); PG8_BAR; PG8_MMA(1, 0, At, B0); PG8_MMA(1, 1, At, B1); PG8_BAR; PG8_SCHED;
.LBB0_438:
	s_add_u32 s10, s10, 0xc000
	s_addc_u32 s11, s11, 0
	s_add_u32 vcc_lo, s16, 0x10000
	s_addc_u32 vcc_hi, s17, 0
	s_mov_b32 s13, -2
	s_add_u32 s16, s10, 0x4000
	s_addc_u32 s17, s11, 0
	s_cmpk_eq_i32 s13, 0x54
	s_cselect_b32 s20, s0, s16
	s_cselect_b32 s21, s1, s17
	s_cselect_b32 s18, s8, vcc_lo
	s_cselect_b32 s19, s9, vcc_hi
	s_add_u32 s16, s20, 0x8000
	s_addc_u32 s17, s21, 0
	s_add_i32 s68, 0, 0x10000
	v_add_u32_e32 v36, s68, v148
	s_add_i32 s88, 0, 0x14000
	ds_read_b128 v[152:155], v36
	ds_read_b128 v[156:159], v36 offset:1024
	ds_read_b128 v[160:163], v36 offset:2048
	ds_read_b128 v[164:167], v36 offset:3072
	v_add_u32_e32 v36, s88, v148
	ds_read_b128 v[168:171], v36
	ds_read_b128 v[172:175], v36 offset:1024
	ds_read_b128 v[176:179], v36 offset:2048
	ds_read_b128 v[180:183], v36 offset:3072
	s_add_i32 m0, s27, 0xc000
	ds_read_b128 v[184:187], v150
	ds_read_b128 v[188:191], v150 offset:1024
	ds_read_b128 v[192:195], v150 offset:2048
	ds_read_b128 v[196:199], v150 offset:3072
	ds_read_b128 v[200:203], v150 offset:4096
	ds_read_b128 v[204:207], v150 offset:5120
	ds_read_b128 v[208:211], v150 offset:6144
	ds_read_b128 v[212:215], v150 offset:7168
	global_load_lds_dwordx4 v144, s[10:11]
	s_add_i32 m0, s27, 0xe000
	s_nop 0
	global_load_lds_dwordx4 v146, s[10:11]
	s_waitcnt vmcnt(8)
	s_waitcnt lgkmcnt(0)
	v_mfma_f32_16x16x32_bf16 v[132:135], v[152:155], v[184:187], 0
	v_mfma_f32_16x16x32_bf16 v[132:135], v[156:159], v[188:191], v[132:135]
	v_mfma_f32_16x16x32_bf16 v[128:131], v[164:167], v[188:191], 0
	v_mfma_f32_16x16x32_bf16 v[128:131], v[160:163], v[184:187], v[128:131]
	s_barrier
	s_setprio 1
	v_mfma_f32_16x16x32_bf16 v[116:119], v[168:171], v[184:187], 0
	v_mfma_f32_16x16x32_bf16 v[116:119], v[172:175], v[188:191], v[116:119]
	v_mfma_f32_16x16x32_bf16 v[112:115], v[180:183], v[188:191], 0
	v_mfma_f32_16x16x32_bf16 v[112:115], v[176:179], v[184:187], v[112:115]
	v_mfma_f32_16x16x32_bf16 v[96:99], v[176:179], v[192:195], 0
	v_mfma_f32_16x16x32_bf16 v[96:99], v[180:183], v[196:199], v[96:99]
	v_mfma_f32_16x16x32_bf16 v[124:127], v[156:159], v[196:199], 0
	v_mfma_f32_16x16x32_bf16 v[124:127], v[152:155], v[192:195], v[124:127]
	v_mfma_f32_16x16x32_bf16 v[120:123], v[160:163], v[192:195], 0
	v_mfma_f32_16x16x32_bf16 v[120:123], v[164:167], v[196:199], v[120:123]
	v_mfma_f32_16x16x32_bf16 v[100:103], v[172:175], v[196:199], 0
	v_mfma_f32_16x16x32_bf16 v[100:103], v[168:171], v[192:195], v[100:103]
	v_mfma_f32_16x16x32_bf16 v[84:87], v[168:171], v[200:203], 0
	v_mfma_f32_16x16x32_bf16 v[84:87], v[172:175], v[204:207], v[84:87]
	v_mfma_f32_16x16x32_bf16 v[108:111], v[156:159], v[204:207], 0
	v_mfma_f32_16x16x32_bf16 v[108:111], v[152:155], v[200:203], v[108:111]
	v_mfma_f32_16x16x32_bf16 v[104:107], v[160:163], v[200:203], 0
	v_mfma_f32_16x16x32_bf16 v[104:107], v[164:167], v[204:207], v[104:107]
	v_mfma_f32_16x16x32_bf16 v[80:83], v[180:183], v[204:207], 0
	v_mfma_f32_16x16x32_bf16 v[80:83], v[176:179], v[200:203], v[80:83]
	v_mfma_f32_16x16x32_bf16 v[72:75], v[176:179], v[208:211], 0
	v_mfma_f32_16x16x32_bf16 v[72:75], v[180:183], v[212:215], v[72:75]
	v_mfma_f32_16x16x32_bf16 v[92:95], v[156:159], v[212:215], 0
	v_mfma_f32_16x16x32_bf16 v[92:95], v[152:155], v[208:211], v[92:95]
	v_mfma_f32_16x16x32_bf16 v[88:91], v[160:163], v[208:211], 0
	v_mfma_f32_16x16x32_bf16 v[88:91], v[164:167], v[212:215], v[88:91]
	v_mfma_f32_16x16x32_bf16 v[76:79], v[172:175], v[212:215], 0
	v_mfma_f32_16x16x32_bf16 v[76:79], v[168:171], v[208:211], v[76:79]
	s_setprio 0
	s_barrier
	s_add_i32 s68, s68, s24
	s_mov_b32 m0, s68
	ds_read_b128 v[184:187], v150 offset:16384
	ds_read_b128 v[188:191], v150 offset:17408
	ds_read_b128 v[192:195], v150 offset:18432
	ds_read_b128 v[196:199], v150 offset:19456
	ds_read_b128 v[200:203], v150 offset:20480
	ds_read_b128 v[204:207], v150 offset:21504
	ds_read_b128 v[208:211], v150 offset:22528
	ds_read_b128 v[212:215], v150 offset:23552
	global_load_lds_dwordx4 v138, s[18:19]
	s_add_i32 m0, s68, 0x2000
	s_add_u32 s68, s18, 0x4000
	s_addc_u32 s69, s19, 0
	s_add_i32 s88, s88, s24
	global_load_lds_dwordx4 v142, s[18:19]
	s_mov_b32 m0, s88
	s_nop 0
	global_load_lds_dwordx4 v138, s[68:69]
	s_add_i32 m0, s88, 0x2000
	s_nop 0
	global_load_lds_dwordx4 v142, s[68:69]
	s_mov_b32 m0, s27
	s_nop 0
	global_load_lds_dwordx4 v136, s[20:21]
	s_mov_b32 m0, s28
	s_nop 0
	global_load_lds_dwordx4 v140, s[20:21]
	s_waitcnt vmcnt(8)
	s_waitcnt lgkmcnt(0)
	v_mfma_f32_16x16x32_bf16 v[68:71], v[152:155], v[184:187], 0
	v_mfma_f32_16x16x32_bf16 v[68:71], v[156:159], v[188:191], v[68:71]
	v_mfma_f32_16x16x32_bf16 v[64:67], v[164:167], v[188:191], 0
	v_mfma_f32_16x16x32_bf16 v[64:67], v[160:163], v[184:187], v[64:67]
	s_barrier
	s_setprio 1
	v_mfma_f32_16x16x32_bf16 v[52:55], v[168:171], v[184:187], 0
	v_mfma_f32_16x16x32_bf16 v[52:55], v[172:175], v[188:191], v[52:55]
	v_mfma_f32_16x16x32_bf16 v[48:51], v[180:183], v[188:191], 0
	v_mfma_f32_16x16x32_bf16 v[48:51], v[176:179], v[184:187], v[48:51]
	v_mfma_f32_16x16x32_bf16 v[28:31], v[176:179], v[192:195], 0
	v_mfma_f32_16x16x32_bf16 v[28:31], v[180:183], v[196:199], v[28:31]
	v_mfma_f32_16x16x32_bf16 v[60:63], v[156:159], v[196:199], 0
	v_mfma_f32_16x16x32_bf16 v[60:63], v[152:155], v[192:195], v[60:63]
	v_mfma_f32_16x16x32_bf16 v[56:59], v[160:163], v[192:195], 0
	v_mfma_f32_16x16x32_bf16 v[56:59], v[164:167], v[196:199], v[56:59]
	v_mfma_f32_16x16x32_bf16 v[32:35], v[172:175], v[196:199], 0
	v_mfma_f32_16x16x32_bf16 v[32:35], v[168:171], v[192:195], v[32:35]
	v_mfma_f32_16x16x32_bf16 v[16:19], v[168:171], v[200:203], 0
	v_mfma_f32_16x16x32_bf16 v[16:19], v[172:175], v[204:207], v[16:19]
	v_mfma_f32_16x16x32_bf16 v[44:47], v[156:159], v[204:207], 0
	v_mfma_f32_16x16x32_bf16 v[44:47], v[152:155], v[200:203], v[44:47]
	v_mfma_f32_16x16x32_bf16 v[40:43], v[160:163], v[200:203], 0
	v_mfma_f32_16x16x32_bf16 v[40:43], v[164:167], v[204:207], v[40:43]
	v_mfma_f32_16x16x32_bf16 v[12:15], v[180:183], v[204:207], 0
	v_mfma_f32_16x16x32_bf16 v[12:15], v[176:179], v[200:203], v[12:15]
	v_mfma_f32_16x16x32_bf16 v[4:7], v[176:179], v[208:211], 0
	v_mfma_f32_16x16x32_bf16 v[4:7], v[180:183], v[212:215], v[4:7]
	v_mfma_f32_16x16x32_bf16 v[24:27], v[156:159], v[212:215], 0
	v_mfma_f32_16x16x32_bf16 v[24:27], v[152:155], v[208:211], v[24:27]
	v_mfma_f32_16x16x32_bf16 v[20:23], v[160:163], v[208:211], 0
	v_mfma_f32_16x16x32_bf16 v[20:23], v[164:167], v[212:215], v[20:23]
	v_mfma_f32_16x16x32_bf16 v[8:11], v[172:175], v[212:215], 0
	v_mfma_f32_16x16x32_bf16 v[8:11], v[168:171], v[208:211], v[8:11]
	s_setprio 0
	s_barrier
; #define PG8_STAGE(bufoff, gbase, voff) do { _Pragma("unroll") for (int _i = 0; _i < 2; ++_i) \
;         __builtin_amdgcn_global_load_lds((const unsigned*)((const char*)(gbase) + (voff)[_i]), (PG8_LAS unsigned*)(lds + (bufoff) + ldsw + _i * 8192), 16, 0, 0); } while (0)
; #define PG8_LDA(dst, b, h) do { _Pragma("unroll") for (int m = 0; m < 4; ++m) _Pragma("unroll") for (int k = 0; k < 2; ++k) dst[m][k] = *(const PG8_LAS bf16x8*)(lds + PG8_SA(b, h) + aoff + m * 2048 + k * 1024); } while (0)
; #define PG8_LDB(dst, b, h) do { _Pragma("unroll") for (int n = 0; n < 2; ++n) _Pragma("unroll") for (int k = 0; k < 2; ++k) dst[n][k] = *(const PG8_LAS bf16x8*)(lds + PG8_SB(b, h) + boff + n * 2048 + k * 1024); } while (0)
; #define PG8_MMA(ai, bj, At, Bt) do { __builtin_amdgcn_s_setprio(1); _Pragma("unroll") for (int m = 0; m < 4; ++m) _Pragma("unroll") for (int n = 0; n < 2; ++n) _Pragma("unroll") for (int k = 0; k < 2; ++k) \
;         acc[ai][bj][m][n] = __builtin_amdgcn_mfma_f32_16x16x32_bf16(Bt[n][k], At[m][k], acc[ai][bj][m][n], 0, 0, 0); __builtin_amdgcn_s_setprio(0); } while (0)
; #define PG8_WAIT_V(n) asm volatile("s_waitcnt vmcnt(" #n ")" ::: "memory")
; #define PG8_WAIT_L(n) asm volatile("s_waitcnt lgkmcnt(" #n ")" ::: "memory")
; #define PG8_BAR __builtin_amdgcn_s_barrier()
; #define PG8_SCHED __builtin_amdgcn_sched_barrier(0)
; template <class Epi, class Sched, bool ALIGN_EPI = false, bool SP2 = false, bool ABLK = false, bool BBLK = false>
; __device__ __forceinline__ void gemm_phase(PG8_LAS unsigned char* lds, const Gemm g, const Sched& S, const Epi& E) {
;     ...
;             PG8_LDB(B0, 1, 0); PG8_LDB(B1, 1, 1); PG8_SCHED; PG8_LDA(At, 1, 0); PG8_STAGE(PG8_SA(0, 1), a2 + hstepA, voffA);
;             PG8_WAIT_V(8); PG8_WAIT_L(0); PG8_BAR; PG8_MMA(0, 0, At, B0); PG8_MMA(0, 1, At, B1); PG8_BAR; PG8_SCHED;
;             PG8_LDA(At, 1, 1); PG8_STAGE(PG8_SB(1, 0), b3, voffB); PG8_STAGE(PG8_SB(1, 1), b3 + hstepB, voffB); PG8_STAGE(PG8_SA(1, 0), a3, voffA);
;             PG8_WAIT_V(8); PG8_WAIT_L(0); PG8_BAR; PG8_MMA(1, 0, At, B0); PG8_MMA(1, 1, At, B1); PG8_BAR; PG8_SCHED;
	s_add_i32 s68, 0, 0x18000
	v_add_u32_e32 v36, s68, v148
	s_add_i32 s69, 0, 0x1c000
	ds_read_b128 v[152:155], v36
	ds_read_b128 v[156:159], v36 offset:1024
	ds_read_b128 v[160:163], v36 offset:2048
	ds_read_b128 v[164:167], v36 offset:3072
	v_add_u32_e32 v36, s69, v148
	ds_read_b128 v[168:171], v36
	ds_read_b128 v[172:175], v36 offset:1024
	ds_read_b128 v[176:179], v36 offset:2048
	ds_read_b128 v[180:183], v36 offset:3072
	s_add_u32 s20, s20, 0x4000
	s_addc_u32 s21, s21, 0
	s_mov_b32 m0, s29
	ds_read_b128 v[184:187], v150 offset:32768
	ds_read_b128 v[188:191], v150 offset:33792
	ds_read_b128 v[192:195], v150 offset:34816
	ds_read_b128 v[196:199], v150 offset:35840
	ds_read_b128 v[200:203], v150 offset:36864
	ds_read_b128 v[204:207], v150 offset:37888
	ds_read_b128 v[208:211], v150 offset:38912
	ds_read_b128 v[212:215], v150 offset:39936
	global_load_lds_dwordx4 v136, s[20:21]
	s_mov_b32 m0, s30
	s_nop 0
	global_load_lds_dwordx4 v140, s[20:21]
	s_waitcnt vmcnt(8)
	s_waitcnt lgkmcnt(0)
	v_mfma_f32_16x16x32_bf16 v[132:135], v[152:155], v[184:187], v[132:135]
	v_mfma_f32_16x16x32_bf16 v[132:135], v[156:159], v[188:191], v[132:135]
	v_mfma_f32_16x16x32_bf16 v[128:131], v[164:167], v[188:191], v[128:131]
	v_mfma_f32_16x16x32_bf16 v[128:131], v[160:163], v[184:187], v[128:131]
	s_barrier
	s_setprio 1
	v_mfma_f32_16x16x32_bf16 v[116:119], v[168:171], v[184:187], v[116:119]
	v_mfma_f32_16x16x32_bf16 v[116:119], v[172:175], v[188:191], v[116:119]
	v_mfma_f32_16x16x32_bf16 v[112:115], v[180:183], v[188:191], v[112:115]
	v_mfma_f32_16x16x32_bf16 v[112:115], v[176:179], v[184:187], v[112:115]
	v_mfma_f32_16x16x32_bf16 v[96:99], v[176:179], v[192:195], v[96:99]
	v_mfma_f32_16x16x32_bf16 v[96:99], v[180:183], v[196:199], v[96:99]
	v_mfma_f32_16x16x32_bf16 v[124:127], v[156:159], v[196:199], v[124:127]
	v_mfma_f32_16x16x32_bf16 v[124:127], v[152:155], v[192:195], v[124:127]
	v_mfma_f32_16x16x32_bf16 v[120:123], v[160:163], v[192:195], v[120:123]
	v_mfma_f32_16x16x32_bf16 v[120:123], v[164:167], v[196:199], v[120:123]
	v_mfma_f32_16x16x32_bf16 v[100:103], v[172:175], v[196:199], v[100:103]
	v_mfma_f32_16x16x32_bf16 v[100:103], v[168:171], v[192:195], v[100:103]
	v_mfma_f32_16x16x32_bf16 v[84:87], v[168:171], v[200:203], v[84:87]
	v_mfma_f32_16x16x32_bf16 v[84:87], v[172:175], v[204:207], v[84:87]
	v_mfma_f32_16x16x32_bf16 v[108:111], v[156:159], v[204:207], v[108:111]
	v_mfma_f32_16x16x32_bf16 v[108:111], v[152:155], v[200:203], v[108:111]
	v_mfma_f32_16x16x32_bf16 v[104:107], v[160:163], v[200:203], v[104:107]
	v_mfma_f32_16x16x32_bf16 v[104:107], v[164:167], v[204:207], v[104:107]
	v_mfma_f32_16x16x32_bf16 v[80:83], v[180:183], v[204:207], v[80:83]
	v_mfma_f32_16x16x32_bf16 v[80:83], v[176:179], v[200:203], v[80:83]
	v_mfma_f32_16x16x32_bf16 v[72:75], v[176:179], v[208:211], v[72:75]
	v_mfma_f32_16x16x32_bf16 v[72:75], v[180:183], v[212:215], v[72:75]
	v_mfma_f32_16x16x32_bf16 v[92:95], v[156:159], v[212:215], v[92:95]
	v_mfma_f32_16x16x32_bf16 v[92:95], v[152:155], v[208:211], v[92:95]
	v_mfma_f32_16x16x32_bf16 v[88:91], v[160:163], v[208:211], v[88:91]
	v_mfma_f32_16x16x32_bf16 v[88:91], v[164:167], v[212:215], v[88:91]
	v_mfma_f32_16x16x32_bf16 v[76:79], v[172:175], v[212:215], v[76:79]
	v_mfma_f32_16x16x32_bf16 v[76:79], v[168:171], v[208:211], v[76:79]
	s_setprio 0
	s_barrier
	s_add_u32 s20, s18, 0x8000
	s_addc_u32 s21, s19, 0
	s_add_i32 s68, s68, s24
	s_mov_b32 m0, s68
	ds_read_b128 v[184:187], v150 offset:49152
	ds_read_b128 v[188:191], v150 offset:50176
	ds_read_b128 v[192:195], v150 offset:51200
	ds_read_b128 v[196:199], v150 offset:52224
	ds_read_b128 v[200:203], v150 offset:53248
	ds_read_b128 v[204:207], v150 offset:54272
	ds_read_b128 v[208:211], v150 offset:55296
	ds_read_b128 v[212:215], v150 offset:56320
	global_load_lds_dwordx4 v138, s[20:21]
	s_add_i32 m0, s68, 0x2000
	s_add_u32 s18, s18, 0xc000
	s_addc_u32 s19, s19, 0
	global_load_lds_dwordx4 v142, s[20:21]
	s_add_i32 s20, s69, s24
	s_mov_b32 m0, s20
	s_nop 0
	global_load_lds_dwordx4 v138, s[18:19]
	s_add_i32 m0, s20, 0x2000
	s_nop 0
	global_load_lds_dwordx4 v142, s[18:19]
	s_mov_b32 m0, s35
	s_nop 0
	global_load_lds_dwordx4 v136, s[16:17]
	s_mov_b32 m0, s70
	s_nop 0
	global_load_lds_dwordx4 v140, s[16:17]
	s_waitcnt vmcnt(8)
	s_waitcnt lgkmcnt(0)
	v_mfma_f32_16x16x32_bf16 v[68:71], v[152:155], v[184:187], v[68:71]
	v_mfma_f32_16x16x32_bf16 v[68:71], v[156:159], v[188:191], v[68:71]
	v_mfma_f32_16x16x32_bf16 v[64:67], v[164:167], v[188:191], v[64:67]
	v_mfma_f32_16x16x32_bf16 v[64:67], v[160:163], v[184:187], v[64:67]
	s_barrier
	s_setprio 1
	v_mfma_f32_16x16x32_bf16 v[52:55], v[168:171], v[184:187], v[52:55]
	v_mfma_f32_16x16x32_bf16 v[52:55], v[172:175], v[188:191], v[52:55]
	v_mfma_f32_16x16x32_bf16 v[48:51], v[180:183], v[188:191], v[48:51]
	v_mfma_f32_16x16x32_bf16 v[48:51], v[176:179], v[184:187], v[48:51]
	v_mfma_f32_16x16x32_bf16 v[28:31], v[176:179], v[192:195], v[28:31]
	v_mfma_f32_16x16x32_bf16 v[28:31], v[180:183], v[196:199], v[28:31]
	v_mfma_f32_16x16x32_bf16 v[60:63], v[156:159], v[196:199], v[60:63]
	v_mfma_f32_16x16x32_bf16 v[60:63], v[152:155], v[192:195], v[60:63]
	v_mfma_f32_16x16x32_bf16 v[56:59], v[160:163], v[192:195], v[56:59]
	v_mfma_f32_16x16x32_bf16 v[56:59], v[164:167], v[196:199], v[56:59]
	v_mfma_f32_16x16x32_bf16 v[32:35], v[172:175], v[196:199], v[32:35]
	v_mfma_f32_16x16x32_bf16 v[32:35], v[168:171], v[192:195], v[32:35]
	v_mfma_f32_16x16x32_bf16 v[16:19], v[168:171], v[200:203], v[16:19]
	v_mfma_f32_16x16x32_bf16 v[16:19], v[172:175], v[204:207], v[16:19]
	v_mfma_f32_16x16x32_bf16 v[44:47], v[156:159], v[204:207], v[44:47]
	v_mfma_f32_16x16x32_bf16 v[44:47], v[152:155], v[200:203], v[44:47]
	v_mfma_f32_16x16x32_bf16 v[40:43], v[160:163], v[200:203], v[40:43]
	v_mfma_f32_16x16x32_bf16 v[40:43], v[164:167], v[204:207], v[40:43]
	v_mfma_f32_16x16x32_bf16 v[12:15], v[180:183], v[204:207], v[12:15]
	v_mfma_f32_16x16x32_bf16 v[12:15], v[176:179], v[200:203], v[12:15]
	v_mfma_f32_16x16x32_bf16 v[4:7], v[176:179], v[208:211], v[4:7]
	v_mfma_f32_16x16x32_bf16 v[4:7], v[180:183], v[212:215], v[4:7]
	v_mfma_f32_16x16x32_bf16 v[24:27], v[156:159], v[212:215], v[24:27]
	v_mfma_f32_16x16x32_bf16 v[24:27], v[152:155], v[208:211], v[24:27]
	v_mfma_f32_16x16x32_bf16 v[20:23], v[160:163], v[208:211], v[20:23]
	v_mfma_f32_16x16x32_bf16 v[20:23], v[164:167], v[212:215], v[20:23]
	v_mfma_f32_16x16x32_bf16 v[8:11], v[172:175], v[212:215], v[8:11]
	v_mfma_f32_16x16x32_bf16 v[8:11], v[168:171], v[208:211], v[8:11]
	s_setprio 0
	s_barrier
	s_add_i32 s13, s13, 2
	s_add_u32 s10, s10, 0x10000
	s_addc_u32 s11, s11, 0
	s_add_u32 vcc_lo, vcc_lo, 0x10000
	s_addc_u32 vcc_hi, vcc_hi, 0
	s_cmpk_gt_u32 s13, 0x55
; #define PG8_STAGE(bufoff, gbase, voff) do { _Pragma("unroll") for (int _i = 0; _i < 2; ++_i) \
;         __builtin_amdgcn_global_load_lds((const unsigned*)((const char*)(gbase) + (voff)[_i]), (PG8_LAS unsigned*)(lds + (bufoff) + ldsw + _i * 8192), 16, 0, 0); } while (0)
; #define PG8_LDA(dst, b, h) do { _Pragma("unroll") for (int m = 0; m < 4; ++m) _Pragma("unroll") for (int k = 0; k < 2; ++k) dst[m][k] = *(const PG8_LAS bf16x8*)(lds + PG8_SA(b, h) + aoff + m * 2048 + k * 1024); } while (0)
; #define PG8_LDB(dst, b, h) do { _Pragma("unroll") for (int n = 0; n < 2; ++n) _Pragma("unroll") for (int k = 0; k < 2; ++k) dst[n][k] = *(const PG8_LAS bf16x8*)(lds + PG8_SB(b, h) + boff + n * 2048 + k * 1024); } while (0)
; #define PG8_MMA(ai, bj, At, Bt) do { __builtin_amdgcn_s_setprio(1); _Pragma("unroll") for (int m = 0; m < 4; ++m) _Pragma("unroll") for (int n = 0; n < 2; ++n) _Pragma("unroll") for (int k = 0; k < 2; ++k) \
;         acc[ai][bj][m][n] = __builtin_amdgcn_mfma_f32_16x16x32_bf16(Bt[n][k], At[m][k], acc[ai][bj][m][n], 0, 0, 0); __builtin_amdgcn_s_setprio(0); } while (0)
; #define PG8_WAIT_V(n) asm volatile("s_waitcnt vmcnt(" #n ")" ::: "memory")
; template <class Epi, class Sched, bool ALIGN_EPI = false, bool SP2 = false, bool ABLK = false, bool BBLK = false>
; __device__ __forceinline__ void gemm_phase(PG8_LAS unsigned char* lds, const Gemm g, const Sched& S, const Epi& E) {
;     ...
;         for (int t = 0; t < nt; t += 2) {
;             const bool last = (t == nt - 2);
;             const char* a1 = cA + (size_t)(t + 1) * kstepA;
;             const char* a2 = last ? nA : cA + (size_t)(t + 2) * kstepA; const char* b2 = last ? nB : cB + (size_t)(t + 2) * kstepB;
;             const char* a3 = a2 + kstepA; const char* b3 = b2 + kstepB;
;             if (last && has_next) S.a_ready(nxt);
;             if constexpr (SP2) {
;             PG8_LDB(B0, 0, 0); PG8_LDB(B1, 0, 1); PG8_SCHED; PG8_LDA(At, 0, 0); PG8_STAGE(PG8_SA(1, 1), a1 + hstepA, voffA);
;             PG8_WAIT_V(8); PG8_WAIT_L(0); PG8_BAR; PG8_MMA(0, 0, At, B0); PG8_MMA(0, 1, At, B1); PG8_BAR; PG8_SCHED;
;             PG8_LDA(At, 0, 1); PG8_STAGE(PG8_SB(0, 0), b2, voffB); PG8_STAGE(PG8_SB(0, 1), b2 + hstepB, voffB); PG8_STAGE(PG8_SA(0, 0), a2, voffA);
;             PG8_WAIT_V(8); PG8_WAIT_L(0); PG8_BAR; PG8_MMA(1, 0, At, B0); PG8_MMA(1, 1, At, B1); PG8_BAR; PG8_SCHED;
.LBB0_439:
	s_add_u32 s16, s10, 0x4000
	s_addc_u32 s17, s11, 0
	s_cmpk_eq_i32 s13, 0x54
	s_cselect_b32 s20, s0, s16
	s_cselect_b32 s21, s1, s17
	s_cselect_b32 s18, s8, vcc_lo
	s_cselect_b32 s19, s9, vcc_hi
	s_add_u32 s16, s20, 0x8000
	s_addc_u32 s17, s21, 0
	s_add_i32 s68, 0, 0x10000
	v_add_u32_e32 v36, s68, v148
	s_add_i32 s88, 0, 0x14000
	ds_read_b128 v[152:155], v36
	ds_read_b128 v[156:159], v36 offset:1024
	ds_read_b128 v[160:163], v36 offset:2048
	ds_read_b128 v[164:167], v36 offset:3072
	v_add_u32_e32 v36, s88, v148
	ds_read_b128 v[168:171], v36
	ds_read_b128 v[172:175], v36 offset:1024
	ds_read_b128 v[176:179], v36 offset:2048
	ds_read_b128 v[180:183], v36 offset:3072
	s_add_i32 m0, s27, 0xc000
	ds_read_b128 v[184:187], v150
	ds_read_b128 v[188:191], v150 offset:1024
	ds_read_b128 v[192:195], v150 offset:2048
	ds_read_b128 v[196:199], v150 offset:3072
	ds_read_b128 v[200:203], v150 offset:4096
	ds_read_b128 v[204:207], v150 offset:5120
	ds_read_b128 v[208:211], v150 offset:6144
	ds_read_b128 v[212:215], v150 offset:7168
	global_load_lds_dwordx4 v144, s[10:11]
	s_add_i32 m0, s27, 0xe000
	s_nop 0
	global_load_lds_dwordx4 v146, s[10:11]
	s_waitcnt vmcnt(8)
	s_waitcnt lgkmcnt(0)
	v_mfma_f32_16x16x32_bf16 v[132:135], v[152:155], v[184:187], v[132:135]
	v_mfma_f32_16x16x32_bf16 v[132:135], v[156:159], v[188:191], v[132:135]
	v_mfma_f32_16x16x32_bf16 v[128:131], v[164:167], v[188:191], v[128:131]
	v_mfma_f32_16x16x32_bf16 v[128:131], v[160:163], v[184:187], v[128:131]
	s_barrier
	s_setprio 1
	v_mfma_f32_16x16x32_bf16 v[116:119], v[168:171], v[184:187], v[116:119]
	v_mfma_f32_16x16x32_bf16 v[116:119], v[172:175], v[188:191], v[116:119]
	v_mfma_f32_16x16x32_bf16 v[112:115], v[180:183], v[188:191], v[112:115]
	v_mfma_f32_16x16x32_bf16 v[112:115], v[176:179], v[184:187], v[112:115]
	v_mfma_f32_16x16x32_bf16 v[96:99], v[176:179], v[192:195], v[96:99]
	v_mfma_f32_16x16x32_bf16 v[96:99], v[180:183], v[196:199], v[96:99]
	v_mfma_f32_16x16x32_bf16 v[124:127], v[156:159], v[196:199], v[124:127]
	v_mfma_f32_16x16x32_bf16 v[124:127], v[152:155], v[192:195], v[124:127]
	v_mfma_f32_16x16x32_bf16 v[120:123], v[160:163], v[192:195], v[120:123]
	v_mfma_f32_16x16x32_bf16 v[120:123], v[164:167], v[196:199], v[120:123]
	v_mfma_f32_16x16x32_bf16 v[100:103], v[172:175], v[196:199], v[100:103]
	v_mfma_f32_16x16x32_bf16 v[100:103], v[168:171], v[192:195], v[100:103]
	v_mfma_f32_16x16x32_bf16 v[84:87], v[168:171], v[200:203], v[84:87]
	v_mfma_f32_16x16x32_bf16 v[84:87], v[172:175], v[204:207], v[84:87]
	v_mfma_f32_16x16x32_bf16 v[108:111], v[156:159], v[204:207], v[108:111]
	v_mfma_f32_16x16x32_bf16 v[108:111], v[152:155], v[200:203], v[108:111]
	v_mfma_f32_16x16x32_bf16 v[104:107], v[160:163], v[200:203], v[104:107]
	v_mfma_f32_16x16x32_bf16 v[104:107], v[164:167], v[204:207], v[104:107]
	v_mfma_f32_16x16x32_bf16 v[80:83], v[180:183], v[204:207], v[80:83]
	v_mfma_f32_16x16x32_bf16 v[80:83], v[176:179], v[200:203], v[80:83]
	v_mfma_f32_16x16x32_bf16 v[72:75], v[176:179], v[208:211], v[72:75]
	v_mfma_f32_16x16x32_bf16 v[72:75], v[180:183], v[212:215], v[72:75]
	v_mfma_f32_16x16x32_bf16 v[92:95], v[156:159], v[212:215], v[92:95]
	v_mfma_f32_16x16x32_bf16 v[92:95], v[152:155], v[208:211], v[92:95]
	v_mfma_f32_16x16x32_bf16 v[88:91], v[160:163], v[208:211], v[88:91]
	v_mfma_f32_16x16x32_bf16 v[88:91], v[164:167], v[212:215], v[88:91]
	v_mfma_f32_16x16x32_bf16 v[76:79], v[172:175], v[212:215], v[76:79]
	v_mfma_f32_16x16x32_bf16 v[76:79], v[168:171], v[208:211], v[76:79]
	s_setprio 0
	s_barrier
	s_add_i32 s68, s68, s24
	s_mov_b32 m0, s68
	ds_read_b128 v[184:187], v150 offset:16384
	ds_read_b128 v[188:191], v150 offset:17408
	ds_read_b128 v[192:195], v150 offset:18432
	ds_read_b128 v[196:199], v150 offset:19456
	ds_read_b128 v[200:203], v150 offset:20480
	ds_read_b128 v[204:207], v150 offset:21504
	ds_read_b128 v[208:211], v150 offset:22528
	ds_read_b128 v[212:215], v150 offset:23552
	global_load_lds_dwordx4 v138, s[18:19]
	s_add_i32 m0, s68, 0x2000
	s_add_u32 s68, s18, 0x4000
	s_addc_u32 s69, s19, 0
	s_add_i32 s88, s88, s24
	global_load_lds_dwordx4 v142, s[18:19]
	s_mov_b32 m0, s88
	s_nop 0
	global_load_lds_dwordx4 v138, s[68:69]
	s_add_i32 m0, s88, 0x2000
	s_nop 0
	global_load_lds_dwordx4 v142, s[68:69]
	s_mov_b32 m0, s27
	s_nop 0
	global_load_lds_dwordx4 v136, s[20:21]
	s_mov_b32 m0, s28
	s_nop 0
	global_load_lds_dwordx4 v140, s[20:21]
	s_waitcnt vmcnt(8)
	s_waitcnt lgkmcnt(0)
	v_mfma_f32_16x16x32_bf16 v[68:71], v[152:155], v[184:187], v[68:71]
	v_mfma_f32_16x16x32_bf16 v[68:71], v[156:159], v[188:191], v[68:71]
	v_mfma_f32_16x16x32_bf16 v[64:67], v[164:167], v[188:191], v[64:67]
	v_mfma_f32_16x16x32_bf16 v[64:67], v[160:163], v[184:187], v[64:67]
	s_barrier
; #define PG8_STAGE(bufoff, gbase, voff) do { _Pragma("unroll") for (int _i = 0; _i < 2; ++_i) \
;         __builtin_amdgcn_global_load_lds((const unsigned*)((const char*)(gbase) + (voff)[_i]), (PG8_LAS unsigned*)(lds + (bufoff) + ldsw + _i * 8192), 16, 0, 0); } while (0)
; #define PG8_LDA(dst, b, h) do { _Pragma("unroll") for (int m = 0; m < 4; ++m) _Pragma("unroll") for (int k = 0; k < 2; ++k) dst[m][k] = *(const PG8_LAS bf16x8*)(lds + PG8_SA(b, h) + aoff + m * 2048 + k * 1024); } while (0)
; #define PG8_LDB(dst, b, h) do { _Pragma("unroll") for (int n = 0; n < 2; ++n) _Pragma("unroll") for (int k = 0; k < 2; ++k) dst[n][k] = *(const PG8_LAS bf16x8*)(lds + PG8_SB(b, h) + boff + n * 2048 + k * 1024); } while (0)
; #define PG8_MMA(ai, bj, At, Bt) do { __builtin_amdgcn_s_setprio(1); _Pragma("unroll") for (int m = 0; m < 4; ++m) _Pragma("unroll") for (int n = 0; n < 2; ++n) _Pragma("unroll") for (int k = 0; k < 2; ++k) \
;         acc[ai][bj][m][n] = __builtin_amdgcn_mfma_f32_16x16x32_bf16(Bt[n][k], At[m][k], acc[ai][bj][m][n], 0, 0, 0); __builtin_amdgcn_s_setprio(0); } while (0)
; #define PG8_WAIT_V(n) asm volatile("s_waitcnt vmcnt(" #n ")" ::: "memory")
; #define PG8_WAIT_L(n) asm volatile("s_waitcnt lgkmcnt(" #n ")" ::: "memory")
; #define PG8_BAR __builtin_amdgcn_s_barrier()
; #define PG8_SCHED __builtin_amdgcn_sched_barrier(0)
; template <class Epi, class Sched, bool ALIGN_EPI = false, bool SP2 = false, bool ABLK = false, bool BBLK = false>
; __device__ __forceinline__ void gemm_phase(PG8_LAS unsigned char* lds, const Gemm g, const Sched& S, const Epi& E) {
;     ...
;             PG8_WAIT_V(8); PG8_WAIT_L(0); PG8_BAR; PG8_MMA(0, 0, At, B0); PG8_MMA(0, 1, At, B1); PG8_BAR; PG8_SCHED;
;             PG8_LDA(At, 0, 1); PG8_STAGE(PG8_SB(0, 0), b2, voffB); PG8_STAGE(PG8_SB(0, 1), b2 + hstepB, voffB); PG8_STAGE(PG8_SA(0, 0), a2, voffA);
;             PG8_WAIT_V(8); PG8_WAIT_L(0); PG8_BAR; PG8_MMA(1, 0, At, B0); PG8_MMA(1, 1, At, B1); PG8_BAR; PG8_SCHED;
;             PG8_LDB(B0, 1, 0); PG8_LDB(B1, 1, 1); PG8_SCHED; PG8_LDA(At, 1, 0); PG8_STAGE(PG8_SA(0, 1), a2 + hstepA, voffA);
;             PG8_WAIT_V(8); PG8_WAIT_L(0); PG8_BAR; PG8_MMA(0, 0, At, B0); PG8_MMA(0, 1, At, B1); PG8_BAR; PG8_SCHED;
	s_setprio 1
	v_mfma_f32_16x16x32_bf16 v[52:55], v[168:171], v[184:187], v[52:55]
	v_mfma_f32_16x16x32_bf16 v[52:55], v[172:175], v[188:191], v[52:55]
	v_mfma_f32_16x16x32_bf16 v[48:51], v[180:183], v[188:191], v[48:51]
	v_mfma_f32_16x16x32_bf16 v[48:51], v[176:179], v[184:187], v[48:51]
	v_mfma_f32_16x16x32_bf16 v[28:31], v[176:179], v[192:195], v[28:31]
	v_mfma_f32_16x16x32_bf16 v[28:31], v[180:183], v[196:199], v[28:31]
	v_mfma_f32_16x16x32_bf16 v[60:63], v[156:159], v[196:199], v[60:63]
	v_mfma_f32_16x16x32_bf16 v[60:63], v[152:155], v[192:195], v[60:63]
	v_mfma_f32_16x16x32_bf16 v[56:59], v[160:163], v[192:195], v[56:59]
	v_mfma_f32_16x16x32_bf16 v[56:59], v[164:167], v[196:199], v[56:59]
	v_mfma_f32_16x16x32_bf16 v[32:35], v[172:175], v[196:199], v[32:35]
	v_mfma_f32_16x16x32_bf16 v[32:35], v[168:171], v[192:195], v[32:35]
	v_mfma_f32_16x16x32_bf16 v[16:19], v[168:171], v[200:203], v[16:19]
	v_mfma_f32_16x16x32_bf16 v[16:19], v[172:175], v[204:207], v[16:19]
	v_mfma_f32_16x16x32_bf16 v[44:47], v[156:159], v[204:207], v[44:47]
	v_mfma_f32_16x16x32_bf16 v[44:47], v[152:155], v[200:203], v[44:47]
	v_mfma_f32_16x16x32_bf16 v[40:43], v[160:163], v[200:203], v[40:43]
	v_mfma_f32_16x16x32_bf16 v[40:43], v[164:167], v[204:207], v[40:43]
	v_mfma_f32_16x16x32_bf16 v[12:15], v[180:183], v[204:207], v[12:15]
	v_mfma_f32_16x16x32_bf16 v[12:15], v[176:179], v[200:203], v[12:15]
	v_mfma_f32_16x16x32_bf16 v[4:7], v[176:179], v[208:211], v[4:7]
	v_mfma_f32_16x16x32_bf16 v[4:7], v[180:183], v[212:215], v[4:7]
	v_mfma_f32_16x16x32_bf16 v[24:27], v[156:159], v[212:215], v[24:27]
	v_mfma_f32_16x16x32_bf16 v[24:27], v[152:155], v[208:211], v[24:27]
	v_mfma_f32_16x16x32_bf16 v[20:23], v[160:163], v[208:211], v[20:23]
	v_mfma_f32_16x16x32_bf16 v[20:23], v[164:167], v[212:215], v[20:23]
	v_mfma_f32_16x16x32_bf16 v[8:11], v[172:175], v[212:215], v[8:11]
	v_mfma_f32_16x16x32_bf16 v[8:11], v[168:171], v[208:211], v[8:11]
	s_setprio 0
	s_barrier
	s_add_i32 s68, 0, 0x18000
	v_add_u32_e32 v36, s68, v148
	s_add_i32 s69, 0, 0x1c000
	ds_read_b128 v[152:155], v36
	ds_read_b128 v[156:159], v36 offset:1024
	ds_read_b128 v[160:163], v36 offset:2048
	ds_read_b128 v[164:167], v36 offset:3072
	v_add_u32_e32 v36, s69, v148
	ds_read_b128 v[168:171], v36
	ds_read_b128 v[172:175], v36 offset:1024
	ds_read_b128 v[176:179], v36 offset:2048
	ds_read_b128 v[180:183], v36 offset:3072
	s_add_u32 s20, s20, 0x4000
	s_addc_u32 s21, s21, 0
	s_mov_b32 m0, s29
	ds_read_b128 v[184:187], v150 offset:32768
	ds_read_b128 v[188:191], v150 offset:33792
	ds_read_b128 v[192:195], v150 offset:34816
	ds_read_b128 v[196:199], v150 offset:35840
	ds_read_b128 v[200:203], v150 offset:36864
	ds_read_b128 v[204:207], v150 offset:37888
	ds_read_b128 v[208:211], v150 offset:38912
	ds_read_b128 v[212:215], v150 offset:39936
	global_load_lds_dwordx4 v136, s[20:21]
	s_mov_b32 m0, s30
	s_nop 0
	global_load_lds_dwordx4 v140, s[20:21]
	s_waitcnt vmcnt(8)
	s_waitcnt lgkmcnt(0)
	v_mfma_f32_16x16x32_bf16 v[132:135], v[152:155], v[184:187], v[132:135]
	v_mfma_f32_16x16x32_bf16 v[132:135], v[156:159], v[188:191], v[132:135]
	v_mfma_f32_16x16x32_bf16 v[128:131], v[164:167], v[188:191], v[128:131]
	v_mfma_f32_16x16x32_bf16 v[128:131], v[160:163], v[184:187], v[128:131]
	s_barrier
	s_setprio 1
	v_mfma_f32_16x16x32_bf16 v[116:119], v[168:171], v[184:187], v[116:119]
	v_mfma_f32_16x16x32_bf16 v[116:119], v[172:175], v[188:191], v[116:119]
	v_mfma_f32_16x16x32_bf16 v[112:115], v[180:183], v[188:191], v[112:115]
	v_mfma_f32_16x16x32_bf16 v[112:115], v[176:179], v[184:187], v[112:115]
	v_mfma_f32_16x16x32_bf16 v[96:99], v[176:179], v[192:195], v[96:99]
	v_mfma_f32_16x16x32_bf16 v[96:99], v[180:183], v[196:199], v[96:99]
	v_mfma_f32_16x16x32_bf16 v[124:127], v[156:159], v[196:199], v[124:127]
	v_mfma_f32_16x16x32_bf16 v[124:127], v[152:155], v[192:195], v[124:127]
	v_mfma_f32_16x16x32_bf16 v[120:123], v[160:163], v[192:195], v[120:123]
	v_mfma_f32_16x16x32_bf16 v[120:123], v[164:167], v[196:199], v[120:123]
	v_mfma_f32_16x16x32_bf16 v[100:103], v[172:175], v[196:199], v[100:103]
	v_mfma_f32_16x16x32_bf16 v[100:103], v[168:171], v[192:195], v[100:103]
	v_mfma_f32_16x16x32_bf16 v[84:87], v[168:171], v[200:203], v[84:87]
	v_mfma_f32_16x16x32_bf16 v[84:87], v[172:175], v[204:207], v[84:87]
	v_mfma_f32_16x16x32_bf16 v[108:111], v[156:159], v[204:207], v[108:111]
	v_mfma_f32_16x16x32_bf16 v[108:111], v[152:155], v[200:203], v[108:111]
	v_mfma_f32_16x16x32_bf16 v[104:107], v[160:163], v[200:203], v[104:107]
	v_mfma_f32_16x16x32_bf16 v[104:107], v[164:167], v[204:207], v[104:107]
	v_mfma_f32_16x16x32_bf16 v[80:83], v[180:183], v[204:207], v[80:83]
	v_mfma_f32_16x16x32_bf16 v[80:83], v[176:179], v[200:203], v[80:83]
	v_mfma_f32_16x16x32_bf16 v[72:75], v[176:179], v[208:211], v[72:75]
	v_mfma_f32_16x16x32_bf16 v[72:75], v[180:183], v[212:215], v[72:75]
	v_mfma_f32_16x16x32_bf16 v[92:95], v[156:159], v[212:215], v[92:95]
	v_mfma_f32_16x16x32_bf16 v[92:95], v[152:155], v[208:211], v[92:95]
	v_mfma_f32_16x16x32_bf16 v[88:91], v[160:163], v[208:211], v[88:91]
	v_mfma_f32_16x16x32_bf16 v[88:91], v[164:167], v[212:215], v[88:91]
	v_mfma_f32_16x16x32_bf16 v[76:79], v[172:175], v[212:215], v[76:79]
	v_mfma_f32_16x16x32_bf16 v[76:79], v[168:171], v[208:211], v[76:79]
	s_setprio 0
	s_barrier
; #define PG8_STAGE(bufoff, gbase, voff) do { _Pragma("unroll") for (int _i = 0; _i < 2; ++_i) \
;         __builtin_amdgcn_global_load_lds((const unsigned*)((const char*)(gbase) + (voff)[_i]), (PG8_LAS unsigned*)(lds + (bufoff) + ldsw + _i * 8192), 16, 0, 0); } while (0)
; #define PG8_LDA(dst, b, h) do { _Pragma("unroll") for (int m = 0; m < 4; ++m) _Pragma("unroll") for (int k = 0; k < 2; ++k) dst[m][k] = *(const PG8_LAS bf16x8*)(lds + PG8_SA(b, h) + aoff + m * 2048 + k * 1024); } while (0)
; #define PG8_MMA(ai, bj, At, Bt) do { __builtin_amdgcn_s_setprio(1); _Pragma("unroll") for (int m = 0; m < 4; ++m) _Pragma("unroll") for (int n = 0; n < 2; ++n) _Pragma("unroll") for (int k = 0; k < 2; ++k) \
;         acc[ai][bj][m][n] = __builtin_amdgcn_mfma_f32_16x16x32_bf16(Bt[n][k], At[m][k], acc[ai][bj][m][n], 0, 0, 0); __builtin_amdgcn_s_setprio(0); } while (0)
; #define PG8_WAIT_V(n) asm volatile("s_waitcnt vmcnt(" #n ")" ::: "memory")
; #define PG8_WAIT_L(n) asm volatile("s_waitcnt lgkmcnt(" #n ")" ::: "memory")
; #define PG8_BAR __builtin_amdgcn_s_barrier()
; #define PG8_SCHED __builtin_amdgcn_sched_barrier(0)
; template <class Epi, class Sched, bool ALIGN_EPI = false, bool SP2 = false, bool ABLK = false, bool BBLK = false>
; __device__ __forceinline__ void gemm_phase(PG8_LAS unsigned char* lds, const Gemm g, const Sched& S, const Epi& E) {
;     ...
;             PG8_LDA(At, 1, 1); PG8_STAGE(PG8_SB(1, 0), b3, voffB); PG8_STAGE(PG8_SB(1, 1), b3 + hstepB, voffB); PG8_STAGE(PG8_SA(1, 0), a3, voffA);
;             PG8_WAIT_V(8); PG8_WAIT_L(0); PG8_BAR; PG8_MMA(1, 0, At, B0); PG8_MMA(1, 1, At, B1); PG8_BAR; PG8_SCHED;
	s_add_u32 s20, s18, 0x8000
	s_addc_u32 s21, s19, 0
	s_add_i32 s68, s68, s24
	s_mov_b32 m0, s68
	ds_read_b128 v[184:187], v150 offset:49152
	ds_read_b128 v[188:191], v150 offset:50176
	ds_read_b128 v[192:195], v150 offset:51200
	ds_read_b128 v[196:199], v150 offset:52224
	ds_read_b128 v[200:203], v150 offset:53248
	ds_read_b128 v[204:207], v150 offset:54272
	ds_read_b128 v[208:211], v150 offset:55296
	ds_read_b128 v[212:215], v150 offset:56320
	global_load_lds_dwordx4 v138, s[20:21]
	s_add_i32 m0, s68, 0x2000
	s_add_u32 s18, s18, 0xc000
	s_addc_u32 s19, s19, 0
	global_load_lds_dwordx4 v142, s[20:21]
	s_add_i32 s20, s69, s24
	s_mov_b32 m0, s20
	s_nop 0
	global_load_lds_dwordx4 v138, s[18:19]
	s_add_i32 m0, s20, 0x2000
	s_nop 0
	global_load_lds_dwordx4 v142, s[18:19]
	s_mov_b32 m0, s35
	s_nop 0
	global_load_lds_dwordx4 v136, s[16:17]
	s_mov_b32 m0, s70
	s_nop 0
	global_load_lds_dwordx4 v140, s[16:17]
	s_waitcnt vmcnt(8)
	s_waitcnt lgkmcnt(0)
	v_mfma_f32_16x16x32_bf16 v[68:71], v[152:155], v[184:187], v[68:71]
	v_mfma_f32_16x16x32_bf16 v[68:71], v[156:159], v[188:191], v[68:71]
	v_mfma_f32_16x16x32_bf16 v[64:67], v[164:167], v[188:191], v[64:67]
	v_mfma_f32_16x16x32_bf16 v[64:67], v[160:163], v[184:187], v[64:67]
	s_barrier
	s_setprio 1
	v_mfma_f32_16x16x32_bf16 v[52:55], v[168:171], v[184:187], v[52:55]
	v_mfma_f32_16x16x32_bf16 v[52:55], v[172:175], v[188:191], v[52:55]
	v_mfma_f32_16x16x32_bf16 v[48:51], v[180:183], v[188:191], v[48:51]
	v_mfma_f32_16x16x32_bf16 v[48:51], v[176:179], v[184:187], v[48:51]
	v_mfma_f32_16x16x32_bf16 v[28:31], v[176:179], v[192:195], v[28:31]
	v_mfma_f32_16x16x32_bf16 v[28:31], v[180:183], v[196:199], v[28:31]
	v_mfma_f32_16x16x32_bf16 v[60:63], v[156:159], v[196:199], v[60:63]
	v_mfma_f32_16x16x32_bf16 v[60:63], v[152:155], v[192:195], v[60:63]
	v_mfma_f32_16x16x32_bf16 v[56:59], v[160:163], v[192:195], v[56:59]
	v_mfma_f32_16x16x32_bf16 v[56:59], v[164:167], v[196:199], v[56:59]
	v_mfma_f32_16x16x32_bf16 v[32:35], v[172:175], v[196:199], v[32:35]
	v_mfma_f32_16x16x32_bf16 v[32:35], v[168:171], v[192:195], v[32:35]
	v_mfma_f32_16x16x32_bf16 v[16:19], v[168:171], v[200:203], v[16:19]
	v_mfma_f32_16x16x32_bf16 v[16:19], v[172:175], v[204:207], v[16:19]
	v_mfma_f32_16x16x32_bf16 v[44:47], v[156:159], v[204:207], v[44:47]
	v_mfma_f32_16x16x32_bf16 v[44:47], v[152:155], v[200:203], v[44:47]
	v_mfma_f32_16x16x32_bf16 v[40:43], v[160:163], v[200:203], v[40:43]
	v_mfma_f32_16x16x32_bf16 v[40:43], v[164:167], v[204:207], v[40:43]
	v_mfma_f32_16x16x32_bf16 v[12:15], v[180:183], v[204:207], v[12:15]
	v_mfma_f32_16x16x32_bf16 v[12:15], v[176:179], v[200:203], v[12:15]
	v_mfma_f32_16x16x32_bf16 v[4:7], v[176:179], v[208:211], v[4:7]
	v_mfma_f32_16x16x32_bf16 v[4:7], v[180:183], v[212:215], v[4:7]
	v_mfma_f32_16x16x32_bf16 v[24:27], v[156:159], v[212:215], v[24:27]
	v_mfma_f32_16x16x32_bf16 v[24:27], v[152:155], v[208:211], v[24:27]
	v_mfma_f32_16x16x32_bf16 v[20:23], v[160:163], v[208:211], v[20:23]
	v_mfma_f32_16x16x32_bf16 v[20:23], v[164:167], v[212:215], v[20:23]
	v_mfma_f32_16x16x32_bf16 v[8:11], v[172:175], v[212:215], v[8:11]
	v_mfma_f32_16x16x32_bf16 v[8:11], v[168:171], v[208:211], v[8:11]
	s_setprio 0
	s_barrier
	s_add_i32 s13, s13, 2
	s_add_u32 s10, s10, 0x10000
	s_addc_u32 s11, s11, 0
	s_add_u32 vcc_lo, vcc_lo, 0x10000
	s_addc_u32 vcc_hi, vcc_hi, 0
	s_cmpk_gt_u32 s13, 0x55
	s_cbranch_scc0 .LBB0_439
	s_and_b64 vcc, exec, s[6:7]
	s_cbranch_vccz .LBB0_442
	s_barrier

; #define PG8_LAS __attribute__((address_space(3)))
; #define PG8_STAGE(bufoff, gbase, voff) do { _Pragma("unroll") for (int _i = 0; _i < 2; ++_i) \
;         __builtin_amdgcn_global_load_lds((const unsigned*)((const char*)(gbase) + (voff)[_i]), (PG8_LAS unsigned*)(lds + (bufoff) + ldsw + _i * 8192), 16, 0, 0); } while (0)
; #define PG8_LDA(dst, b, h) do { _Pragma("unroll") for (int m = 0; m < 4; ++m) _Pragma("unroll") for (int k = 0; k < 2; ++k) dst[m][k] = *(const PG8_LAS bf16x8*)(lds + PG8_SA(b, h) + aoff + m * 2048 + k * 1024); } while (0)
; #define PG8_LDB(dst, b, h) do { _Pragma("unroll") for (int n = 0; n < 2; ++n) _Pragma("unroll") for (int k = 0; k < 2; ++k) dst[n][k] = *(const PG8_LAS bf16x8*)(lds + PG8_SB(b, h) + boff + n * 2048 + k * 1024); } while (0)
; #define PG8_WAIT_V(n) asm volatile("s_waitcnt vmcnt(" #n ")" ::: "memory")
; template <class Epi, class Sched, bool ALIGN_EPI = false, bool SP2 = false, bool ABLK = false, bool BBLK = false>
; __device__ __forceinline__ void gemm_phase(PG8_LAS unsigned char* lds, const Gemm g, const Sched& S, const Epi& E) {
;     ...
;         const bool has_next = S.next(ui + 1, nxt);
;         PG8_LAS unsigned char* const rs_area = lds + STAGE_BYTES + wid * 512;
;         E.stage(cur, rs_area, wr, lane);
;         const char* nA = has_next ? (const char*)g.A + (size_t)nxt.pm * tstep : cA; const char* nB = has_next ? (const char*)g.Bt + (size_t)nxt.pn * tstep : cB;
;         for (int t = 0; t < nt; t += 2) {
;             const bool last = (t == nt - 2);
;             const char* a1 = cA + (size_t)(t + 1) * kstepA;
;             const char* a2 = last ? nA : cA + (size_t)(t + 2) * kstepA; const char* b2 = last ? nB : cB + (size_t)(t + 2) * kstepB;
;             const char* a3 = a2 + kstepA; const char* b3 = b2 + kstepB;
;             if (last && has_next) S.a_ready(nxt);
;             if constexpr (SP2) {
;             PG8_LDB(B0, 0, 0); PG8_LDB(B1, 0, 1); PG8_SCHED; PG8_LDA(At, 0, 0); PG8_STAGE(PG8_SA(1, 1), a1 + hstepA, voffA);
;             PG8_WAIT_V(8); PG8_WAIT_L(0); PG8_BAR; PG8_MMA(0, 0, At, B0); PG8_MMA(0, 1, At, B1); PG8_BAR; PG8_SCHED;
;             PG8_LDA(At, 0, 1); PG8_STAGE(PG8_SB(0, 0), b2, voffB); PG8_STAGE(PG8_SB(0, 1), b2 + hstepB, voffB); PG8_STAGE(PG8_SA(0, 0), a2, voffA);
;             PG8_WAIT_V(8); PG8_WAIT_L(0); PG8_BAR; PG8_MMA(1, 0, At, B0); PG8_MMA(1, 1, At, B1); PG8_BAR; PG8_SCHED;
.LBB0_915:
	s_lshl_b32 s18, s0, 8
	s_ashr_i32 s19, s18, 31
	s_mov_b32 m0, s63
	v_lshl_add_u64 v[4:5], s[18:19], 2, v[144:145]
	v_lshl_add_u64 v[6:7], v[4:5], 0, s[90:91]
	global_load_lds_dword v[4:5], off
	s_add_i32 m0, s63, 0x100
	s_mov_b32 s0, s1
	global_load_lds_dword v[6:7], off
	s_ashr_i32 s1, s1, 31
	s_lshl_b64 s[10:11], s[0:1], 20
	v_readlane_b32 s16, v252, 27
	v_readlane_b32 s17, v252, 28
	s_add_u32 s10, s16, s10
	s_addc_u32 s11, s17, s11
	s_and_b64 s[16:17], s[2:3], exec
	s_cselect_b32 s1, s11, s21
	s_cselect_b32 s19, s10, s20
	s_ashr_i32 s9, s8, 31
	s_lshl_b64 s[16:17], s[8:9], 20
	v_readlane_b32 s24, v254, 5
	v_readlane_b32 s25, v254, 6
	s_add_u32 s16, s24, s16
	s_addc_u32 s17, s25, s17
	s_and_b64 s[24:25], s[2:3], exec
	s_cselect_b32 s9, s17, s23
	s_cselect_b32 s65, s16, s22
	s_add_u32 s20, s20, 0xc000
	s_addc_u32 s21, s21, 0
	s_add_u32 s70, s22, 0x10000
	s_addc_u32 s71, s23, 0
	s_mov_b32 s13, -2
	s_add_u32 s22, s20, 0x4000
	s_addc_u32 s23, s21, 0
	s_cmp_eq_u32 s13, 28
	s_cselect_b32 s26, s19, s22
	s_cselect_b32 s27, s1, s23
	s_cselect_b32 s24, s65, s70
	s_cselect_b32 s25, s9, s71
	s_add_u32 s22, s26, 0x8000
	s_addc_u32 s23, s27, 0
	s_add_i32 s68, 0, 0x10000
	v_add_u32_e32 v36, s68, v155
	s_add_i32 s77, 0, 0x14000
	ds_read_b128 v[150:153], v36
	ds_read_b128 v[158:161], v36 offset:1024
	ds_read_b128 v[162:165], v36 offset:2048
	ds_read_b128 v[166:169], v36 offset:3072
	v_add_u32_e32 v36, s77, v155
	ds_read_b128 v[170:173], v36
	ds_read_b128 v[174:177], v36 offset:1024
	ds_read_b128 v[178:181], v36 offset:2048
	ds_read_b128 v[182:185], v36 offset:3072
	s_add_i32 m0, s31, 0xc000
	ds_read_b128 v[186:189], v157
	ds_read_b128 v[190:193], v157 offset:1024
	ds_read_b128 v[194:197], v157 offset:2048
	ds_read_b128 v[198:201], v157 offset:3072
	ds_read_b128 v[202:205], v157 offset:4096
	ds_read_b128 v[206:209], v157 offset:5120
	ds_read_b128 v[210:213], v157 offset:6144
	ds_read_b128 v[214:217], v157 offset:7168
	global_load_lds_dwordx4 v146, s[20:21]
	s_add_i32 m0, s31, 0xe000
	s_nop 0
	global_load_lds_dwordx4 v148, s[20:21]
	s_waitcnt vmcnt(8)
	s_waitcnt lgkmcnt(0)
	v_mfma_f32_16x16x32_bf16 v[132:135], v[150:153], v[186:189], 0
	v_mfma_f32_16x16x32_bf16 v[132:135], v[158:161], v[190:193], v[132:135]
	v_mfma_f32_16x16x32_bf16 v[128:131], v[166:169], v[190:193], 0
	v_mfma_f32_16x16x32_bf16 v[128:131], v[162:165], v[186:189], v[128:131]
	s_barrier
	s_setprio 1
	v_mfma_f32_16x16x32_bf16 v[120:123], v[170:173], v[186:189], 0
	v_mfma_f32_16x16x32_bf16 v[120:123], v[174:177], v[190:193], v[120:123]
	v_mfma_f32_16x16x32_bf16 v[112:115], v[182:185], v[190:193], 0
	v_mfma_f32_16x16x32_bf16 v[112:115], v[178:181], v[186:189], v[112:115]
	v_mfma_f32_16x16x32_bf16 v[96:99], v[178:181], v[194:197], 0
	v_mfma_f32_16x16x32_bf16 v[96:99], v[182:185], v[198:201], v[96:99]
	v_mfma_f32_16x16x32_bf16 v[124:127], v[158:161], v[198:201], 0
	v_mfma_f32_16x16x32_bf16 v[124:127], v[150:153], v[194:197], v[124:127]
	v_mfma_f32_16x16x32_bf16 v[116:119], v[162:165], v[194:197], 0
	v_mfma_f32_16x16x32_bf16 v[116:119], v[166:169], v[198:201], v[116:119]
	v_mfma_f32_16x16x32_bf16 v[104:107], v[174:177], v[198:201], 0
	v_mfma_f32_16x16x32_bf16 v[104:107], v[170:173], v[194:197], v[104:107]
	v_mfma_f32_16x16x32_bf16 v[88:91], v[170:173], v[202:205], 0
	v_mfma_f32_16x16x32_bf16 v[88:91], v[174:177], v[206:209], v[88:91]
	v_mfma_f32_16x16x32_bf16 v[108:111], v[158:161], v[206:209], 0
	v_mfma_f32_16x16x32_bf16 v[108:111], v[150:153], v[202:205], v[108:111]
	v_mfma_f32_16x16x32_bf16 v[100:103], v[162:165], v[202:205], 0
	v_mfma_f32_16x16x32_bf16 v[100:103], v[166:169], v[206:209], v[100:103]
	v_mfma_f32_16x16x32_bf16 v[80:83], v[182:185], v[206:209], 0
	v_mfma_f32_16x16x32_bf16 v[80:83], v[178:181], v[202:205], v[80:83]
	v_mfma_f32_16x16x32_bf16 v[72:75], v[178:181], v[210:213], 0
	v_mfma_f32_16x16x32_bf16 v[72:75], v[182:185], v[214:217], v[72:75]
	v_mfma_f32_16x16x32_bf16 v[92:95], v[158:161], v[214:217], 0
	v_mfma_f32_16x16x32_bf16 v[92:95], v[150:153], v[210:213], v[92:95]
	v_mfma_f32_16x16x32_bf16 v[84:87], v[162:165], v[210:213], 0
	v_mfma_f32_16x16x32_bf16 v[84:87], v[166:169], v[214:217], v[84:87]
	v_mfma_f32_16x16x32_bf16 v[76:79], v[174:177], v[214:217], 0
	v_mfma_f32_16x16x32_bf16 v[76:79], v[170:173], v[210:213], v[76:79]
	s_setprio 0
	s_barrier
	s_add_i32 s68, s68, s29
	s_mov_b32 m0, s68
	ds_read_b128 v[186:189], v157 offset:16384
	ds_read_b128 v[190:193], v157 offset:17408
	ds_read_b128 v[194:197], v157 offset:18432
	ds_read_b128 v[198:201], v157 offset:19456
	ds_read_b128 v[202:205], v157 offset:20480
	ds_read_b128 v[206:209], v157 offset:21504
	ds_read_b128 v[210:213], v157 offset:22528
	ds_read_b128 v[214:217], v157 offset:23552
	global_load_lds_dwordx4 v140, s[24:25]
	s_add_i32 m0, s68, 0x2000
	s_add_u32 s68, s24, 0x4000
	s_addc_u32 s69, s25, 0
	s_add_i32 s77, s77, s29
	global_load_lds_dwordx4 v136, s[24:25]
	s_mov_b32 m0, s77
	s_nop 0
	global_load_lds_dwordx4 v140, s[68:69]
	s_add_i32 m0, s77, 0x2000
	s_nop 0
	global_load_lds_dwordx4 v136, s[68:69]
	s_mov_b32 m0, s31
	s_nop 0
	global_load_lds_dwordx4 v142, s[26:27]
	s_mov_b32 m0, s34
	s_nop 0
	global_load_lds_dwordx4 v138, s[26:27]
	s_waitcnt vmcnt(8)
	s_waitcnt lgkmcnt(0)
	v_mfma_f32_16x16x32_bf16 v[68:71], v[150:153], v[186:189], 0
	v_mfma_f32_16x16x32_bf16 v[68:71], v[158:161], v[190:193], v[68:71]
	v_mfma_f32_16x16x32_bf16 v[64:67], v[166:169], v[190:193], 0
	v_mfma_f32_16x16x32_bf16 v[64:67], v[162:165], v[186:189], v[64:67]
	s_barrier
; #define PG8_STAGE(bufoff, gbase, voff) do { _Pragma("unroll") for (int _i = 0; _i < 2; ++_i) \
;         __builtin_amdgcn_global_load_lds((const unsigned*)((const char*)(gbase) + (voff)[_i]), (PG8_LAS unsigned*)(lds + (bufoff) + ldsw + _i * 8192), 16, 0, 0); } while (0)
; #define PG8_LDA(dst, b, h) do { _Pragma("unroll") for (int m = 0; m < 4; ++m) _Pragma("unroll") for (int k = 0; k < 2; ++k) dst[m][k] = *(const PG8_LAS bf16x8*)(lds + PG8_SA(b, h) + aoff + m * 2048 + k * 1024); } while (0)
; #define PG8_LDB(dst, b, h) do { _Pragma("unroll") for (int n = 0; n < 2; ++n) _Pragma("unroll") for (int k = 0; k < 2; ++k) dst[n][k] = *(const PG8_LAS bf16x8*)(lds + PG8_SB(b, h) + boff + n * 2048 + k * 1024); } while (0)
; #define PG8_MMA(ai, bj, At, Bt) do { __builtin_amdgcn_s_setprio(1); _Pragma("unroll") for (int m = 0; m < 4; ++m) _Pragma("unroll") for (int n = 0; n < 2; ++n) _Pragma("unroll") for (int k = 0; k < 2; ++k) \
;         acc[ai][bj][m][n] = __builtin_amdgcn_mfma_f32_16x16x32_bf16(Bt[n][k], At[m][k], acc[ai][bj][m][n], 0, 0, 0); __builtin_amdgcn_s_setprio(0); } while (0)
; #define PG8_WAIT_V(n) asm volatile("s_waitcnt vmcnt(" #n ")" ::: "memory")
; #define PG8_WAIT_L(n) asm volatile("s_waitcnt lgkmcnt(" #n ")" ::: "memory")
; #define PG8_BAR __builtin_amdgcn_s_barrier()
; #define PG8_SCHED __builtin_amdgcn_sched_barrier(0)
; template <class Epi, class Sched, bool ALIGN_EPI = false, bool SP2 = false, bool ABLK = false, bool BBLK = false>
; __device__ __forceinline__ void gemm_phase(PG8_LAS unsigned char* lds, const Gemm g, const Sched& S, const Epi& E) {
;     ...
;             PG8_WAIT_V(8); PG8_WAIT_L(0); PG8_BAR; PG8_MMA(0, 0, At, B0); PG8_MMA(0, 1, At, B1); PG8_BAR; PG8_SCHED;
;             PG8_LDA(At, 0, 1); PG8_STAGE(PG8_SB(0, 0), b2, voffB); PG8_STAGE(PG8_SB(0, 1), b2 + hstepB, voffB); PG8_STAGE(PG8_SA(0, 0), a2, voffA);
;             PG8_WAIT_V(8); PG8_WAIT_L(0); PG8_BAR; PG8_MMA(1, 0, At, B0); PG8_MMA(1, 1, At, B1); PG8_BAR; PG8_SCHED;
;             PG8_LDB(B0, 1, 0); PG8_LDB(B1, 1, 1); PG8_SCHED; PG8_LDA(At, 1, 0); PG8_STAGE(PG8_SA(0, 1), a2 + hstepA, voffA);
;             PG8_WAIT_V(8); PG8_WAIT_L(0); PG8_BAR; PG8_MMA(0, 0, At, B0); PG8_MMA(0, 1, At, B1); PG8_BAR; PG8_SCHED;
	s_setprio 1
	v_mfma_f32_16x16x32_bf16 v[56:59], v[170:173], v[186:189], 0
	v_mfma_f32_16x16x32_bf16 v[56:59], v[174:177], v[190:193], v[56:59]
	v_mfma_f32_16x16x32_bf16 v[48:51], v[182:185], v[190:193], 0
	v_mfma_f32_16x16x32_bf16 v[48:51], v[178:181], v[186:189], v[48:51]
	v_mfma_f32_16x16x32_bf16 v[28:31], v[178:181], v[194:197], 0
	v_mfma_f32_16x16x32_bf16 v[28:31], v[182:185], v[198:201], v[28:31]
	v_mfma_f32_16x16x32_bf16 v[60:63], v[158:161], v[198:201], 0
	v_mfma_f32_16x16x32_bf16 v[60:63], v[150:153], v[194:197], v[60:63]
	v_mfma_f32_16x16x32_bf16 v[52:55], v[162:165], v[194:197], 0
	v_mfma_f32_16x16x32_bf16 v[52:55], v[166:169], v[198:201], v[52:55]
	v_mfma_f32_16x16x32_bf16 v[40:43], v[174:177], v[198:201], 0
	v_mfma_f32_16x16x32_bf16 v[40:43], v[170:173], v[194:197], v[40:43]
	v_mfma_f32_16x16x32_bf16 v[20:23], v[170:173], v[202:205], 0
	v_mfma_f32_16x16x32_bf16 v[20:23], v[174:177], v[206:209], v[20:23]
	v_mfma_f32_16x16x32_bf16 v[44:47], v[158:161], v[206:209], 0
	v_mfma_f32_16x16x32_bf16 v[44:47], v[150:153], v[202:205], v[44:47]
	v_mfma_f32_16x16x32_bf16 v[32:35], v[162:165], v[202:205], 0
	v_mfma_f32_16x16x32_bf16 v[32:35], v[166:169], v[206:209], v[32:35]
	v_mfma_f32_16x16x32_bf16 v[12:15], v[182:185], v[206:209], 0
	v_mfma_f32_16x16x32_bf16 v[12:15], v[178:181], v[202:205], v[12:15]
	v_mfma_f32_16x16x32_bf16 v[4:7], v[178:181], v[210:213], 0
	v_mfma_f32_16x16x32_bf16 v[4:7], v[182:185], v[214:217], v[4:7]
	v_mfma_f32_16x16x32_bf16 v[24:27], v[158:161], v[214:217], 0
	v_mfma_f32_16x16x32_bf16 v[24:27], v[150:153], v[210:213], v[24:27]
	v_mfma_f32_16x16x32_bf16 v[16:19], v[162:165], v[210:213], 0
	v_mfma_f32_16x16x32_bf16 v[16:19], v[166:169], v[214:217], v[16:19]
	v_mfma_f32_16x16x32_bf16 v[8:11], v[174:177], v[214:217], 0
	v_mfma_f32_16x16x32_bf16 v[8:11], v[170:173], v[210:213], v[8:11]
	s_setprio 0
	s_barrier
	s_add_i32 s68, 0, 0x18000
	v_add_u32_e32 v36, s68, v155
	s_add_i32 s69, 0, 0x1c000
	ds_read_b128 v[150:153], v36
	ds_read_b128 v[158:161], v36 offset:1024
	ds_read_b128 v[162:165], v36 offset:2048
	ds_read_b128 v[166:169], v36 offset:3072
	v_add_u32_e32 v36, s69, v155
	ds_read_b128 v[170:173], v36
	ds_read_b128 v[174:177], v36 offset:1024
	ds_read_b128 v[178:181], v36 offset:2048
	ds_read_b128 v[182:185], v36 offset:3072
	s_add_u32 s26, s26, 0x4000
	s_addc_u32 s27, s27, 0
	s_mov_b32 m0, s35
	ds_read_b128 v[186:189], v157 offset:32768
	ds_read_b128 v[190:193], v157 offset:33792
	ds_read_b128 v[194:197], v157 offset:34816
	ds_read_b128 v[198:201], v157 offset:35840
	ds_read_b128 v[202:205], v157 offset:36864
	ds_read_b128 v[206:209], v157 offset:37888
	ds_read_b128 v[210:213], v157 offset:38912
	ds_read_b128 v[214:217], v157 offset:39936
	global_load_lds_dwordx4 v142, s[26:27]
	s_mov_b32 m0, s36
	s_nop 0
	global_load_lds_dwordx4 v138, s[26:27]
	s_waitcnt vmcnt(8)
	s_waitcnt lgkmcnt(0)
	v_mfma_f32_16x16x32_bf16 v[132:135], v[150:153], v[186:189], v[132:135]
	v_mfma_f32_16x16x32_bf16 v[132:135], v[158:161], v[190:193], v[132:135]
	v_mfma_f32_16x16x32_bf16 v[128:131], v[166:169], v[190:193], v[128:131]
	v_mfma_f32_16x16x32_bf16 v[128:131], v[162:165], v[186:189], v[128:131]
	s_barrier
	s_setprio 1
	v_mfma_f32_16x16x32_bf16 v[120:123], v[170:173], v[186:189], v[120:123]
	v_mfma_f32_16x16x32_bf16 v[120:123], v[174:177], v[190:193], v[120:123]
	v_mfma_f32_16x16x32_bf16 v[112:115], v[182:185], v[190:193], v[112:115]
	v_mfma_f32_16x16x32_bf16 v[112:115], v[178:181], v[186:189], v[112:115]
	v_mfma_f32_16x16x32_bf16 v[96:99], v[178:181], v[194:197], v[96:99]
	v_mfma_f32_16x16x32_bf16 v[96:99], v[182:185], v[198:201], v[96:99]
	v_mfma_f32_16x16x32_bf16 v[124:127], v[158:161], v[198:201], v[124:127]
	v_mfma_f32_16x16x32_bf16 v[124:127], v[150:153], v[194:197], v[124:127]
	v_mfma_f32_16x16x32_bf16 v[116:119], v[162:165], v[194:197], v[116:119]
	v_mfma_f32_16x16x32_bf16 v[116:119], v[166:169], v[198:201], v[116:119]
	v_mfma_f32_16x16x32_bf16 v[104:107], v[174:177], v[198:201], v[104:107]
	v_mfma_f32_16x16x32_bf16 v[104:107], v[170:173], v[194:197], v[104:107]
	v_mfma_f32_16x16x32_bf16 v[88:91], v[170:173], v[202:205], v[88:91]
	v_mfma_f32_16x16x32_bf16 v[88:91], v[174:177], v[206:209], v[88:91]
	v_mfma_f32_16x16x32_bf16 v[108:111], v[158:161], v[206:209], v[108:111]
	v_mfma_f32_16x16x32_bf16 v[108:111], v[150:153], v[202:205], v[108:111]
	v_mfma_f32_16x16x32_bf16 v[100:103], v[162:165], v[202:205], v[100:103]
	v_mfma_f32_16x16x32_bf16 v[100:103], v[166:169], v[206:209], v[100:103]
	v_mfma_f32_16x16x32_bf16 v[80:83], v[182:185], v[206:209], v[80:83]
	v_mfma_f32_16x16x32_bf16 v[80:83], v[178:181], v[202:205], v[80:83]
	v_mfma_f32_16x16x32_bf16 v[72:75], v[178:181], v[210:213], v[72:75]
	v_mfma_f32_16x16x32_bf16 v[72:75], v[182:185], v[214:217], v[72:75]
	v_mfma_f32_16x16x32_bf16 v[92:95], v[158:161], v[214:217], v[92:95]
	v_mfma_f32_16x16x32_bf16 v[92:95], v[150:153], v[210:213], v[92:95]
	v_mfma_f32_16x16x32_bf16 v[84:87], v[162:165], v[210:213], v[84:87]
	v_mfma_f32_16x16x32_bf16 v[84:87], v[166:169], v[214:217], v[84:87]
	v_mfma_f32_16x16x32_bf16 v[76:79], v[174:177], v[214:217], v[76:79]
	v_mfma_f32_16x16x32_bf16 v[76:79], v[170:173], v[210:213], v[76:79]
	s_setprio 0
	s_barrier
; #define PG8_STAGE(bufoff, gbase, voff) do { _Pragma("unroll") for (int _i = 0; _i < 2; ++_i) \
;         __builtin_amdgcn_global_load_lds((const unsigned*)((const char*)(gbase) + (voff)[_i]), (PG8_LAS unsigned*)(lds + (bufoff) + ldsw + _i * 8192), 16, 0, 0); } while (0)
; #define PG8_LDA(dst, b, h) do { _Pragma("unroll") for (int m = 0; m < 4; ++m) _Pragma("unroll") for (int k = 0; k < 2; ++k) dst[m][k] = *(const PG8_LAS bf16x8*)(lds + PG8_SA(b, h) + aoff + m * 2048 + k * 1024); } while (0)
; #define PG8_LDB(dst, b, h) do { _Pragma("unroll") for (int n = 0; n < 2; ++n) _Pragma("unroll") for (int k = 0; k < 2; ++k) dst[n][k] = *(const PG8_LAS bf16x8*)(lds + PG8_SB(b, h) + boff + n * 2048 + k * 1024); } while (0)
; #define PG8_MMA(ai, bj, At, Bt) do { __builtin_amdgcn_s_setprio(1); _Pragma("unroll") for (int m = 0; m < 4; ++m) _Pragma("unroll") for (int n = 0; n < 2; ++n) _Pragma("unroll") for (int k = 0; k < 2; ++k) \
;         acc[ai][bj][m][n] = __builtin_amdgcn_mfma_f32_16x16x32_bf16(Bt[n][k], At[m][k], acc[ai][bj][m][n], 0, 0, 0); __builtin_amdgcn_s_setprio(0); } while (0)
; #define PG8_WAIT_V(n) asm volatile("s_waitcnt vmcnt(" #n ")" ::: "memory")
; template <class Epi, class Sched, bool ALIGN_EPI = false, bool SP2 = false, bool ABLK = false, bool BBLK = false>
; __device__ __forceinline__ void gemm_phase(PG8_LAS unsigned char* lds, const Gemm g, const Sched& S, const Epi& E) {
;     ...
;         for (int t = 0; t < nt; t += 2) {
;             const bool last = (t == nt - 2);
;             const char* a1 = cA + (size_t)(t + 1) * kstepA;
;             const char* a2 = last ? nA : cA + (size_t)(t + 2) * kstepA; const char* b2 = last ? nB : cB + (size_t)(t + 2) * kstepB;
;             const char* a3 = a2 + kstepA; const char* b3 = b2 + kstepB;
;             if (last && has_next) S.a_ready(nxt);
;             if constexpr (SP2) {
;             PG8_LDB(B0, 0, 0); PG8_LDB(B1, 0, 1); PG8_SCHED; PG8_LDA(At, 0, 0); PG8_STAGE(PG8_SA(1, 1), a1 + hstepA, voffA);
;             PG8_WAIT_V(8); PG8_WAIT_L(0); PG8_BAR; PG8_MMA(0, 0, At, B0); PG8_MMA(0, 1, At, B1); PG8_BAR; PG8_SCHED;
;     ...
;             PG8_LDA(At, 1, 1); PG8_STAGE(PG8_SB(1, 0), b3, voffB); PG8_STAGE(PG8_SB(1, 1), b3 + hstepB, voffB); PG8_STAGE(PG8_SA(1, 0), a3, voffA);
;             PG8_WAIT_V(8); PG8_WAIT_L(0); PG8_BAR; PG8_MMA(1, 0, At, B0); PG8_MMA(1, 1, At, B1); PG8_BAR; PG8_SCHED;
	s_add_u32 s26, s24, 0x8000
	s_addc_u32 s27, s25, 0
	s_add_i32 s68, s68, s29
	s_mov_b32 m0, s68
	ds_read_b128 v[186:189], v157 offset:49152
	ds_read_b128 v[190:193], v157 offset:50176
	ds_read_b128 v[194:197], v157 offset:51200
	ds_read_b128 v[198:201], v157 offset:52224
	ds_read_b128 v[202:205], v157 offset:53248
	ds_read_b128 v[206:209], v157 offset:54272
	ds_read_b128 v[210:213], v157 offset:55296
	ds_read_b128 v[214:217], v157 offset:56320
	global_load_lds_dwordx4 v140, s[26:27]
	s_add_i32 m0, s68, 0x2000
	s_add_u32 s24, s24, 0xc000
	s_addc_u32 s25, s25, 0
	global_load_lds_dwordx4 v136, s[26:27]
	s_add_i32 s26, s69, s29
	s_mov_b32 m0, s26
	s_nop 0
	global_load_lds_dwordx4 v140, s[24:25]
	s_add_i32 m0, s26, 0x2000
	s_nop 0
	global_load_lds_dwordx4 v136, s[24:25]
	s_mov_b32 m0, s37
	s_nop 0
	global_load_lds_dwordx4 v142, s[22:23]
	s_mov_b32 m0, s62
	s_nop 0
	global_load_lds_dwordx4 v138, s[22:23]
	s_waitcnt vmcnt(8)
	s_waitcnt lgkmcnt(0)
	v_mfma_f32_16x16x32_bf16 v[68:71], v[150:153], v[186:189], v[68:71]
	v_mfma_f32_16x16x32_bf16 v[68:71], v[158:161], v[190:193], v[68:71]
	v_mfma_f32_16x16x32_bf16 v[64:67], v[166:169], v[190:193], v[64:67]
	v_mfma_f32_16x16x32_bf16 v[64:67], v[162:165], v[186:189], v[64:67]
	s_barrier
	s_setprio 1
	v_mfma_f32_16x16x32_bf16 v[56:59], v[170:173], v[186:189], v[56:59]
	v_mfma_f32_16x16x32_bf16 v[56:59], v[174:177], v[190:193], v[56:59]
	v_mfma_f32_16x16x32_bf16 v[48:51], v[182:185], v[190:193], v[48:51]
	v_mfma_f32_16x16x32_bf16 v[48:51], v[178:181], v[186:189], v[48:51]
	v_mfma_f32_16x16x32_bf16 v[28:31], v[178:181], v[194:197], v[28:31]
	v_mfma_f32_16x16x32_bf16 v[28:31], v[182:185], v[198:201], v[28:31]
	v_mfma_f32_16x16x32_bf16 v[60:63], v[158:161], v[198:201], v[60:63]
	v_mfma_f32_16x16x32_bf16 v[60:63], v[150:153], v[194:197], v[60:63]
	v_mfma_f32_16x16x32_bf16 v[52:55], v[162:165], v[194:197], v[52:55]
	v_mfma_f32_16x16x32_bf16 v[52:55], v[166:169], v[198:201], v[52:55]
	v_mfma_f32_16x16x32_bf16 v[40:43], v[174:177], v[198:201], v[40:43]
	v_mfma_f32_16x16x32_bf16 v[40:43], v[170:173], v[194:197], v[40:43]
	v_mfma_f32_16x16x32_bf16 v[20:23], v[170:173], v[202:205], v[20:23]
	v_mfma_f32_16x16x32_bf16 v[20:23], v[174:177], v[206:209], v[20:23]
	v_mfma_f32_16x16x32_bf16 v[44:47], v[158:161], v[206:209], v[44:47]
	v_mfma_f32_16x16x32_bf16 v[44:47], v[150:153], v[202:205], v[44:47]
	v_mfma_f32_16x16x32_bf16 v[32:35], v[162:165], v[202:205], v[32:35]
	v_mfma_f32_16x16x32_bf16 v[32:35], v[166:169], v[206:209], v[32:35]
	v_mfma_f32_16x16x32_bf16 v[12:15], v[182:185], v[206:209], v[12:15]
	v_mfma_f32_16x16x32_bf16 v[12:15], v[178:181], v[202:205], v[12:15]
	v_mfma_f32_16x16x32_bf16 v[4:7], v[178:181], v[210:213], v[4:7]
	v_mfma_f32_16x16x32_bf16 v[4:7], v[182:185], v[214:217], v[4:7]
	v_mfma_f32_16x16x32_bf16 v[24:27], v[158:161], v[214:217], v[24:27]
	v_mfma_f32_16x16x32_bf16 v[24:27], v[150:153], v[210:213], v[24:27]
	v_mfma_f32_16x16x32_bf16 v[16:19], v[162:165], v[210:213], v[16:19]
	v_mfma_f32_16x16x32_bf16 v[16:19], v[166:169], v[214:217], v[16:19]
	v_mfma_f32_16x16x32_bf16 v[8:11], v[174:177], v[214:217], v[8:11]
	v_mfma_f32_16x16x32_bf16 v[8:11], v[170:173], v[210:213], v[8:11]
	s_setprio 0
	s_barrier
	s_add_i32 s13, s13, 2
	s_add_u32 s20, s20, 0x10000
	s_addc_u32 s21, s21, 0
	s_add_u32 s70, s70, 0x10000
	s_addc_u32 s71, s71, 0
	s_cmp_gt_u32 s13, 29
.LBB0_916:
	s_add_u32 s22, s20, 0x4000
	s_addc_u32 s23, s21, 0
	s_cmp_eq_u32 s13, 28
	s_cselect_b32 s26, s19, s22
	s_cselect_b32 s27, s1, s23
	s_cselect_b32 s24, s65, s70
	s_cselect_b32 s25, s9, s71
	s_add_u32 s22, s26, 0x8000
	s_addc_u32 s23, s27, 0
	s_add_i32 s68, 0, 0x10000
	v_add_u32_e32 v36, s68, v155
	s_add_i32 s77, 0, 0x14000
	ds_read_b128 v[150:153], v36
	ds_read_b128 v[158:161], v36 offset:1024
	ds_read_b128 v[162:165], v36 offset:2048
	ds_read_b128 v[166:169], v36 offset:3072
	v_add_u32_e32 v36, s77, v155
	ds_read_b128 v[170:173], v36
	ds_read_b128 v[174:177], v36 offset:1024
	ds_read_b128 v[178:181], v36 offset:2048
	ds_read_b128 v[182:185], v36 offset:3072
	s_add_i32 m0, s31, 0xc000
	ds_read_b128 v[186:189], v157
	ds_read_b128 v[190:193], v157 offset:1024
	ds_read_b128 v[194:197], v157 offset:2048
	ds_read_b128 v[198:201], v157 offset:3072
	ds_read_b128 v[202:205], v157 offset:4096
	ds_read_b128 v[206:209], v157 offset:5120
	ds_read_b128 v[210:213], v157 offset:6144
	ds_read_b128 v[214:217], v157 offset:7168
	global_load_lds_dwordx4 v146, s[20:21]
	s_add_i32 m0, s31, 0xe000
	s_nop 0
	global_load_lds_dwordx4 v148, s[20:21]
	s_waitcnt vmcnt(8)
	s_waitcnt lgkmcnt(0)
	v_mfma_f32_16x16x32_bf16 v[132:135], v[150:153], v[186:189], v[132:135]
	v_mfma_f32_16x16x32_bf16 v[132:135], v[158:161], v[190:193], v[132:135]
	v_mfma_f32_16x16x32_bf16 v[128:131], v[166:169], v[190:193], v[128:131]
	v_mfma_f32_16x16x32_bf16 v[128:131], v[162:165], v[186:189], v[128:131]
	s_barrier
; #define PG8_STAGE(bufoff, gbase, voff) do { _Pragma("unroll") for (int _i = 0; _i < 2; ++_i) \
;         __builtin_amdgcn_global_load_lds((const unsigned*)((const char*)(gbase) + (voff)[_i]), (PG8_LAS unsigned*)(lds + (bufoff) + ldsw + _i * 8192), 16, 0, 0); } while (0)
; #define PG8_LDA(dst, b, h) do { _Pragma("unroll") for (int m = 0; m < 4; ++m) _Pragma("unroll") for (int k = 0; k < 2; ++k) dst[m][k] = *(const PG8_LAS bf16x8*)(lds + PG8_SA(b, h) + aoff + m * 2048 + k * 1024); } while (0)
; #define PG8_LDB(dst, b, h) do { _Pragma("unroll") for (int n = 0; n < 2; ++n) _Pragma("unroll") for (int k = 0; k < 2; ++k) dst[n][k] = *(const PG8_LAS bf16x8*)(lds + PG8_SB(b, h) + boff + n * 2048 + k * 1024); } while (0)
; #define PG8_MMA(ai, bj, At, Bt) do { __builtin_amdgcn_s_setprio(1); _Pragma("unroll") for (int m = 0; m < 4; ++m) _Pragma("unroll") for (int n = 0; n < 2; ++n) _Pragma("unroll") for (int k = 0; k < 2; ++k) \
;         acc[ai][bj][m][n] = __builtin_amdgcn_mfma_f32_16x16x32_bf16(Bt[n][k], At[m][k], acc[ai][bj][m][n], 0, 0, 0); __builtin_amdgcn_s_setprio(0); } while (0)
; #define PG8_WAIT_V(n) asm volatile("s_waitcnt vmcnt(" #n ")" ::: "memory")
; #define PG8_WAIT_L(n) asm volatile("s_waitcnt lgkmcnt(" #n ")" ::: "memory")
; #define PG8_BAR __builtin_amdgcn_s_barrier()
; #define PG8_SCHED __builtin_amdgcn_sched_barrier(0)
; template <class Epi, class Sched, bool ALIGN_EPI = false, bool SP2 = false, bool ABLK = false, bool BBLK = false>
; __device__ __forceinline__ void gemm_phase(PG8_LAS unsigned char* lds, const Gemm g, const Sched& S, const Epi& E) {
;     ...
;             PG8_WAIT_V(8); PG8_WAIT_L(0); PG8_BAR; PG8_MMA(0, 0, At, B0); PG8_MMA(0, 1, At, B1); PG8_BAR; PG8_SCHED;
;             PG8_LDA(At, 0, 1); PG8_STAGE(PG8_SB(0, 0), b2, voffB); PG8_STAGE(PG8_SB(0, 1), b2 + hstepB, voffB); PG8_STAGE(PG8_SA(0, 0), a2, voffA);
;             PG8_WAIT_V(8); PG8_WAIT_L(0); PG8_BAR; PG8_MMA(1, 0, At, B0); PG8_MMA(1, 1, At, B1); PG8_BAR; PG8_SCHED;
;             PG8_LDB(B0, 1, 0); PG8_LDB(B1, 1, 1); PG8_SCHED; PG8_LDA(At, 1, 0); PG8_STAGE(PG8_SA(0, 1), a2 + hstepA, voffA);
;             PG8_WAIT_V(8); PG8_WAIT_L(0); PG8_BAR; PG8_MMA(0, 0, At, B0); PG8_MMA(0, 1, At, B1); PG8_BAR; PG8_SCHED;
	s_setprio 1
	v_mfma_f32_16x16x32_bf16 v[120:123], v[170:173], v[186:189], v[120:123]
	v_mfma_f32_16x16x32_bf16 v[120:123], v[174:177], v[190:193], v[120:123]
	v_mfma_f32_16x16x32_bf16 v[112:115], v[182:185], v[190:193], v[112:115]
	v_mfma_f32_16x16x32_bf16 v[112:115], v[178:181], v[186:189], v[112:115]
	v_mfma_f32_16x16x32_bf16 v[96:99], v[178:181], v[194:197], v[96:99]
	v_mfma_f32_16x16x32_bf16 v[96:99], v[182:185], v[198:201], v[96:99]
	v_mfma_f32_16x16x32_bf16 v[124:127], v[158:161], v[198:201], v[124:127]
	v_mfma_f32_16x16x32_bf16 v[124:127], v[150:153], v[194:197], v[124:127]
	v_mfma_f32_16x16x32_bf16 v[116:119], v[162:165], v[194:197], v[116:119]
	v_mfma_f32_16x16x32_bf16 v[116:119], v[166:169], v[198:201], v[116:119]
	v_mfma_f32_16x16x32_bf16 v[104:107], v[174:177], v[198:201], v[104:107]
	v_mfma_f32_16x16x32_bf16 v[104:107], v[170:173], v[194:197], v[104:107]
	v_mfma_f32_16x16x32_bf16 v[88:91], v[170:173], v[202:205], v[88:91]
	v_mfma_f32_16x16x32_bf16 v[88:91], v[174:177], v[206:209], v[88:91]
	v_mfma_f32_16x16x32_bf16 v[108:111], v[158:161], v[206:209], v[108:111]
	v_mfma_f32_16x16x32_bf16 v[108:111], v[150:153], v[202:205], v[108:111]
	v_mfma_f32_16x16x32_bf16 v[100:103], v[162:165], v[202:205], v[100:103]
	v_mfma_f32_16x16x32_bf16 v[100:103], v[166:169], v[206:209], v[100:103]
	v_mfma_f32_16x16x32_bf16 v[80:83], v[182:185], v[206:209], v[80:83]
	v_mfma_f32_16x16x32_bf16 v[80:83], v[178:181], v[202:205], v[80:83]
	v_mfma_f32_16x16x32_bf16 v[72:75], v[178:181], v[210:213], v[72:75]
	v_mfma_f32_16x16x32_bf16 v[72:75], v[182:185], v[214:217], v[72:75]
	v_mfma_f32_16x16x32_bf16 v[92:95], v[158:161], v[214:217], v[92:95]
	v_mfma_f32_16x16x32_bf16 v[92:95], v[150:153], v[210:213], v[92:95]
	v_mfma_f32_16x16x32_bf16 v[84:87], v[162:165], v[210:213], v[84:87]
	v_mfma_f32_16x16x32_bf16 v[84:87], v[166:169], v[214:217], v[84:87]
	v_mfma_f32_16x16x32_bf16 v[76:79], v[174:177], v[214:217], v[76:79]
	v_mfma_f32_16x16x32_bf16 v[76:79], v[170:173], v[210:213], v[76:79]
	s_setprio 0
	s_barrier
	s_add_i32 s68, s68, s29
	s_mov_b32 m0, s68
	ds_read_b128 v[186:189], v157 offset:16384
	ds_read_b128 v[190:193], v157 offset:17408
	ds_read_b128 v[194:197], v157 offset:18432
	ds_read_b128 v[198:201], v157 offset:19456
	ds_read_b128 v[202:205], v157 offset:20480
	ds_read_b128 v[206:209], v157 offset:21504
	ds_read_b128 v[210:213], v157 offset:22528
	ds_read_b128 v[214:217], v157 offset:23552
	global_load_lds_dwordx4 v140, s[24:25]
	s_add_i32 m0, s68, 0x2000
	s_add_u32 s68, s24, 0x4000
	s_addc_u32 s69, s25, 0
	s_add_i32 s77, s77, s29
	global_load_lds_dwordx4 v136, s[24:25]
	s_mov_b32 m0, s77
	s_nop 0
	global_load_lds_dwordx4 v140, s[68:69]
	s_add_i32 m0, s77, 0x2000
	s_nop 0
	global_load_lds_dwordx4 v136, s[68:69]
	s_mov_b32 m0, s31
	s_nop 0
	global_load_lds_dwordx4 v142, s[26:27]
	s_mov_b32 m0, s34
	s_nop 0
	global_load_lds_dwordx4 v138, s[26:27]
	s_waitcnt vmcnt(8)
	s_waitcnt lgkmcnt(0)
	v_mfma_f32_16x16x32_bf16 v[68:71], v[150:153], v[186:189], v[68:71]
	v_mfma_f32_16x16x32_bf16 v[68:71], v[158:161], v[190:193], v[68:71]
	v_mfma_f32_16x16x32_bf16 v[64:67], v[166:169], v[190:193], v[64:67]
	v_mfma_f32_16x16x32_bf16 v[64:67], v[162:165], v[186:189], v[64:67]
	s_barrier
	s_setprio 1
	v_mfma_f32_16x16x32_bf16 v[56:59], v[170:173], v[186:189], v[56:59]
	v_mfma_f32_16x16x32_bf16 v[56:59], v[174:177], v[190:193], v[56:59]
	v_mfma_f32_16x16x32_bf16 v[48:51], v[182:185], v[190:193], v[48:51]
	v_mfma_f32_16x16x32_bf16 v[48:51], v[178:181], v[186:189], v[48:51]
	v_mfma_f32_16x16x32_bf16 v[28:31], v[178:181], v[194:197], v[28:31]
	v_mfma_f32_16x16x32_bf16 v[28:31], v[182:185], v[198:201], v[28:31]
	v_mfma_f32_16x16x32_bf16 v[60:63], v[158:161], v[198:201], v[60:63]
	v_mfma_f32_16x16x32_bf16 v[60:63], v[150:153], v[194:197], v[60:63]
	v_mfma_f32_16x16x32_bf16 v[52:55], v[162:165], v[194:197], v[52:55]
	v_mfma_f32_16x16x32_bf16 v[52:55], v[166:169], v[198:201], v[52:55]
	v_mfma_f32_16x16x32_bf16 v[40:43], v[174:177], v[198:201], v[40:43]
	v_mfma_f32_16x16x32_bf16 v[40:43], v[170:173], v[194:197], v[40:43]
	v_mfma_f32_16x16x32_bf16 v[20:23], v[170:173], v[202:205], v[20:23]
	v_mfma_f32_16x16x32_bf16 v[20:23], v[174:177], v[206:209], v[20:23]
	v_mfma_f32_16x16x32_bf16 v[44:47], v[158:161], v[206:209], v[44:47]
	v_mfma_f32_16x16x32_bf16 v[44:47], v[150:153], v[202:205], v[44:47]
	v_mfma_f32_16x16x32_bf16 v[32:35], v[162:165], v[202:205], v[32:35]
	v_mfma_f32_16x16x32_bf16 v[32:35], v[166:169], v[206:209], v[32:35]
	v_mfma_f32_16x16x32_bf16 v[12:15], v[182:185], v[206:209], v[12:15]
	v_mfma_f32_16x16x32_bf16 v[12:15], v[178:181], v[202:205], v[12:15]
	v_mfma_f32_16x16x32_bf16 v[4:7], v[178:181], v[210:213], v[4:7]
	v_mfma_f32_16x16x32_bf16 v[4:7], v[182:185], v[214:217], v[4:7]
	v_mfma_f32_16x16x32_bf16 v[24:27], v[158:161], v[214:217], v[24:27]
	v_mfma_f32_16x16x32_bf16 v[24:27], v[150:153], v[210:213], v[24:27]
	v_mfma_f32_16x16x32_bf16 v[16:19], v[162:165], v[210:213], v[16:19]
	v_mfma_f32_16x16x32_bf16 v[16:19], v[166:169], v[214:217], v[16:19]
	v_mfma_f32_16x16x32_bf16 v[8:11], v[174:177], v[214:217], v[8:11]
	v_mfma_f32_16x16x32_bf16 v[8:11], v[170:173], v[210:213], v[8:11]
	s_setprio 0
	s_barrier
; #define PG8_STAGE(bufoff, gbase, voff) do { _Pragma("unroll") for (int _i = 0; _i < 2; ++_i) \
;         __builtin_amdgcn_global_load_lds((const unsigned*)((const char*)(gbase) + (voff)[_i]), (PG8_LAS unsigned*)(lds + (bufoff) + ldsw + _i * 8192), 16, 0, 0); } while (0)
; #define PG8_LDA(dst, b, h) do { _Pragma("unroll") for (int m = 0; m < 4; ++m) _Pragma("unroll") for (int k = 0; k < 2; ++k) dst[m][k] = *(const PG8_LAS bf16x8*)(lds + PG8_SA(b, h) + aoff + m * 2048 + k * 1024); } while (0)
; #define PG8_LDB(dst, b, h) do { _Pragma("unroll") for (int n = 0; n < 2; ++n) _Pragma("unroll") for (int k = 0; k < 2; ++k) dst[n][k] = *(const PG8_LAS bf16x8*)(lds + PG8_SB(b, h) + boff + n * 2048 + k * 1024); } while (0)
; #define PG8_MMA(ai, bj, At, Bt) do { __builtin_amdgcn_s_setprio(1); _Pragma("unroll") for (int m = 0; m < 4; ++m) _Pragma("unroll") for (int n = 0; n < 2; ++n) _Pragma("unroll") for (int k = 0; k < 2; ++k) \
;         acc[ai][bj][m][n] = __builtin_amdgcn_mfma_f32_16x16x32_bf16(Bt[n][k], At[m][k], acc[ai][bj][m][n], 0, 0, 0); __builtin_amdgcn_s_setprio(0); } while (0)
; #define PG8_WAIT_V(n) asm volatile("s_waitcnt vmcnt(" #n ")" ::: "memory")
; #define PG8_WAIT_L(n) asm volatile("s_waitcnt lgkmcnt(" #n ")" ::: "memory")
; #define PG8_BAR __builtin_amdgcn_s_barrier()
; #define PG8_SCHED __builtin_amdgcn_sched_barrier(0)
; template <class Epi, class Sched, bool ALIGN_EPI = false, bool SP2 = false, bool ABLK = false, bool BBLK = false>
; __device__ __forceinline__ void gemm_phase(PG8_LAS unsigned char* lds, const Gemm g, const Sched& S, const Epi& E) {
;     ...
;             PG8_LDB(B0, 1, 0); PG8_LDB(B1, 1, 1); PG8_SCHED; PG8_LDA(At, 1, 0); PG8_STAGE(PG8_SA(0, 1), a2 + hstepA, voffA);
;             PG8_WAIT_V(8); PG8_WAIT_L(0); PG8_BAR; PG8_MMA(0, 0, At, B0); PG8_MMA(0, 1, At, B1); PG8_BAR; PG8_SCHED;
;             PG8_LDA(At, 1, 1); PG8_STAGE(PG8_SB(1, 0), b3, voffB); PG8_STAGE(PG8_SB(1, 1), b3 + hstepB, voffB); PG8_STAGE(PG8_SA(1, 0), a3, voffA);
;             PG8_WAIT_V(8); PG8_WAIT_L(0); PG8_BAR; PG8_MMA(1, 0, At, B0); PG8_MMA(1, 1, At, B1); PG8_BAR; PG8_SCHED;
	s_add_i32 s68, 0, 0x18000
	v_add_u32_e32 v36, s68, v155
	s_add_i32 s69, 0, 0x1c000
	ds_read_b128 v[150:153], v36
	ds_read_b128 v[158:161], v36 offset:1024
	ds_read_b128 v[162:165], v36 offset:2048
	ds_read_b128 v[166:169], v36 offset:3072
	v_add_u32_e32 v36, s69, v155
	ds_read_b128 v[170:173], v36
	ds_read_b128 v[174:177], v36 offset:1024
	ds_read_b128 v[178:181], v36 offset:2048
	ds_read_b128 v[182:185], v36 offset:3072
	s_add_u32 s26, s26, 0x4000
	s_addc_u32 s27, s27, 0
	s_mov_b32 m0, s35
	ds_read_b128 v[186:189], v157 offset:32768
	ds_read_b128 v[190:193], v157 offset:33792
	ds_read_b128 v[194:197], v157 offset:34816
	ds_read_b128 v[198:201], v157 offset:35840
	ds_read_b128 v[202:205], v157 offset:36864
	ds_read_b128 v[206:209], v157 offset:37888
	ds_read_b128 v[210:213], v157 offset:38912
	ds_read_b128 v[214:217], v157 offset:39936
	global_load_lds_dwordx4 v142, s[26:27]
	s_mov_b32 m0, s36
	s_nop 0
	global_load_lds_dwordx4 v138, s[26:27]
	s_waitcnt vmcnt(8)
	s_waitcnt lgkmcnt(0)
	v_mfma_f32_16x16x32_bf16 v[132:135], v[150:153], v[186:189], v[132:135]
	v_mfma_f32_16x16x32_bf16 v[132:135], v[158:161], v[190:193], v[132:135]
	v_mfma_f32_16x16x32_bf16 v[128:131], v[166:169], v[190:193], v[128:131]
	v_mfma_f32_16x16x32_bf16 v[128:131], v[162:165], v[186:189], v[128:131]
	s_barrier
	s_setprio 1
	v_mfma_f32_16x16x32_bf16 v[120:123], v[170:173], v[186:189], v[120:123]
	v_mfma_f32_16x16x32_bf16 v[120:123], v[174:177], v[190:193], v[120:123]
	v_mfma_f32_16x16x32_bf16 v[112:115], v[182:185], v[190:193], v[112:115]
	v_mfma_f32_16x16x32_bf16 v[112:115], v[178:181], v[186:189], v[112:115]
	v_mfma_f32_16x16x32_bf16 v[96:99], v[178:181], v[194:197], v[96:99]
	v_mfma_f32_16x16x32_bf16 v[96:99], v[182:185], v[198:201], v[96:99]
	v_mfma_f32_16x16x32_bf16 v[124:127], v[158:161], v[198:201], v[124:127]
	v_mfma_f32_16x16x32_bf16 v[124:127], v[150:153], v[194:197], v[124:127]
	v_mfma_f32_16x16x32_bf16 v[116:119], v[162:165], v[194:197], v[116:119]
	v_mfma_f32_16x16x32_bf16 v[116:119], v[166:169], v[198:201], v[116:119]
	v_mfma_f32_16x16x32_bf16 v[104:107], v[174:177], v[198:201], v[104:107]
	v_mfma_f32_16x16x32_bf16 v[104:107], v[170:173], v[194:197], v[104:107]
	v_mfma_f32_16x16x32_bf16 v[88:91], v[170:173], v[202:205], v[88:91]
	v_mfma_f32_16x16x32_bf16 v[88:91], v[174:177], v[206:209], v[88:91]
	v_mfma_f32_16x16x32_bf16 v[108:111], v[158:161], v[206:209], v[108:111]
	v_mfma_f32_16x16x32_bf16 v[108:111], v[150:153], v[202:205], v[108:111]
	v_mfma_f32_16x16x32_bf16 v[100:103], v[162:165], v[202:205], v[100:103]
	v_mfma_f32_16x16x32_bf16 v[100:103], v[166:169], v[206:209], v[100:103]
	v_mfma_f32_16x16x32_bf16 v[80:83], v[182:185], v[206:209], v[80:83]
	v_mfma_f32_16x16x32_bf16 v[80:83], v[178:181], v[202:205], v[80:83]
	v_mfma_f32_16x16x32_bf16 v[72:75], v[178:181], v[210:213], v[72:75]
	v_mfma_f32_16x16x32_bf16 v[72:75], v[182:185], v[214:217], v[72:75]
	v_mfma_f32_16x16x32_bf16 v[92:95], v[158:161], v[214:217], v[92:95]
	v_mfma_f32_16x16x32_bf16 v[92:95], v[150:153], v[210:213], v[92:95]
	v_mfma_f32_16x16x32_bf16 v[84:87], v[162:165], v[210:213], v[84:87]
	v_mfma_f32_16x16x32_bf16 v[84:87], v[166:169], v[214:217], v[84:87]
	v_mfma_f32_16x16x32_bf16 v[76:79], v[174:177], v[214:217], v[76:79]
	v_mfma_f32_16x16x32_bf16 v[76:79], v[170:173], v[210:213], v[76:79]
	s_setprio 0
	s_barrier
	s_add_u32 s26, s24, 0x8000
	s_addc_u32 s27, s25, 0
	s_add_i32 s68, s68, s29
	s_mov_b32 m0, s68
	ds_read_b128 v[186:189], v157 offset:49152
	ds_read_b128 v[190:193], v157 offset:50176
	ds_read_b128 v[194:197], v157 offset:51200
	ds_read_b128 v[198:201], v157 offset:52224
	ds_read_b128 v[202:205], v157 offset:53248
	ds_read_b128 v[206:209], v157 offset:54272
	ds_read_b128 v[210:213], v157 offset:55296
	ds_read_b128 v[214:217], v157 offset:56320
	global_load_lds_dwordx4 v140, s[26:27]
	s_add_i32 m0, s68, 0x2000
	s_add_u32 s24, s24, 0xc000
	s_addc_u32 s25, s25, 0
	global_load_lds_dwordx4 v136, s[26:27]
	s_add_i32 s26, s69, s29
	s_mov_b32 m0, s26
	s_nop 0
	global_load_lds_dwordx4 v140, s[24:25]
	s_add_i32 m0, s26, 0x2000
	s_nop 0
	global_load_lds_dwordx4 v136, s[24:25]
	s_mov_b32 m0, s37
	s_nop 0
	global_load_lds_dwordx4 v142, s[22:23]
	s_mov_b32 m0, s62
	s_nop 0
	global_load_lds_dwordx4 v138, s[22:23]
	s_waitcnt vmcnt(8)
	s_waitcnt lgkmcnt(0)
	v_mfma_f32_16x16x32_bf16 v[68:71], v[150:153], v[186:189], v[68:71]
	v_mfma_f32_16x16x32_bf16 v[68:71], v[158:161], v[190:193], v[68:71]
	v_mfma_f32_16x16x32_bf16 v[64:67], v[166:169], v[190:193], v[64:67]
	v_mfma_f32_16x16x32_bf16 v[64:67], v[162:165], v[186:189], v[64:67]
	s_barrier
	s_setprio 1
	v_mfma_f32_16x16x32_bf16 v[56:59], v[170:173], v[186:189], v[56:59]
	v_mfma_f32_16x16x32_bf16 v[56:59], v[174:177], v[190:193], v[56:59]
	v_mfma_f32_16x16x32_bf16 v[48:51], v[182:185], v[190:193], v[48:51]
	v_mfma_f32_16x16x32_bf16 v[48:51], v[178:181], v[186:189], v[48:51]
	v_mfma_f32_16x16x32_bf16 v[28:31], v[178:181], v[194:197], v[28:31]
	v_mfma_f32_16x16x32_bf16 v[28:31], v[182:185], v[198:201], v[28:31]
	v_mfma_f32_16x16x32_bf16 v[60:63], v[158:161], v[198:201], v[60:63]
	v_mfma_f32_16x16x32_bf16 v[60:63], v[150:153], v[194:197], v[60:63]
	v_mfma_f32_16x16x32_bf16 v[52:55], v[162:165], v[194:197], v[52:55]
	v_mfma_f32_16x16x32_bf16 v[52:55], v[166:169], v[198:201], v[52:55]
	v_mfma_f32_16x16x32_bf16 v[40:43], v[174:177], v[198:201], v[40:43]
	v_mfma_f32_16x16x32_bf16 v[40:43], v[170:173], v[194:197], v[40:43]
	v_mfma_f32_16x16x32_bf16 v[20:23], v[170:173], v[202:205], v[20:23]
	v_mfma_f32_16x16x32_bf16 v[20:23], v[174:177], v[206:209], v[20:23]
	v_mfma_f32_16x16x32_bf16 v[44:47], v[158:161], v[206:209], v[44:47]
	v_mfma_f32_16x16x32_bf16 v[44:47], v[150:153], v[202:205], v[44:47]
	v_mfma_f32_16x16x32_bf16 v[32:35], v[162:165], v[202:205], v[32:35]
	v_mfma_f32_16x16x32_bf16 v[32:35], v[166:169], v[206:209], v[32:35]
	v_mfma_f32_16x16x32_bf16 v[12:15], v[182:185], v[206:209], v[12:15]
	v_mfma_f32_16x16x32_bf16 v[12:15], v[178:181], v[202:205], v[12:15]
	v_mfma_f32_16x16x32_bf16 v[4:7], v[178:181], v[210:213], v[4:7]
	v_mfma_f32_16x16x32_bf16 v[4:7], v[182:185], v[214:217], v[4:7]
	v_mfma_f32_16x16x32_bf16 v[24:27], v[158:161], v[214:217], v[24:27]
	v_mfma_f32_16x16x32_bf16 v[24:27], v[150:153], v[210:213], v[24:27]
	v_mfma_f32_16x16x32_bf16 v[16:19], v[162:165], v[210:213], v[16:19]
	v_mfma_f32_16x16x32_bf16 v[16:19], v[166:169], v[214:217], v[16:19]
	v_mfma_f32_16x16x32_bf16 v[8:11], v[174:177], v[214:217], v[8:11]
	v_mfma_f32_16x16x32_bf16 v[8:11], v[170:173], v[210:213], v[8:11]
	s_setprio 0
	s_barrier
	s_add_i32 s13, s13, 2
	s_add_u32 s20, s20, 0x10000
	s_addc_u32 s21, s21, 0
	s_add_u32 s70, s70, 0x10000
	s_addc_u32 s71, s71, 0
	s_cmp_gt_u32 s13, 29
	s_cbranch_scc0 .LBB0_916
	s_and_b64 vcc, exec, s[6:7]
	s_cbranch_vccz .LBB0_919
	s_barrier

; #define PG8_STAGE(bufoff, gbase, voff) do { _Pragma("unroll") for (int _i = 0; _i < 2; ++_i) \
;         __builtin_amdgcn_global_load_lds((const unsigned*)((const char*)(gbase) + (voff)[_i]), (PG8_LAS unsigned*)(lds + (bufoff) + ldsw + _i * 8192), 16, 0, 0); } while (0)
; #define PG8_LDA(dst, b, h) do { _Pragma("unroll") for (int m = 0; m < 4; ++m) _Pragma("unroll") for (int k = 0; k < 2; ++k) dst[m][k] = *(const PG8_LAS bf16x8*)(lds + PG8_SA(b, h) + aoff + m * 2048 + k * 1024); } while (0)
; #define PG8_LDB(dst, b, h) do { _Pragma("unroll") for (int n = 0; n < 2; ++n) _Pragma("unroll") for (int k = 0; k < 2; ++k) dst[n][k] = *(const PG8_LAS bf16x8*)(lds + PG8_SB(b, h) + boff + n * 2048 + k * 1024); } while (0)
; #define PG8_MMA(ai, bj, At, Bt) do { __builtin_amdgcn_s_setprio(1); _Pragma("unroll") for (int m = 0; m < 4; ++m) _Pragma("unroll") for (int n = 0; n < 2; ++n) _Pragma("unroll") for (int k = 0; k < 2; ++k) \
;         acc[ai][bj][m][n] = __builtin_amdgcn_mfma_f32_16x16x32_bf16(Bt[n][k], At[m][k], acc[ai][bj][m][n], 0, 0, 0); __builtin_amdgcn_s_setprio(0); } while (0)
; #define PG8_WAIT_V(n) asm volatile("s_waitcnt vmcnt(" #n ")" ::: "memory")
; template <class Epi, class Sched, bool ALIGN_EPI = false, bool SP2 = false, bool ABLK = false, bool BBLK = false>
; __device__ __forceinline__ void gemm_phase(PG8_LAS unsigned char* lds, const Gemm g, const Sched& S, const Epi& E) {
;     ...
;         for (int t = 0; t < nt; t += 2) {
;             const bool last = (t == nt - 2);
;             const char* a1 = cA + (size_t)(t + 1) * kstepA;
;             const char* a2 = last ? nA : cA + (size_t)(t + 2) * kstepA; const char* b2 = last ? nB : cB + (size_t)(t + 2) * kstepB;
;             const char* a3 = a2 + kstepA; const char* b3 = b2 + kstepB;
;             if (last && has_next) S.a_ready(nxt);
;             if constexpr (SP2) {
;             PG8_LDB(B0, 0, 0); PG8_LDB(B1, 0, 1); PG8_SCHED; PG8_LDA(At, 0, 0); PG8_STAGE(PG8_SA(1, 1), a1 + hstepA, voffA);
;             PG8_WAIT_V(8); PG8_WAIT_L(0); PG8_BAR; PG8_MMA(0, 0, At, B0); PG8_MMA(0, 1, At, B1); PG8_BAR; PG8_SCHED;
;             PG8_LDA(At, 0, 1); PG8_STAGE(PG8_SB(0, 0), b2, voffB); PG8_STAGE(PG8_SB(0, 1), b2 + hstepB, voffB); PG8_STAGE(PG8_SA(0, 0), a2, voffA);
;             PG8_WAIT_V(8); PG8_WAIT_L(0); PG8_BAR; PG8_MMA(1, 0, At, B0); PG8_MMA(1, 1, At, B1); PG8_BAR; PG8_SCHED;
.LBB0_2110:
	s_ashr_i32 s17, s16, 31
	s_lshl_b64 s[12:13], s[16:17], 20
	s_add_u32 s18, s72, s12
	s_addc_u32 s19, s73, s13
	s_and_b64 s[12:13], s[4:5], exec
	s_cselect_b32 s12, s19, s23
	s_cselect_b32 s17, s18, s22
	s_ashr_i32 s11, s10, 31
	s_lshl_b64 s[20:21], s[10:11], 20
	v_readlane_b32 s26, v254, 3
	v_readlane_b32 s27, v254, 4
	s_add_u32 s20, s26, s20
	s_addc_u32 s21, s27, s21
	s_and_b64 s[26:27], s[4:5], exec
	s_cselect_b32 s11, s21, s25
	s_cselect_b32 s77, s20, s24
	s_add_u32 s22, s22, 0xc000
	s_addc_u32 s23, s23, 0
	s_add_u32 s82, s24, 0x10000
	s_addc_u32 vcc_lo, s25, 0
	s_mov_b32 s13, -2
	s_add_u32 s24, s22, 0x4000
	s_addc_u32 s25, s23, 0
	s_cmp_eq_u32 s13, 28
	s_cselect_b32 s28, s17, s24
	s_cselect_b32 s29, s12, s25
	s_cselect_b32 s26, s77, s82
	s_cselect_b32 s27, s11, vcc_lo
	s_add_u32 s24, s28, 0x8000
	s_addc_u32 s25, s29, 0
	s_add_i32 s68, 0, 0x10000
	v_add_u32_e32 v151, s68, v148
	s_add_i32 s88, 0, 0x14000
	ds_read_b128 v[36:39], v151
	ds_read_b128 v[152:155], v151 offset:1024
	ds_read_b128 v[156:159], v151 offset:2048
	ds_read_b128 v[160:163], v151 offset:3072
	v_add_u32_e32 v151, s88, v148
	ds_read_b128 v[164:167], v151
	ds_read_b128 v[168:171], v151 offset:1024
	ds_read_b128 v[172:175], v151 offset:2048
	ds_read_b128 v[176:179], v151 offset:3072
	s_add_i32 m0, s9, 0xc000
	ds_read_b128 v[180:183], v150
	ds_read_b128 v[184:187], v150 offset:1024
	ds_read_b128 v[188:191], v150 offset:2048
	ds_read_b128 v[192:195], v150 offset:3072
	ds_read_b128 v[196:199], v150 offset:4096
	ds_read_b128 v[200:203], v150 offset:5120
	ds_read_b128 v[204:207], v150 offset:6144
	ds_read_b128 v[208:211], v150 offset:7168
	global_load_lds_dwordx4 v144, s[22:23]
	s_add_i32 m0, s9, 0xe000
	s_nop 0
	global_load_lds_dwordx4 v146, s[22:23]
	s_waitcnt vmcnt(8)
	s_waitcnt lgkmcnt(0)
	v_mfma_f32_16x16x32_bf16 v[132:135], v[36:39], v[180:183], 0
	v_mfma_f32_16x16x32_bf16 v[132:135], v[152:155], v[184:187], v[132:135]
	v_mfma_f32_16x16x32_bf16 v[128:131], v[160:163], v[184:187], 0
	v_mfma_f32_16x16x32_bf16 v[128:131], v[156:159], v[180:183], v[128:131]
	s_barrier
	s_setprio 1
	v_mfma_f32_16x16x32_bf16 v[116:119], v[164:167], v[180:183], 0
	v_mfma_f32_16x16x32_bf16 v[116:119], v[168:171], v[184:187], v[116:119]
	v_mfma_f32_16x16x32_bf16 v[112:115], v[176:179], v[184:187], 0
	v_mfma_f32_16x16x32_bf16 v[112:115], v[172:175], v[180:183], v[112:115]
	v_mfma_f32_16x16x32_bf16 v[96:99], v[172:175], v[188:191], 0
	v_mfma_f32_16x16x32_bf16 v[96:99], v[176:179], v[192:195], v[96:99]
	v_mfma_f32_16x16x32_bf16 v[124:127], v[152:155], v[192:195], 0
	v_mfma_f32_16x16x32_bf16 v[124:127], v[36:39], v[188:191], v[124:127]
	v_mfma_f32_16x16x32_bf16 v[120:123], v[156:159], v[188:191], 0
	v_mfma_f32_16x16x32_bf16 v[120:123], v[160:163], v[192:195], v[120:123]
	v_mfma_f32_16x16x32_bf16 v[100:103], v[168:171], v[192:195], 0
	v_mfma_f32_16x16x32_bf16 v[100:103], v[164:167], v[188:191], v[100:103]
	v_mfma_f32_16x16x32_bf16 v[84:87], v[164:167], v[196:199], 0
	v_mfma_f32_16x16x32_bf16 v[84:87], v[168:171], v[200:203], v[84:87]
	v_mfma_f32_16x16x32_bf16 v[108:111], v[152:155], v[200:203], 0
	v_mfma_f32_16x16x32_bf16 v[108:111], v[36:39], v[196:199], v[108:111]
	v_mfma_f32_16x16x32_bf16 v[104:107], v[156:159], v[196:199], 0
	v_mfma_f32_16x16x32_bf16 v[104:107], v[160:163], v[200:203], v[104:107]
	v_mfma_f32_16x16x32_bf16 v[80:83], v[176:179], v[200:203], 0
	v_mfma_f32_16x16x32_bf16 v[80:83], v[172:175], v[196:199], v[80:83]
	v_mfma_f32_16x16x32_bf16 v[72:75], v[172:175], v[204:207], 0
	v_mfma_f32_16x16x32_bf16 v[72:75], v[176:179], v[208:211], v[72:75]
	v_mfma_f32_16x16x32_bf16 v[92:95], v[152:155], v[208:211], 0
	v_mfma_f32_16x16x32_bf16 v[92:95], v[36:39], v[204:207], v[92:95]
	v_mfma_f32_16x16x32_bf16 v[88:91], v[156:159], v[204:207], 0
	v_mfma_f32_16x16x32_bf16 v[88:91], v[160:163], v[208:211], v[88:91]
	v_mfma_f32_16x16x32_bf16 v[76:79], v[168:171], v[208:211], 0
	v_mfma_f32_16x16x32_bf16 v[76:79], v[164:167], v[204:207], v[76:79]
	s_setprio 0
	s_barrier
	s_add_i32 s68, s68, s34
	s_mov_b32 m0, s68
	ds_read_b128 v[180:183], v150 offset:16384
	ds_read_b128 v[184:187], v150 offset:17408
	ds_read_b128 v[188:191], v150 offset:18432
	ds_read_b128 v[192:195], v150 offset:19456
	ds_read_b128 v[196:199], v150 offset:20480
	ds_read_b128 v[200:203], v150 offset:21504
	ds_read_b128 v[204:207], v150 offset:22528
	ds_read_b128 v[208:211], v150 offset:23552
	global_load_lds_dwordx4 v138, s[26:27]
	s_add_i32 m0, s68, 0x2000
	s_add_u32 s68, s26, 0x4000
	s_addc_u32 s69, s27, 0
	s_add_i32 s88, s88, s34
	global_load_lds_dwordx4 v142, s[26:27]
	s_mov_b32 m0, s88
	s_nop 0
	global_load_lds_dwordx4 v138, s[68:69]
	s_add_i32 m0, s88, 0x2000
	s_nop 0
	global_load_lds_dwordx4 v142, s[68:69]
	s_mov_b32 m0, s9
	s_nop 0
	global_load_lds_dwordx4 v136, s[28:29]
	s_mov_b32 m0, s35
	s_nop 0
	global_load_lds_dwordx4 v140, s[28:29]
	s_waitcnt vmcnt(8)
	s_waitcnt lgkmcnt(0)
	v_mfma_f32_16x16x32_bf16 v[68:71], v[36:39], v[180:183], 0
	v_mfma_f32_16x16x32_bf16 v[68:71], v[152:155], v[184:187], v[68:71]
	v_mfma_f32_16x16x32_bf16 v[64:67], v[160:163], v[184:187], 0
	v_mfma_f32_16x16x32_bf16 v[64:67], v[156:159], v[180:183], v[64:67]
	s_barrier
; #define PG8_STAGE(bufoff, gbase, voff) do { _Pragma("unroll") for (int _i = 0; _i < 2; ++_i) \
;         __builtin_amdgcn_global_load_lds((const unsigned*)((const char*)(gbase) + (voff)[_i]), (PG8_LAS unsigned*)(lds + (bufoff) + ldsw + _i * 8192), 16, 0, 0); } while (0)
; #define PG8_LDA(dst, b, h) do { _Pragma("unroll") for (int m = 0; m < 4; ++m) _Pragma("unroll") for (int k = 0; k < 2; ++k) dst[m][k] = *(const PG8_LAS bf16x8*)(lds + PG8_SA(b, h) + aoff + m * 2048 + k * 1024); } while (0)
; #define PG8_LDB(dst, b, h) do { _Pragma("unroll") for (int n = 0; n < 2; ++n) _Pragma("unroll") for (int k = 0; k < 2; ++k) dst[n][k] = *(const PG8_LAS bf16x8*)(lds + PG8_SB(b, h) + boff + n * 2048 + k * 1024); } while (0)
; #define PG8_MMA(ai, bj, At, Bt) do { __builtin_amdgcn_s_setprio(1); _Pragma("unroll") for (int m = 0; m < 4; ++m) _Pragma("unroll") for (int n = 0; n < 2; ++n) _Pragma("unroll") for (int k = 0; k < 2; ++k) \
;         acc[ai][bj][m][n] = __builtin_amdgcn_mfma_f32_16x16x32_bf16(Bt[n][k], At[m][k], acc[ai][bj][m][n], 0, 0, 0); __builtin_amdgcn_s_setprio(0); } while (0)
; #define PG8_WAIT_V(n) asm volatile("s_waitcnt vmcnt(" #n ")" ::: "memory")
; #define PG8_WAIT_L(n) asm volatile("s_waitcnt lgkmcnt(" #n ")" ::: "memory")
; #define PG8_BAR __builtin_amdgcn_s_barrier()
; #define PG8_SCHED __builtin_amdgcn_sched_barrier(0)
; template <class Epi, class Sched, bool ALIGN_EPI = false, bool SP2 = false, bool ABLK = false, bool BBLK = false>
; __device__ __forceinline__ void gemm_phase(PG8_LAS unsigned char* lds, const Gemm g, const Sched& S, const Epi& E) {
;     ...
;             PG8_WAIT_V(8); PG8_WAIT_L(0); PG8_BAR; PG8_MMA(0, 0, At, B0); PG8_MMA(0, 1, At, B1); PG8_BAR; PG8_SCHED;
;             PG8_LDA(At, 0, 1); PG8_STAGE(PG8_SB(0, 0), b2, voffB); PG8_STAGE(PG8_SB(0, 1), b2 + hstepB, voffB); PG8_STAGE(PG8_SA(0, 0), a2, voffA);
;             PG8_WAIT_V(8); PG8_WAIT_L(0); PG8_BAR; PG8_MMA(1, 0, At, B0); PG8_MMA(1, 1, At, B1); PG8_BAR; PG8_SCHED;
;             PG8_LDB(B0, 1, 0); PG8_LDB(B1, 1, 1); PG8_SCHED; PG8_LDA(At, 1, 0); PG8_STAGE(PG8_SA(0, 1), a2 + hstepA, voffA);
;             PG8_WAIT_V(8); PG8_WAIT_L(0); PG8_BAR; PG8_MMA(0, 0, At, B0); PG8_MMA(0, 1, At, B1); PG8_BAR; PG8_SCHED;
	s_setprio 1
	v_mfma_f32_16x16x32_bf16 v[56:59], v[156:159], v[188:191], 0
	v_mfma_f32_16x16x32_bf16 v[56:59], v[160:163], v[192:195], v[56:59]
	v_mfma_f32_16x16x32_bf16 v[60:63], v[152:155], v[192:195], 0
	v_mfma_f32_16x16x32_bf16 v[60:63], v[36:39], v[188:191], v[60:63]
	v_mfma_f32_16x16x32_bf16 v[44:47], v[36:39], v[196:199], 0
	v_mfma_f32_16x16x32_bf16 v[44:47], v[152:155], v[200:203], v[44:47]
	v_mfma_f32_16x16x32_bf16 v[40:43], v[160:163], v[200:203], 0
	v_mfma_f32_16x16x32_bf16 v[40:43], v[156:159], v[196:199], v[40:43]
	v_mfma_f32_16x16x32_bf16 v[20:23], v[156:159], v[204:207], 0
	v_mfma_f32_16x16x32_bf16 v[20:23], v[160:163], v[208:211], v[20:23]
	v_mfma_f32_16x16x32_bf16 v[24:27], v[152:155], v[208:211], 0
	v_mfma_f32_16x16x32_bf16 v[24:27], v[36:39], v[204:207], v[24:27]
	v_mfma_f32_16x16x32_bf16 v[48:51], v[172:175], v[180:183], 0
	v_mfma_f32_16x16x32_bf16 v[32:35], v[164:167], v[188:191], 0
	v_mfma_f32_16x16x32_bf16 v[28:31], v[172:175], v[188:191], 0
	v_mfma_f32_16x16x32_bf16 v[16:19], v[164:167], v[196:199], 0
	v_mfma_f32_16x16x32_bf16 v[12:15], v[172:175], v[196:199], 0
	v_mfma_f32_16x16x32_bf16 v[8:11], v[164:167], v[204:207], 0
	v_mfma_f32_16x16x32_bf16 v[4:7], v[172:175], v[204:207], 0
	v_mfma_f32_16x16x32_bf16 v[36:39], v[164:167], v[180:183], 0
	v_mfma_f32_16x16x32_bf16 v[48:51], v[176:179], v[184:187], v[48:51]
	v_mfma_f32_16x16x32_bf16 v[32:35], v[168:171], v[192:195], v[32:35]
	v_mfma_f32_16x16x32_bf16 v[28:31], v[176:179], v[192:195], v[28:31]
	v_mfma_f32_16x16x32_bf16 v[16:19], v[168:171], v[200:203], v[16:19]
	v_mfma_f32_16x16x32_bf16 v[12:15], v[176:179], v[200:203], v[12:15]
	v_mfma_f32_16x16x32_bf16 v[8:11], v[168:171], v[208:211], v[8:11]
	v_mfma_f32_16x16x32_bf16 v[4:7], v[176:179], v[208:211], v[4:7]
	v_mfma_f32_16x16x32_bf16 v[36:39], v[168:171], v[184:187], v[36:39]
	s_setprio 0
	s_barrier
	s_add_i32 s68, 0, 0x18000
	v_add_u32_e32 v151, s68, v148
	s_add_i32 s69, 0, 0x1c000
	ds_read_b128 v[52:55], v151
	ds_read_b128 v[152:155], v151 offset:1024
	ds_read_b128 v[156:159], v151 offset:2048
	ds_read_b128 v[160:163], v151 offset:3072
	v_add_u32_e32 v151, s69, v148
	ds_read_b128 v[164:167], v151
	ds_read_b128 v[168:171], v151 offset:1024
	ds_read_b128 v[172:175], v151 offset:2048
	ds_read_b128 v[176:179], v151 offset:3072
	s_add_u32 s28, s28, 0x4000
	s_addc_u32 s29, s29, 0
	s_mov_b32 m0, s36
	ds_read_b128 v[180:183], v150 offset:32768
	ds_read_b128 v[184:187], v150 offset:33792
	ds_read_b128 v[188:191], v150 offset:34816
	ds_read_b128 v[192:195], v150 offset:35840
	ds_read_b128 v[196:199], v150 offset:36864
	ds_read_b128 v[200:203], v150 offset:37888
	ds_read_b128 v[204:207], v150 offset:38912
	ds_read_b128 v[208:211], v150 offset:39936
	global_load_lds_dwordx4 v136, s[28:29]
	s_mov_b32 m0, s37
	s_nop 0
	global_load_lds_dwordx4 v140, s[28:29]
	s_waitcnt vmcnt(8)
	s_waitcnt lgkmcnt(0)
	v_mfma_f32_16x16x32_bf16 v[132:135], v[52:55], v[180:183], v[132:135]
	v_mfma_f32_16x16x32_bf16 v[132:135], v[152:155], v[184:187], v[132:135]
	v_mfma_f32_16x16x32_bf16 v[128:131], v[160:163], v[184:187], v[128:131]
	v_mfma_f32_16x16x32_bf16 v[128:131], v[156:159], v[180:183], v[128:131]
	s_barrier
	s_setprio 1
	v_mfma_f32_16x16x32_bf16 v[116:119], v[164:167], v[180:183], v[116:119]
	v_mfma_f32_16x16x32_bf16 v[116:119], v[168:171], v[184:187], v[116:119]
	v_mfma_f32_16x16x32_bf16 v[112:115], v[176:179], v[184:187], v[112:115]
	v_mfma_f32_16x16x32_bf16 v[112:115], v[172:175], v[180:183], v[112:115]
	v_mfma_f32_16x16x32_bf16 v[96:99], v[172:175], v[188:191], v[96:99]
	v_mfma_f32_16x16x32_bf16 v[96:99], v[176:179], v[192:195], v[96:99]
	v_mfma_f32_16x16x32_bf16 v[124:127], v[152:155], v[192:195], v[124:127]
	v_mfma_f32_16x16x32_bf16 v[124:127], v[52:55], v[188:191], v[124:127]
	v_mfma_f32_16x16x32_bf16 v[120:123], v[156:159], v[188:191], v[120:123]
	v_mfma_f32_16x16x32_bf16 v[120:123], v[160:163], v[192:195], v[120:123]
	v_mfma_f32_16x16x32_bf16 v[100:103], v[168:171], v[192:195], v[100:103]
	v_mfma_f32_16x16x32_bf16 v[100:103], v[164:167], v[188:191], v[100:103]
	v_mfma_f32_16x16x32_bf16 v[84:87], v[164:167], v[196:199], v[84:87]
	v_mfma_f32_16x16x32_bf16 v[84:87], v[168:171], v[200:203], v[84:87]
	v_mfma_f32_16x16x32_bf16 v[108:111], v[152:155], v[200:203], v[108:111]
	v_mfma_f32_16x16x32_bf16 v[108:111], v[52:55], v[196:199], v[108:111]
	v_mfma_f32_16x16x32_bf16 v[104:107], v[156:159], v[196:199], v[104:107]
	v_mfma_f32_16x16x32_bf16 v[104:107], v[160:163], v[200:203], v[104:107]
	v_mfma_f32_16x16x32_bf16 v[80:83], v[176:179], v[200:203], v[80:83]
	v_mfma_f32_16x16x32_bf16 v[80:83], v[172:175], v[196:199], v[80:83]
	v_mfma_f32_16x16x32_bf16 v[72:75], v[172:175], v[204:207], v[72:75]
	v_mfma_f32_16x16x32_bf16 v[72:75], v[176:179], v[208:211], v[72:75]
	v_mfma_f32_16x16x32_bf16 v[92:95], v[152:155], v[208:211], v[92:95]
	v_mfma_f32_16x16x32_bf16 v[92:95], v[52:55], v[204:207], v[92:95]
	v_mfma_f32_16x16x32_bf16 v[88:91], v[156:159], v[204:207], v[88:91]
	v_mfma_f32_16x16x32_bf16 v[88:91], v[160:163], v[208:211], v[88:91]
	v_mfma_f32_16x16x32_bf16 v[76:79], v[168:171], v[208:211], v[76:79]
	v_mfma_f32_16x16x32_bf16 v[76:79], v[164:167], v[204:207], v[76:79]
	s_setprio 0
	s_barrier
; #define PG8_STAGE(bufoff, gbase, voff) do { _Pragma("unroll") for (int _i = 0; _i < 2; ++_i) \
;         __builtin_amdgcn_global_load_lds((const unsigned*)((const char*)(gbase) + (voff)[_i]), (PG8_LAS unsigned*)(lds + (bufoff) + ldsw + _i * 8192), 16, 0, 0); } while (0)
; #define PG8_LDA(dst, b, h) do { _Pragma("unroll") for (int m = 0; m < 4; ++m) _Pragma("unroll") for (int k = 0; k < 2; ++k) dst[m][k] = *(const PG8_LAS bf16x8*)(lds + PG8_SA(b, h) + aoff + m * 2048 + k * 1024); } while (0)
; #define PG8_LDB(dst, b, h) do { _Pragma("unroll") for (int n = 0; n < 2; ++n) _Pragma("unroll") for (int k = 0; k < 2; ++k) dst[n][k] = *(const PG8_LAS bf16x8*)(lds + PG8_SB(b, h) + boff + n * 2048 + k * 1024); } while (0)
; #define PG8_MMA(ai, bj, At, Bt) do { __builtin_amdgcn_s_setprio(1); _Pragma("unroll") for (int m = 0; m < 4; ++m) _Pragma("unroll") for (int n = 0; n < 2; ++n) _Pragma("unroll") for (int k = 0; k < 2; ++k) \
;         acc[ai][bj][m][n] = __builtin_amdgcn_mfma_f32_16x16x32_bf16(Bt[n][k], At[m][k], acc[ai][bj][m][n], 0, 0, 0); __builtin_amdgcn_s_setprio(0); } while (0)
; #define PG8_WAIT_V(n) asm volatile("s_waitcnt vmcnt(" #n ")" ::: "memory")
; template <class Epi, class Sched, bool ALIGN_EPI = false, bool SP2 = false, bool ABLK = false, bool BBLK = false>
; __device__ __forceinline__ void gemm_phase(PG8_LAS unsigned char* lds, const Gemm g, const Sched& S, const Epi& E) {
;     ...
;         for (int t = 0; t < nt; t += 2) {
;             const bool last = (t == nt - 2);
;             const char* a1 = cA + (size_t)(t + 1) * kstepA;
;             const char* a2 = last ? nA : cA + (size_t)(t + 2) * kstepA; const char* b2 = last ? nB : cB + (size_t)(t + 2) * kstepB;
;             const char* a3 = a2 + kstepA; const char* b3 = b2 + kstepB;
;             if (last && has_next) S.a_ready(nxt);
;             if constexpr (SP2) {
;             PG8_LDB(B0, 0, 0); PG8_LDB(B1, 0, 1); PG8_SCHED; PG8_LDA(At, 0, 0); PG8_STAGE(PG8_SA(1, 1), a1 + hstepA, voffA);
;             PG8_WAIT_V(8); PG8_WAIT_L(0); PG8_BAR; PG8_MMA(0, 0, At, B0); PG8_MMA(0, 1, At, B1); PG8_BAR; PG8_SCHED;
;     ...
;             PG8_LDA(At, 1, 1); PG8_STAGE(PG8_SB(1, 0), b3, voffB); PG8_STAGE(PG8_SB(1, 1), b3 + hstepB, voffB); PG8_STAGE(PG8_SA(1, 0), a3, voffA);
;             PG8_WAIT_V(8); PG8_WAIT_L(0); PG8_BAR; PG8_MMA(1, 0, At, B0); PG8_MMA(1, 1, At, B1); PG8_BAR; PG8_SCHED;
	s_add_u32 s28, s26, 0x8000
	s_addc_u32 s29, s27, 0
	s_add_i32 s68, s68, s34
	s_mov_b32 m0, s68
	ds_read_b128 v[180:183], v150 offset:49152
	ds_read_b128 v[184:187], v150 offset:50176
	ds_read_b128 v[188:191], v150 offset:51200
	ds_read_b128 v[192:195], v150 offset:52224
	ds_read_b128 v[196:199], v150 offset:53248
	ds_read_b128 v[200:203], v150 offset:54272
	ds_read_b128 v[204:207], v150 offset:55296
	ds_read_b128 v[208:211], v150 offset:56320
	global_load_lds_dwordx4 v138, s[28:29]
	s_add_i32 m0, s68, 0x2000
	s_add_u32 s26, s26, 0xc000
	s_addc_u32 s27, s27, 0
	global_load_lds_dwordx4 v142, s[28:29]
	s_add_i32 s28, s69, s34
	s_mov_b32 m0, s28
	s_nop 0
	global_load_lds_dwordx4 v138, s[26:27]
	s_add_i32 m0, s28, 0x2000
	s_nop 0
	global_load_lds_dwordx4 v142, s[26:27]
	s_mov_b32 m0, s64
	s_nop 0
	global_load_lds_dwordx4 v136, s[24:25]
	s_mov_b32 m0, s65
	s_nop 0
	global_load_lds_dwordx4 v140, s[24:25]
	s_waitcnt vmcnt(8)
	s_waitcnt lgkmcnt(0)
	v_mfma_f32_16x16x32_bf16 v[68:71], v[52:55], v[180:183], v[68:71]
	v_mfma_f32_16x16x32_bf16 v[68:71], v[152:155], v[184:187], v[68:71]
	v_mfma_f32_16x16x32_bf16 v[64:67], v[160:163], v[184:187], v[64:67]
	v_mfma_f32_16x16x32_bf16 v[64:67], v[156:159], v[180:183], v[64:67]
	s_barrier
	s_setprio 1
	v_mfma_f32_16x16x32_bf16 v[56:59], v[156:159], v[188:191], v[56:59]
	v_mfma_f32_16x16x32_bf16 v[56:59], v[160:163], v[192:195], v[56:59]
	v_mfma_f32_16x16x32_bf16 v[60:63], v[152:155], v[192:195], v[60:63]
	v_mfma_f32_16x16x32_bf16 v[60:63], v[52:55], v[188:191], v[60:63]
	v_mfma_f32_16x16x32_bf16 v[44:47], v[52:55], v[196:199], v[44:47]
	v_mfma_f32_16x16x32_bf16 v[44:47], v[152:155], v[200:203], v[44:47]
	v_mfma_f32_16x16x32_bf16 v[40:43], v[160:163], v[200:203], v[40:43]
	v_mfma_f32_16x16x32_bf16 v[40:43], v[156:159], v[196:199], v[40:43]
	v_mfma_f32_16x16x32_bf16 v[20:23], v[156:159], v[204:207], v[20:23]
	v_mfma_f32_16x16x32_bf16 v[20:23], v[160:163], v[208:211], v[20:23]
	v_mfma_f32_16x16x32_bf16 v[24:27], v[152:155], v[208:211], v[24:27]
	v_mfma_f32_16x16x32_bf16 v[24:27], v[52:55], v[204:207], v[24:27]
	v_mfma_f32_16x16x32_bf16 v[36:39], v[164:167], v[180:183], v[36:39]
	v_mfma_f32_16x16x32_bf16 v[52:55], v[168:171], v[184:187], v[36:39]
	v_mfma_f32_16x16x32_bf16 v[36:39], v[172:175], v[180:183], v[48:51]
	v_mfma_f32_16x16x32_bf16 v[32:35], v[164:167], v[188:191], v[32:35]
	v_mfma_f32_16x16x32_bf16 v[28:31], v[172:175], v[188:191], v[28:31]
	v_mfma_f32_16x16x32_bf16 v[16:19], v[164:167], v[196:199], v[16:19]
	v_mfma_f32_16x16x32_bf16 v[12:15], v[172:175], v[196:199], v[12:15]
	v_mfma_f32_16x16x32_bf16 v[8:11], v[164:167], v[204:207], v[8:11]
	v_mfma_f32_16x16x32_bf16 v[4:7], v[172:175], v[204:207], v[4:7]
	v_mfma_f32_16x16x32_bf16 v[48:51], v[176:179], v[184:187], v[36:39]
	v_mfma_f32_16x16x32_bf16 v[32:35], v[168:171], v[192:195], v[32:35]
	v_mfma_f32_16x16x32_bf16 v[28:31], v[176:179], v[192:195], v[28:31]
	v_mfma_f32_16x16x32_bf16 v[16:19], v[168:171], v[200:203], v[16:19]
	v_mfma_f32_16x16x32_bf16 v[12:15], v[176:179], v[200:203], v[12:15]
	v_mfma_f32_16x16x32_bf16 v[8:11], v[168:171], v[208:211], v[8:11]
	v_mfma_f32_16x16x32_bf16 v[4:7], v[176:179], v[208:211], v[4:7]
	s_setprio 0
	s_barrier
	s_add_i32 s13, s13, 2
	s_add_u32 s22, s22, 0x10000
	s_addc_u32 s23, s23, 0
	s_add_u32 s82, s82, 0x10000
	s_addc_u32 vcc_lo, vcc_lo, 0
	s_cmp_gt_u32 s13, 29
.LBB0_2111:
	s_add_u32 s24, s22, 0x4000
	s_addc_u32 s25, s23, 0
	s_cmp_eq_u32 s13, 28
	s_cselect_b32 s28, s17, s24
	s_cselect_b32 s29, s12, s25
	s_cselect_b32 s26, s77, s82
	s_cselect_b32 s27, s11, vcc_lo
	s_add_u32 s24, s28, 0x8000
	s_addc_u32 s25, s29, 0
	s_add_i32 s68, 0, 0x10000
	v_add_u32_e32 v151, s68, v148
	s_add_i32 s88, 0, 0x14000
	ds_read_b128 v[36:39], v151
	ds_read_b128 v[152:155], v151 offset:1024
	ds_read_b128 v[156:159], v151 offset:2048
	ds_read_b128 v[160:163], v151 offset:3072
	v_add_u32_e32 v151, s88, v148
	ds_read_b128 v[164:167], v151
	ds_read_b128 v[168:171], v151 offset:1024
	ds_read_b128 v[172:175], v151 offset:2048
	ds_read_b128 v[176:179], v151 offset:3072
	s_add_i32 m0, s9, 0xc000
	ds_read_b128 v[180:183], v150
	ds_read_b128 v[184:187], v150 offset:1024
	ds_read_b128 v[188:191], v150 offset:2048
	ds_read_b128 v[192:195], v150 offset:3072
	ds_read_b128 v[196:199], v150 offset:4096
	ds_read_b128 v[200:203], v150 offset:5120
	ds_read_b128 v[204:207], v150 offset:6144
	ds_read_b128 v[208:211], v150 offset:7168
	global_load_lds_dwordx4 v144, s[22:23]
	s_add_i32 m0, s9, 0xe000
	s_nop 0
	global_load_lds_dwordx4 v146, s[22:23]
	s_waitcnt vmcnt(8)
	s_waitcnt lgkmcnt(0)
	v_mfma_f32_16x16x32_bf16 v[132:135], v[36:39], v[180:183], v[132:135]
	v_mfma_f32_16x16x32_bf16 v[132:135], v[152:155], v[184:187], v[132:135]
	v_mfma_f32_16x16x32_bf16 v[128:131], v[160:163], v[184:187], v[128:131]
	v_mfma_f32_16x16x32_bf16 v[128:131], v[156:159], v[180:183], v[128:131]
	s_barrier
; #define PG8_STAGE(bufoff, gbase, voff) do { _Pragma("unroll") for (int _i = 0; _i < 2; ++_i) \
;         __builtin_amdgcn_global_load_lds((const unsigned*)((const char*)(gbase) + (voff)[_i]), (PG8_LAS unsigned*)(lds + (bufoff) + ldsw + _i * 8192), 16, 0, 0); } while (0)
; #define PG8_LDA(dst, b, h) do { _Pragma("unroll") for (int m = 0; m < 4; ++m) _Pragma("unroll") for (int k = 0; k < 2; ++k) dst[m][k] = *(const PG8_LAS bf16x8*)(lds + PG8_SA(b, h) + aoff + m * 2048 + k * 1024); } while (0)
; #define PG8_LDB(dst, b, h) do { _Pragma("unroll") for (int n = 0; n < 2; ++n) _Pragma("unroll") for (int k = 0; k < 2; ++k) dst[n][k] = *(const PG8_LAS bf16x8*)(lds + PG8_SB(b, h) + boff + n * 2048 + k * 1024); } while (0)
; #define PG8_MMA(ai, bj, At, Bt) do { __builtin_amdgcn_s_setprio(1); _Pragma("unroll") for (int m = 0; m < 4; ++m) _Pragma("unroll") for (int n = 0; n < 2; ++n) _Pragma("unroll") for (int k = 0; k < 2; ++k) \
;         acc[ai][bj][m][n] = __builtin_amdgcn_mfma_f32_16x16x32_bf16(Bt[n][k], At[m][k], acc[ai][bj][m][n], 0, 0, 0); __builtin_amdgcn_s_setprio(0); } while (0)
; #define PG8_WAIT_V(n) asm volatile("s_waitcnt vmcnt(" #n ")" ::: "memory")
; #define PG8_WAIT_L(n) asm volatile("s_waitcnt lgkmcnt(" #n ")" ::: "memory")
; #define PG8_BAR __builtin_amdgcn_s_barrier()
; #define PG8_SCHED __builtin_amdgcn_sched_barrier(0)
; template <class Epi, class Sched, bool ALIGN_EPI = false, bool SP2 = false, bool ABLK = false, bool BBLK = false>
; __device__ __forceinline__ void gemm_phase(PG8_LAS unsigned char* lds, const Gemm g, const Sched& S, const Epi& E) {
;     ...
;             PG8_WAIT_V(8); PG8_WAIT_L(0); PG8_BAR; PG8_MMA(0, 0, At, B0); PG8_MMA(0, 1, At, B1); PG8_BAR; PG8_SCHED;
;             PG8_LDA(At, 0, 1); PG8_STAGE(PG8_SB(0, 0), b2, voffB); PG8_STAGE(PG8_SB(0, 1), b2 + hstepB, voffB); PG8_STAGE(PG8_SA(0, 0), a2, voffA);
;             PG8_WAIT_V(8); PG8_WAIT_L(0); PG8_BAR; PG8_MMA(1, 0, At, B0); PG8_MMA(1, 1, At, B1); PG8_BAR; PG8_SCHED;
;             PG8_LDB(B0, 1, 0); PG8_LDB(B1, 1, 1); PG8_SCHED; PG8_LDA(At, 1, 0); PG8_STAGE(PG8_SA(0, 1), a2 + hstepA, voffA);
;             PG8_WAIT_V(8); PG8_WAIT_L(0); PG8_BAR; PG8_MMA(0, 0, At, B0); PG8_MMA(0, 1, At, B1); PG8_BAR; PG8_SCHED;
	s_setprio 1
	v_mfma_f32_16x16x32_bf16 v[116:119], v[164:167], v[180:183], v[116:119]
	v_mfma_f32_16x16x32_bf16 v[116:119], v[168:171], v[184:187], v[116:119]
	v_mfma_f32_16x16x32_bf16 v[112:115], v[176:179], v[184:187], v[112:115]
	v_mfma_f32_16x16x32_bf16 v[112:115], v[172:175], v[180:183], v[112:115]
	v_mfma_f32_16x16x32_bf16 v[96:99], v[172:175], v[188:191], v[96:99]
	v_mfma_f32_16x16x32_bf16 v[96:99], v[176:179], v[192:195], v[96:99]
	v_mfma_f32_16x16x32_bf16 v[124:127], v[152:155], v[192:195], v[124:127]
	v_mfma_f32_16x16x32_bf16 v[124:127], v[36:39], v[188:191], v[124:127]
	v_mfma_f32_16x16x32_bf16 v[120:123], v[156:159], v[188:191], v[120:123]
	v_mfma_f32_16x16x32_bf16 v[120:123], v[160:163], v[192:195], v[120:123]
	v_mfma_f32_16x16x32_bf16 v[100:103], v[168:171], v[192:195], v[100:103]
	v_mfma_f32_16x16x32_bf16 v[100:103], v[164:167], v[188:191], v[100:103]
	v_mfma_f32_16x16x32_bf16 v[84:87], v[164:167], v[196:199], v[84:87]
	v_mfma_f32_16x16x32_bf16 v[84:87], v[168:171], v[200:203], v[84:87]
	v_mfma_f32_16x16x32_bf16 v[108:111], v[152:155], v[200:203], v[108:111]
	v_mfma_f32_16x16x32_bf16 v[108:111], v[36:39], v[196:199], v[108:111]
	v_mfma_f32_16x16x32_bf16 v[104:107], v[156:159], v[196:199], v[104:107]
	v_mfma_f32_16x16x32_bf16 v[104:107], v[160:163], v[200:203], v[104:107]
	v_mfma_f32_16x16x32_bf16 v[80:83], v[176:179], v[200:203], v[80:83]
	v_mfma_f32_16x16x32_bf16 v[80:83], v[172:175], v[196:199], v[80:83]
	v_mfma_f32_16x16x32_bf16 v[72:75], v[172:175], v[204:207], v[72:75]
	v_mfma_f32_16x16x32_bf16 v[72:75], v[176:179], v[208:211], v[72:75]
	v_mfma_f32_16x16x32_bf16 v[92:95], v[152:155], v[208:211], v[92:95]
	v_mfma_f32_16x16x32_bf16 v[92:95], v[36:39], v[204:207], v[92:95]
	v_mfma_f32_16x16x32_bf16 v[88:91], v[156:159], v[204:207], v[88:91]
	v_mfma_f32_16x16x32_bf16 v[88:91], v[160:163], v[208:211], v[88:91]
	v_mfma_f32_16x16x32_bf16 v[76:79], v[168:171], v[208:211], v[76:79]
	v_mfma_f32_16x16x32_bf16 v[76:79], v[164:167], v[204:207], v[76:79]
	s_setprio 0
	s_barrier
	s_add_i32 s68, s68, s34
	s_mov_b32 m0, s68
	ds_read_b128 v[180:183], v150 offset:16384
	ds_read_b128 v[184:187], v150 offset:17408
	ds_read_b128 v[188:191], v150 offset:18432
	ds_read_b128 v[192:195], v150 offset:19456
	ds_read_b128 v[196:199], v150 offset:20480
	ds_read_b128 v[200:203], v150 offset:21504
	ds_read_b128 v[204:207], v150 offset:22528
	ds_read_b128 v[208:211], v150 offset:23552
	global_load_lds_dwordx4 v138, s[26:27]
	s_add_i32 m0, s68, 0x2000
	s_add_u32 s68, s26, 0x4000
	s_addc_u32 s69, s27, 0
	s_add_i32 s88, s88, s34
	global_load_lds_dwordx4 v142, s[26:27]
	s_mov_b32 m0, s88
	s_nop 0
	global_load_lds_dwordx4 v138, s[68:69]
	s_add_i32 m0, s88, 0x2000
	s_nop 0
	global_load_lds_dwordx4 v142, s[68:69]
	s_mov_b32 m0, s9
	s_nop 0
	global_load_lds_dwordx4 v136, s[28:29]
	s_mov_b32 m0, s35
	s_nop 0
	global_load_lds_dwordx4 v140, s[28:29]
	s_waitcnt vmcnt(8)
	s_waitcnt lgkmcnt(0)
	v_mfma_f32_16x16x32_bf16 v[68:71], v[36:39], v[180:183], v[68:71]
	v_mfma_f32_16x16x32_bf16 v[68:71], v[152:155], v[184:187], v[68:71]
	v_mfma_f32_16x16x32_bf16 v[64:67], v[160:163], v[184:187], v[64:67]
	v_mfma_f32_16x16x32_bf16 v[64:67], v[156:159], v[180:183], v[64:67]
	s_barrier
	s_setprio 1
	v_mfma_f32_16x16x32_bf16 v[56:59], v[156:159], v[188:191], v[56:59]
	v_mfma_f32_16x16x32_bf16 v[56:59], v[160:163], v[192:195], v[56:59]
	v_mfma_f32_16x16x32_bf16 v[60:63], v[152:155], v[192:195], v[60:63]
	v_mfma_f32_16x16x32_bf16 v[60:63], v[36:39], v[188:191], v[60:63]
	v_mfma_f32_16x16x32_bf16 v[44:47], v[36:39], v[196:199], v[44:47]
	v_mfma_f32_16x16x32_bf16 v[44:47], v[152:155], v[200:203], v[44:47]
	v_mfma_f32_16x16x32_bf16 v[40:43], v[160:163], v[200:203], v[40:43]
	v_mfma_f32_16x16x32_bf16 v[40:43], v[156:159], v[196:199], v[40:43]
	v_mfma_f32_16x16x32_bf16 v[20:23], v[156:159], v[204:207], v[20:23]
	v_mfma_f32_16x16x32_bf16 v[20:23], v[160:163], v[208:211], v[20:23]
	v_mfma_f32_16x16x32_bf16 v[24:27], v[152:155], v[208:211], v[24:27]
	v_mfma_f32_16x16x32_bf16 v[24:27], v[36:39], v[204:207], v[24:27]
	v_mfma_f32_16x16x32_bf16 v[48:51], v[172:175], v[180:183], v[48:51]
	v_mfma_f32_16x16x32_bf16 v[32:35], v[164:167], v[188:191], v[32:35]
	v_mfma_f32_16x16x32_bf16 v[28:31], v[172:175], v[188:191], v[28:31]
	v_mfma_f32_16x16x32_bf16 v[16:19], v[164:167], v[196:199], v[16:19]
	v_mfma_f32_16x16x32_bf16 v[12:15], v[172:175], v[196:199], v[12:15]
	v_mfma_f32_16x16x32_bf16 v[8:11], v[164:167], v[204:207], v[8:11]
	v_mfma_f32_16x16x32_bf16 v[4:7], v[172:175], v[204:207], v[4:7]
	v_mfma_f32_16x16x32_bf16 v[36:39], v[164:167], v[180:183], v[52:55]
	v_mfma_f32_16x16x32_bf16 v[48:51], v[176:179], v[184:187], v[48:51]
	v_mfma_f32_16x16x32_bf16 v[32:35], v[168:171], v[192:195], v[32:35]
	v_mfma_f32_16x16x32_bf16 v[28:31], v[176:179], v[192:195], v[28:31]
	v_mfma_f32_16x16x32_bf16 v[16:19], v[168:171], v[200:203], v[16:19]
	v_mfma_f32_16x16x32_bf16 v[12:15], v[176:179], v[200:203], v[12:15]
	v_mfma_f32_16x16x32_bf16 v[8:11], v[168:171], v[208:211], v[8:11]
	v_mfma_f32_16x16x32_bf16 v[4:7], v[176:179], v[208:211], v[4:7]
	v_mfma_f32_16x16x32_bf16 v[36:39], v[168:171], v[184:187], v[36:39]
	s_setprio 0
	s_barrier
; #define PG8_STAGE(bufoff, gbase, voff) do { _Pragma("unroll") for (int _i = 0; _i < 2; ++_i) \
;         __builtin_amdgcn_global_load_lds((const unsigned*)((const char*)(gbase) + (voff)[_i]), (PG8_LAS unsigned*)(lds + (bufoff) + ldsw + _i * 8192), 16, 0, 0); } while (0)
; #define PG8_LDA(dst, b, h) do { _Pragma("unroll") for (int m = 0; m < 4; ++m) _Pragma("unroll") for (int k = 0; k < 2; ++k) dst[m][k] = *(const PG8_LAS bf16x8*)(lds + PG8_SA(b, h) + aoff + m * 2048 + k * 1024); } while (0)
; #define PG8_LDB(dst, b, h) do { _Pragma("unroll") for (int n = 0; n < 2; ++n) _Pragma("unroll") for (int k = 0; k < 2; ++k) dst[n][k] = *(const PG8_LAS bf16x8*)(lds + PG8_SB(b, h) + boff + n * 2048 + k * 1024); } while (0)
; #define PG8_MMA(ai, bj, At, Bt) do { __builtin_amdgcn_s_setprio(1); _Pragma("unroll") for (int m = 0; m < 4; ++m) _Pragma("unroll") for (int n = 0; n < 2; ++n) _Pragma("unroll") for (int k = 0; k < 2; ++k) \
;         acc[ai][bj][m][n] = __builtin_amdgcn_mfma_f32_16x16x32_bf16(Bt[n][k], At[m][k], acc[ai][bj][m][n], 0, 0, 0); __builtin_amdgcn_s_setprio(0); } while (0)
; #define PG8_WAIT_V(n) asm volatile("s_waitcnt vmcnt(" #n ")" ::: "memory")
; #define PG8_WAIT_L(n) asm volatile("s_waitcnt lgkmcnt(" #n ")" ::: "memory")
; #define PG8_BAR __builtin_amdgcn_s_barrier()
; #define PG8_SCHED __builtin_amdgcn_sched_barrier(0)
; template <class Epi, class Sched, bool ALIGN_EPI = false, bool SP2 = false, bool ABLK = false, bool BBLK = false>
; __device__ __forceinline__ void gemm_phase(PG8_LAS unsigned char* lds, const Gemm g, const Sched& S, const Epi& E) {
;     ...
;             PG8_LDB(B0, 1, 0); PG8_LDB(B1, 1, 1); PG8_SCHED; PG8_LDA(At, 1, 0); PG8_STAGE(PG8_SA(0, 1), a2 + hstepA, voffA);
;             PG8_WAIT_V(8); PG8_WAIT_L(0); PG8_BAR; PG8_MMA(0, 0, At, B0); PG8_MMA(0, 1, At, B1); PG8_BAR; PG8_SCHED;
;             PG8_LDA(At, 1, 1); PG8_STAGE(PG8_SB(1, 0), b3, voffB); PG8_STAGE(PG8_SB(1, 1), b3 + hstepB, voffB); PG8_STAGE(PG8_SA(1, 0), a3, voffA);
;             PG8_WAIT_V(8); PG8_WAIT_L(0); PG8_BAR; PG8_MMA(1, 0, At, B0); PG8_MMA(1, 1, At, B1); PG8_BAR; PG8_SCHED;
	s_add_i32 s68, 0, 0x18000
	v_add_u32_e32 v151, s68, v148
	s_add_i32 s69, 0, 0x1c000
	ds_read_b128 v[52:55], v151
	ds_read_b128 v[152:155], v151 offset:1024
	ds_read_b128 v[156:159], v151 offset:2048
	ds_read_b128 v[160:163], v151 offset:3072
	v_add_u32_e32 v151, s69, v148
	ds_read_b128 v[164:167], v151
	ds_read_b128 v[168:171], v151 offset:1024
	ds_read_b128 v[172:175], v151 offset:2048
	ds_read_b128 v[176:179], v151 offset:3072
	s_add_u32 s28, s28, 0x4000
	s_addc_u32 s29, s29, 0
	s_mov_b32 m0, s36
	ds_read_b128 v[180:183], v150 offset:32768
	ds_read_b128 v[184:187], v150 offset:33792
	ds_read_b128 v[188:191], v150 offset:34816
	ds_read_b128 v[192:195], v150 offset:35840
	ds_read_b128 v[196:199], v150 offset:36864
	ds_read_b128 v[200:203], v150 offset:37888
	ds_read_b128 v[204:207], v150 offset:38912
	ds_read_b128 v[208:211], v150 offset:39936
	global_load_lds_dwordx4 v136, s[28:29]
	s_mov_b32 m0, s37
	s_nop 0
	global_load_lds_dwordx4 v140, s[28:29]
	s_waitcnt vmcnt(8)
	s_waitcnt lgkmcnt(0)
	v_mfma_f32_16x16x32_bf16 v[132:135], v[52:55], v[180:183], v[132:135]
	v_mfma_f32_16x16x32_bf16 v[132:135], v[152:155], v[184:187], v[132:135]
	v_mfma_f32_16x16x32_bf16 v[128:131], v[160:163], v[184:187], v[128:131]
	v_mfma_f32_16x16x32_bf16 v[128:131], v[156:159], v[180:183], v[128:131]
	s_barrier
	s_setprio 1
	v_mfma_f32_16x16x32_bf16 v[116:119], v[164:167], v[180:183], v[116:119]
	v_mfma_f32_16x16x32_bf16 v[116:119], v[168:171], v[184:187], v[116:119]
	v_mfma_f32_16x16x32_bf16 v[112:115], v[176:179], v[184:187], v[112:115]
	v_mfma_f32_16x16x32_bf16 v[112:115], v[172:175], v[180:183], v[112:115]
	v_mfma_f32_16x16x32_bf16 v[96:99], v[172:175], v[188:191], v[96:99]
	v_mfma_f32_16x16x32_bf16 v[96:99], v[176:179], v[192:195], v[96:99]
	v_mfma_f32_16x16x32_bf16 v[124:127], v[152:155], v[192:195], v[124:127]
	v_mfma_f32_16x16x32_bf16 v[124:127], v[52:55], v[188:191], v[124:127]
	v_mfma_f32_16x16x32_bf16 v[120:123], v[156:159], v[188:191], v[120:123]
	v_mfma_f32_16x16x32_bf16 v[120:123], v[160:163], v[192:195], v[120:123]
	v_mfma_f32_16x16x32_bf16 v[100:103], v[168:171], v[192:195], v[100:103]
	v_mfma_f32_16x16x32_bf16 v[100:103], v[164:167], v[188:191], v[100:103]
	v_mfma_f32_16x16x32_bf16 v[84:87], v[164:167], v[196:199], v[84:87]
	v_mfma_f32_16x16x32_bf16 v[84:87], v[168:171], v[200:203], v[84:87]
	v_mfma_f32_16x16x32_bf16 v[108:111], v[152:155], v[200:203], v[108:111]
	v_mfma_f32_16x16x32_bf16 v[108:111], v[52:55], v[196:199], v[108:111]
	v_mfma_f32_16x16x32_bf16 v[104:107], v[156:159], v[196:199], v[104:107]
	v_mfma_f32_16x16x32_bf16 v[104:107], v[160:163], v[200:203], v[104:107]
	v_mfma_f32_16x16x32_bf16 v[80:83], v[176:179], v[200:203], v[80:83]
	v_mfma_f32_16x16x32_bf16 v[80:83], v[172:175], v[196:199], v[80:83]
	v_mfma_f32_16x16x32_bf16 v[72:75], v[172:175], v[204:207], v[72:75]
	v_mfma_f32_16x16x32_bf16 v[72:75], v[176:179], v[208:211], v[72:75]
	v_mfma_f32_16x16x32_bf16 v[92:95], v[152:155], v[208:211], v[92:95]
	v_mfma_f32_16x16x32_bf16 v[92:95], v[52:55], v[204:207], v[92:95]
	v_mfma_f32_16x16x32_bf16 v[88:91], v[156:159], v[204:207], v[88:91]
	v_mfma_f32_16x16x32_bf16 v[88:91], v[160:163], v[208:211], v[88:91]
	v_mfma_f32_16x16x32_bf16 v[76:79], v[168:171], v[208:211], v[76:79]
	v_mfma_f32_16x16x32_bf16 v[76:79], v[164:167], v[204:207], v[76:79]
	s_setprio 0
	s_barrier
	s_add_u32 s28, s26, 0x8000
	s_addc_u32 s29, s27, 0
	s_add_i32 s68, s68, s34
	s_mov_b32 m0, s68
	ds_read_b128 v[180:183], v150 offset:49152
	ds_read_b128 v[184:187], v150 offset:50176
	ds_read_b128 v[188:191], v150 offset:51200
	ds_read_b128 v[192:195], v150 offset:52224
	ds_read_b128 v[196:199], v150 offset:53248
	ds_read_b128 v[200:203], v150 offset:54272
	ds_read_b128 v[204:207], v150 offset:55296
	ds_read_b128 v[208:211], v150 offset:56320
	global_load_lds_dwordx4 v138, s[28:29]
	s_add_i32 m0, s68, 0x2000
	s_add_u32 s26, s26, 0xc000
	s_addc_u32 s27, s27, 0
	global_load_lds_dwordx4 v142, s[28:29]
	s_add_i32 s28, s69, s34
	s_mov_b32 m0, s28
	s_nop 0
	global_load_lds_dwordx4 v138, s[26:27]
	s_add_i32 m0, s28, 0x2000
	s_nop 0
	global_load_lds_dwordx4 v142, s[26:27]
	s_mov_b32 m0, s64
	s_nop 0
	global_load_lds_dwordx4 v136, s[24:25]
	s_mov_b32 m0, s65
	s_nop 0
	global_load_lds_dwordx4 v140, s[24:25]
	s_waitcnt vmcnt(8)
	s_waitcnt lgkmcnt(0)
	v_mfma_f32_16x16x32_bf16 v[68:71], v[52:55], v[180:183], v[68:71]
	v_mfma_f32_16x16x32_bf16 v[68:71], v[152:155], v[184:187], v[68:71]
	v_mfma_f32_16x16x32_bf16 v[64:67], v[160:163], v[184:187], v[64:67]
	v_mfma_f32_16x16x32_bf16 v[64:67], v[156:159], v[180:183], v[64:67]
	s_barrier
	s_setprio 1
	v_mfma_f32_16x16x32_bf16 v[56:59], v[156:159], v[188:191], v[56:59]
	v_mfma_f32_16x16x32_bf16 v[56:59], v[160:163], v[192:195], v[56:59]
	v_mfma_f32_16x16x32_bf16 v[60:63], v[152:155], v[192:195], v[60:63]
	v_mfma_f32_16x16x32_bf16 v[60:63], v[52:55], v[188:191], v[60:63]
	v_mfma_f32_16x16x32_bf16 v[44:47], v[52:55], v[196:199], v[44:47]
	v_mfma_f32_16x16x32_bf16 v[44:47], v[152:155], v[200:203], v[44:47]
	v_mfma_f32_16x16x32_bf16 v[40:43], v[160:163], v[200:203], v[40:43]
	v_mfma_f32_16x16x32_bf16 v[40:43], v[156:159], v[196:199], v[40:43]
	v_mfma_f32_16x16x32_bf16 v[20:23], v[156:159], v[204:207], v[20:23]
	v_mfma_f32_16x16x32_bf16 v[20:23], v[160:163], v[208:211], v[20:23]
	v_mfma_f32_16x16x32_bf16 v[24:27], v[152:155], v[208:211], v[24:27]
	v_mfma_f32_16x16x32_bf16 v[24:27], v[52:55], v[204:207], v[24:27]
	v_mfma_f32_16x16x32_bf16 v[36:39], v[164:167], v[180:183], v[36:39]
	v_mfma_f32_16x16x32_bf16 v[52:55], v[168:171], v[184:187], v[36:39]
	v_mfma_f32_16x16x32_bf16 v[36:39], v[172:175], v[180:183], v[48:51]
	v_mfma_f32_16x16x32_bf16 v[32:35], v[164:167], v[188:191], v[32:35]
	v_mfma_f32_16x16x32_bf16 v[28:31], v[172:175], v[188:191], v[28:31]
	v_mfma_f32_16x16x32_bf16 v[16:19], v[164:167], v[196:199], v[16:19]
	v_mfma_f32_16x16x32_bf16 v[12:15], v[172:175], v[196:199], v[12:15]
	v_mfma_f32_16x16x32_bf16 v[8:11], v[164:167], v[204:207], v[8:11]
	v_mfma_f32_16x16x32_bf16 v[4:7], v[172:175], v[204:207], v[4:7]
	v_mfma_f32_16x16x32_bf16 v[48:51], v[176:179], v[184:187], v[36:39]
	v_mfma_f32_16x16x32_bf16 v[32:35], v[168:171], v[192:195], v[32:35]
	v_mfma_f32_16x16x32_bf16 v[28:31], v[176:179], v[192:195], v[28:31]
	v_mfma_f32_16x16x32_bf16 v[16:19], v[168:171], v[200:203], v[16:19]
	v_mfma_f32_16x16x32_bf16 v[12:15], v[176:179], v[200:203], v[12:15]
	v_mfma_f32_16x16x32_bf16 v[8:11], v[168:171], v[208:211], v[8:11]
	v_mfma_f32_16x16x32_bf16 v[4:7], v[176:179], v[208:211], v[4:7]
	s_setprio 0
	s_barrier
	s_add_i32 s13, s13, 2
	s_add_u32 s22, s22, 0x10000
	s_addc_u32 s23, s23, 0
	s_add_u32 s82, s82, 0x10000
	s_addc_u32 vcc_lo, vcc_lo, 0
	s_cmp_gt_u32 s13, 29
	s_cbranch_scc0 .LBB0_2111
	s_and_b64 vcc, exec, s[6:7]
	s_movk_i32 s77, 0x1000
	s_cbranch_vccz .LBB0_2114
	s_barrier
